# de-serialized epilogue/norm ladders (row-invariant gain vectors hoisted, stores never drained inside loops, counted vmcnt), write-through stores for FFN-up and in-proj S5 outputs
# speedup vs baseline: 1.0150x; 1.0120x over previous
.LBB0_138:
	s_add_u32 s34, s22, 0x5e00000
	s_addc_u32 s35, s23, 0
	s_cmp_lt_i32 s26, 64
	s_cselect_b64 s[0:1], -1, 0
	s_and_b64 s[6:7], s[0:1], exec
	s_cselect_b32 s78, 0, 32
	v_lshrrev_b32_e32 v125, 6, v144
	v_and_b32_e32 v85, 63, v144
	s_cmp_ge_i32 s3, s78
	s_mov_b64 s[6:7], -1
	s_cbranch_scc0 .LBB0_227
	s_sub_i32 s58, s26, s78
	s_andn2_b64 vcc, exec, s[0:1]
	s_sub_i32 s60, s3, s78
	s_cbranch_vccnz .LBB0_144
	v_lshlrev_b32_e32 v32, 2, v144
	v_mov_b32_e32 v33, 0
	v_lshl_add_u64 v[0:1], s[54:55], 0, v[32:33]
	v_add_co_u32_e32 v4, vcc, 0x60000, v0
	s_mov_b32 s0, 0x60000
	s_nop 0
	v_addc_co_u32_e32 v5, vcc, 0, v1, vcc
	v_add_co_u32_e32 v6, vcc, 0xcc000, v0
	s_mov_b32 s1, 0xcc000
	s_nop 0
	v_addc_co_u32_e32 v7, vcc, 0, v1, vcc
	v_add_co_u32_e32 v8, vcc, 0x138000, v0
	s_mov_b32 s2, 0x138000
	s_nop 0
	v_addc_co_u32_e32 v9, vcc, 0, v1, vcc
	v_add_co_u32_e32 v10, vcc, 0x1a4000, v0
	s_mov_b32 s6, 0x1a4000
	s_nop 0
	v_addc_co_u32_e32 v11, vcc, 0, v1, vcc
	v_add_co_u32_e32 v12, vcc, 0x210000, v0
	s_mov_b32 s7, 0x210000
	s_nop 0
	v_addc_co_u32_e32 v13, vcc, 0, v1, vcc
	v_add_co_u32_e32 v14, vcc, 0x27c000, v0
	s_mov_b32 s8, 0x27c000
	s_nop 0
	v_addc_co_u32_e32 v15, vcc, 0, v1, vcc
	v_add_co_u32_e32 v16, vcc, 0x2e8000, v0
	s_mov_b32 s9, 0x2e8000
	s_nop 0
	v_addc_co_u32_e32 v17, vcc, 0, v1, vcc
	v_add_co_u32_e32 v18, vcc, 0x354000, v0
	s_mov_b32 s10, 0x354000
	s_nop 0
	v_addc_co_u32_e32 v19, vcc, 0, v1, vcc
	global_load_dword v23, v[4:5], off
	global_load_dword v24, v[6:7], off
	global_load_dword v25, v[8:9], off
	global_load_dword v26, v[10:11], off
	global_load_dword v27, v[10:11], off offset:2048
	global_load_dword v28, v[8:9], off offset:2048
	global_load_dword v29, v[6:7], off offset:2048
	global_load_dword v30, v[4:5], off offset:2048
	global_load_dword v31, v[12:13], off
	global_load_dword v34, v[14:15], off
	global_load_dword v35, v[16:17], off
	global_load_dword v36, v[18:19], off
	global_load_dword v37, v[18:19], off offset:2048
	global_load_dword v38, v[16:17], off offset:2048
	global_load_dword v39, v[14:15], off offset:2048
	global_load_dword v40, v[12:13], off offset:2048
	v_or_b32_e32 v4, 0x1000, v32
	v_mov_b32_e32 v5, v33
	global_load_dword v41, v32, s[62:63]
	global_load_dword v42, v32, s[62:63] offset:2048
	global_load_dword v43, v4, s[62:63]
	v_lshl_add_u64 v[4:5], s[54:55], 0, v[4:5]
	v_add_co_u32_e32 v6, vcc, s0, v4
	v_lshl_add_u64 v[2:3], s[62:63], 0, v[32:33]
	s_nop 0
	v_addc_co_u32_e32 v7, vcc, 0, v5, vcc
	v_add_co_u32_e32 v8, vcc, s1, v4
	s_movk_i32 s11, 0x1000
	s_nop 0
	v_addc_co_u32_e32 v9, vcc, 0, v5, vcc
	v_add_co_u32_e32 v10, vcc, s2, v4
	v_add_u32_e32 v22, 0, v32
	s_nop 0
	v_addc_co_u32_e32 v11, vcc, 0, v5, vcc
	v_add_co_u32_e32 v12, vcc, s6, v4
	s_nop 1
	v_addc_co_u32_e32 v13, vcc, 0, v5, vcc
	v_add_co_u32_e32 v14, vcc, s7, v4
	s_nop 1
	v_addc_co_u32_e32 v15, vcc, 0, v5, vcc
	v_add_co_u32_e32 v16, vcc, s8, v4
	s_nop 1
	v_addc_co_u32_e32 v17, vcc, 0, v5, vcc
	v_add_co_u32_e32 v18, vcc, s9, v4
	s_nop 1
	v_addc_co_u32_e32 v19, vcc, 0, v5, vcc
	v_add_co_u32_e32 v4, vcc, s10, v4
	s_nop 1
	v_addc_co_u32_e32 v5, vcc, 0, v5, vcc
	global_load_dword v44, v[6:7], off
	global_load_dword v45, v[8:9], off
	global_load_dword v46, v[10:11], off
	global_load_dword v47, v[12:13], off
	global_load_dword v48, v[14:15], off
	global_load_dword v49, v[16:17], off
	global_load_dword v50, v[18:19], off
	global_load_dword v51, v[4:5], off
	v_add_co_u32_e32 v4, vcc, s11, v2
	s_mov_b32 s11, 0x61000
	s_nop 0
	v_addc_co_u32_e32 v5, vcc, 0, v3, vcc
	global_load_dword v52, v[4:5], off offset:2048
	v_add_co_u32_e32 v4, vcc, s11, v0
	s_mov_b32 s11, 0xcd000
	s_nop 0
	v_addc_co_u32_e32 v5, vcc, 0, v1, vcc
	v_add_co_u32_e32 v6, vcc, s11, v0
	s_mov_b32 s11, 0x139000
	s_nop 0
	v_addc_co_u32_e32 v7, vcc, 0, v1, vcc
	v_add_co_u32_e32 v8, vcc, s11, v0
	s_mov_b32 s11, 0x1a5000
	s_nop 0
	v_addc_co_u32_e32 v9, vcc, 0, v1, vcc
	v_add_co_u32_e32 v10, vcc, s11, v0
	s_mov_b32 s11, 0x211000
	s_nop 0
	v_addc_co_u32_e32 v11, vcc, 0, v1, vcc
	v_add_co_u32_e32 v12, vcc, s11, v0
	s_mov_b32 s11, 0x27d000
	s_nop 0
	v_addc_co_u32_e32 v13, vcc, 0, v1, vcc
	v_add_co_u32_e32 v14, vcc, s11, v0
	s_mov_b32 s11, 0x2e9000
	s_nop 0
	v_addc_co_u32_e32 v15, vcc, 0, v1, vcc
	v_add_co_u32_e32 v16, vcc, s11, v0
	s_mov_b32 s11, 0x355000
	s_nop 0
	v_addc_co_u32_e32 v17, vcc, 0, v1, vcc
	v_add_co_u32_e32 v18, vcc, s11, v0
	s_movk_i32 s11, 0x2000
	s_nop 0
	v_addc_co_u32_e32 v19, vcc, 0, v1, vcc
	global_load_dword v53, v[4:5], off offset:2048
	global_load_dword v54, v[6:7], off offset:2048
	global_load_dword v55, v[8:9], off offset:2048
	global_load_dword v56, v[10:11], off offset:2048
	global_load_dword v57, v[12:13], off offset:2048
	global_load_dword v58, v[14:15], off offset:2048
	global_load_dword v59, v[16:17], off offset:2048
	global_load_dword v60, v[18:19], off offset:2048
	v_or_b32_e32 v4, 0x2000, v32
	v_mov_b32_e32 v5, v33
	v_lshl_add_u64 v[6:7], s[54:55], 0, v[4:5]
	v_add_co_u32_e32 v8, vcc, s0, v6
	v_or_b32_e32 v32, 0x3000, v32
	s_nop 0
	v_addc_co_u32_e32 v9, vcc, 0, v7, vcc
	v_add_co_u32_e32 v10, vcc, s1, v6
	s_nop 1
	v_addc_co_u32_e32 v11, vcc, 0, v7, vcc
	v_add_co_u32_e32 v12, vcc, s2, v6
	s_nop 1
	v_addc_co_u32_e32 v13, vcc, 0, v7, vcc
	v_add_co_u32_e32 v14, vcc, s6, v6
	s_nop 1
	v_addc_co_u32_e32 v15, vcc, 0, v7, vcc
	v_add_co_u32_e32 v16, vcc, s7, v6
	s_nop 1
	v_addc_co_u32_e32 v17, vcc, 0, v7, vcc
	v_add_co_u32_e32 v18, vcc, s8, v6
	s_nop 1
	v_addc_co_u32_e32 v19, vcc, 0, v7, vcc
	v_add_co_u32_e32 v20, vcc, s9, v6
	s_nop 1
	v_addc_co_u32_e32 v21, vcc, 0, v7, vcc
	v_add_co_u32_e32 v6, vcc, s10, v6
	s_nop 1
	v_addc_co_u32_e32 v7, vcc, 0, v7, vcc
	global_load_dword v61, v[8:9], off
	global_load_dword v62, v[10:11], off
	global_load_dword v63, v[12:13], off
	global_load_dword v64, v[14:15], off
	global_load_dword v65, v[16:17], off
	global_load_dword v66, v[18:19], off
	global_load_dword v67, v[20:21], off
	global_load_dword v68, v[6:7], off
	v_add_co_u32_e32 v6, vcc, s11, v2
	s_mov_b32 s11, 0x62000
	s_nop 0
	v_addc_co_u32_e32 v7, vcc, 0, v3, vcc
	global_load_dword v69, v[6:7], off offset:2048
	v_add_co_u32_e32 v6, vcc, s11, v0
	s_mov_b32 s11, 0xce000
	s_nop 0
	v_addc_co_u32_e32 v7, vcc, 0, v1, vcc
	v_add_co_u32_e32 v8, vcc, s11, v0
	s_mov_b32 s11, 0x13a000
	s_nop 0
	v_addc_co_u32_e32 v9, vcc, 0, v1, vcc
	v_add_co_u32_e32 v10, vcc, s11, v0
	s_mov_b32 s11, 0x1a6000
	s_nop 0
	v_addc_co_u32_e32 v11, vcc, 0, v1, vcc
	v_add_co_u32_e32 v12, vcc, s11, v0
	s_mov_b32 s11, 0x212000
	s_nop 0
	v_addc_co_u32_e32 v13, vcc, 0, v1, vcc
	v_add_co_u32_e32 v14, vcc, s11, v0
	s_mov_b32 s11, 0x27e000
	s_nop 0
	v_addc_co_u32_e32 v15, vcc, 0, v1, vcc
	v_add_co_u32_e32 v16, vcc, s11, v0
	s_mov_b32 s11, 0x2ea000
	s_nop 0
	v_addc_co_u32_e32 v17, vcc, 0, v1, vcc
	v_add_co_u32_e32 v18, vcc, s11, v0
	s_mov_b32 s11, 0x356000
	s_nop 0
	v_addc_co_u32_e32 v19, vcc, 0, v1, vcc
	v_add_co_u32_e32 v20, vcc, s11, v0
	s_movk_i32 s11, 0x3000
	s_nop 0
	v_addc_co_u32_e32 v21, vcc, 0, v1, vcc
	global_load_dword v70, v[6:7], off offset:2048
	global_load_dword v71, v[8:9], off offset:2048
	global_load_dword v72, v[10:11], off offset:2048
	global_load_dword v73, v[12:13], off offset:2048
	global_load_dword v74, v[14:15], off offset:2048
	global_load_dword v75, v[16:17], off offset:2048
	global_load_dword v76, v[18:19], off offset:2048
	s_nop 0
	global_load_dword v20, v[20:21], off offset:2048
	s_nop 0
	global_load_dword v21, v4, s[62:63]
	global_load_dword v77, v32, s[62:63]
	v_lshl_add_u64 v[4:5], s[54:55], 0, v[32:33]
	v_add_co_u32_e32 v6, vcc, s0, v4
	s_mov_b32 s0, 0x63000
	s_nop 0
	v_addc_co_u32_e32 v7, vcc, 0, v5, vcc
	v_add_co_u32_e32 v8, vcc, s1, v4
	s_nop 1
	v_addc_co_u32_e32 v9, vcc, 0, v5, vcc
	v_add_co_u32_e32 v10, vcc, s2, v4
	s_nop 1
	v_addc_co_u32_e32 v11, vcc, 0, v5, vcc
	v_add_co_u32_e32 v12, vcc, s6, v4
	s_nop 1
	v_addc_co_u32_e32 v13, vcc, 0, v5, vcc
	v_add_co_u32_e32 v14, vcc, s7, v4
	s_nop 1
	v_addc_co_u32_e32 v15, vcc, 0, v5, vcc
	v_add_co_u32_e32 v16, vcc, s8, v4
	s_nop 1
	v_addc_co_u32_e32 v17, vcc, 0, v5, vcc
	v_add_co_u32_e32 v18, vcc, s9, v4
	s_nop 1
	v_addc_co_u32_e32 v19, vcc, 0, v5, vcc
	v_add_co_u32_e32 v4, vcc, s10, v4
	s_nop 1
	v_addc_co_u32_e32 v5, vcc, 0, v5, vcc
	v_add_co_u32_e32 v2, vcc, s11, v2
	global_load_dword v32, v[6:7], off
	global_load_dword v78, v[8:9], off
	global_load_dword v79, v[10:11], off
	global_load_dword v80, v[12:13], off
	global_load_dword v81, v[14:15], off
	s_nop 0
	global_load_dword v16, v[16:17], off
	s_nop 0
	global_load_dword v17, v[18:19], off
	s_nop 0
	global_load_dword v18, v[4:5], off
	v_addc_co_u32_e32 v3, vcc, 0, v3, vcc
	global_load_dword v19, v[2:3], off offset:2048
	v_add_co_u32_e32 v2, vcc, s0, v0
	s_mov_b32 s0, 0xcf000
	s_nop 0
	v_addc_co_u32_e32 v3, vcc, 0, v1, vcc
	v_add_co_u32_e32 v4, vcc, s0, v0
	s_mov_b32 s0, 0x13b000
	s_nop 0
	v_addc_co_u32_e32 v5, vcc, 0, v1, vcc
	v_add_co_u32_e32 v6, vcc, s0, v0
	s_mov_b32 s0, 0x1a7000
	s_nop 0
	v_addc_co_u32_e32 v7, vcc, 0, v1, vcc
	v_add_co_u32_e32 v8, vcc, s0, v0
	s_mov_b32 s0, 0x213000
	s_nop 0
	v_addc_co_u32_e32 v9, vcc, 0, v1, vcc
	v_add_co_u32_e32 v10, vcc, s0, v0
	s_mov_b32 s0, 0x27f000
	s_nop 0
	v_addc_co_u32_e32 v11, vcc, 0, v1, vcc
	v_add_co_u32_e32 v12, vcc, s0, v0
	s_mov_b32 s0, 0x2eb000
	s_nop 0
	v_addc_co_u32_e32 v13, vcc, 0, v1, vcc
	v_add_co_u32_e32 v14, vcc, s0, v0
	s_mov_b32 s0, 0x357000
	s_nop 0
	v_addc_co_u32_e32 v15, vcc, 0, v1, vcc
	v_add_co_u32_e32 v0, vcc, s0, v0
	s_movk_i32 s0, 0x800
	s_nop 0
	v_addc_co_u32_e32 v1, vcc, 0, v1, vcc
	global_load_dword v2, v[2:3], off offset:2048
	s_nop 0
	global_load_dword v3, v[4:5], off offset:2048
	s_nop 0
	global_load_dword v4, v[6:7], off offset:2048
	global_load_dword v5, v[8:9], off offset:2048
	s_nop 0
	global_load_dword v6, v[10:11], off offset:2048
	global_load_dword v7, v[12:13], off offset:2048
	global_load_dword v8, v[14:15], off offset:2048
	s_nop 0
	global_load_dword v0, v[0:1], off offset:2048
	s_waitcnt vmcnt(55)
	v_add_f32_e32 v1, v41, v23
	s_waitcnt vmcnt(54)
	v_add_f32_e32 v9, v42, v30
	v_add_f32_e32 v1, v1, v24
	v_add_f32_e32 v9, v9, v29
	v_add_f32_e32 v1, v1, v25
	v_add_f32_e32 v9, v9, v28
	v_add_f32_e32 v1, v1, v26
	v_add_f32_e32 v9, v9, v27
	v_add_f32_e32 v1, v1, v31
	v_add_f32_e32 v9, v9, v40
	v_add_f32_e32 v1, v1, v34
	v_add_f32_e32 v9, v9, v39
	v_add_f32_e32 v1, v1, v35
	v_add_f32_e32 v9, v9, v38
	v_add_f32_e32 v1, v1, v36
	v_add_f32_e32 v9, v9, v37
	ds_write2st64_b32 v22, v1, v9 offset1:8
	s_waitcnt vmcnt(52)
	v_add_f32_e32 v1, v43, v44
	s_waitcnt vmcnt(43)
	v_add_f32_e32 v9, v52, v53
	v_add_f32_e32 v1, v1, v45
	s_waitcnt vmcnt(42)
	v_add_f32_e32 v9, v9, v54
	v_add_f32_e32 v1, v1, v46
	s_waitcnt vmcnt(41)
	v_add_f32_e32 v9, v9, v55
	v_add_f32_e32 v1, v1, v47
	s_waitcnt vmcnt(40)
	v_add_f32_e32 v9, v9, v56
	v_add_f32_e32 v1, v1, v48
	s_waitcnt vmcnt(39)
	v_add_f32_e32 v9, v9, v57
	v_add_f32_e32 v1, v1, v49
	s_waitcnt vmcnt(38)
	v_add_f32_e32 v9, v9, v58
	v_add_f32_e32 v1, v1, v50
	s_waitcnt vmcnt(37)
	v_add_f32_e32 v9, v9, v59
	v_add_f32_e32 v1, v1, v51
	s_waitcnt vmcnt(36)
	v_add_f32_e32 v9, v9, v60
	ds_write2st64_b32 v22, v1, v9 offset0:16 offset1:24
	s_waitcnt vmcnt(18)
	v_add_f32_e32 v1, v21, v61
	v_add_f32_e32 v9, v69, v70
	v_add_f32_e32 v1, v1, v62
	v_add_f32_e32 v9, v9, v71
	v_add_f32_e32 v1, v1, v63
	v_add_f32_e32 v9, v9, v72
	v_add_f32_e32 v1, v1, v64
	v_add_f32_e32 v9, v9, v73
	v_add_f32_e32 v1, v1, v65
	v_add_f32_e32 v9, v9, v74
	v_add_f32_e32 v1, v1, v66
	v_add_f32_e32 v9, v9, v75
	v_add_f32_e32 v1, v1, v67
	v_add_f32_e32 v9, v9, v76
	v_add_f32_e32 v1, v1, v68
	v_add_f32_e32 v9, v9, v20
	ds_write2st64_b32 v22, v1, v9 offset0:32 offset1:40
	s_waitcnt vmcnt(16)
	v_add_f32_e32 v1, v77, v32
	s_waitcnt vmcnt(15)
	v_add_f32_e32 v1, v1, v78
	s_waitcnt vmcnt(14)
	v_add_f32_e32 v1, v1, v79
	s_waitcnt vmcnt(13)
	v_add_f32_e32 v1, v1, v80
	s_waitcnt vmcnt(12)
	v_add_f32_e32 v1, v1, v81
	s_waitcnt vmcnt(11)
	v_add_f32_e32 v1, v1, v16
	s_waitcnt vmcnt(10)
	v_add_f32_e32 v1, v1, v17
	v_lshl_add_u32 v36, s60, 3, v125
	s_waitcnt vmcnt(9)
	v_add_f32_e32 v1, v1, v18
	v_cmp_gt_i32_e32 vcc, s0, v36
	s_waitcnt vmcnt(7)
	v_add_f32_e32 v2, v19, v2
	s_waitcnt vmcnt(6)
	v_add_f32_e32 v2, v2, v3
	s_waitcnt vmcnt(5)
	v_add_f32_e32 v2, v2, v4
	s_waitcnt vmcnt(4)
	v_add_f32_e32 v2, v2, v5
	s_waitcnt vmcnt(3)
	v_add_f32_e32 v2, v2, v6
	s_waitcnt vmcnt(2)
	v_add_f32_e32 v2, v2, v7
	s_waitcnt vmcnt(1)
	v_add_f32_e32 v2, v2, v8
	s_waitcnt vmcnt(0)
	v_add_f32_e32 v0, v2, v0
	ds_write2st64_b32 v22, v1, v0 offset0:48 offset1:56
	s_waitcnt lgkmcnt(0)
	s_barrier
	s_and_saveexec_b64 s[0:1], vcc
	s_cbranch_execz .LBB0_143
	v_mbcnt_lo_u32_b32 v0, -1, 0
	v_mbcnt_hi_u32_b32 v0, -1, v0
	v_and_b32_e32 v1, 64, v0
	v_add_u32_e32 v1, 64, v1
	v_xor_b32_e32 v2, 32, v0
	v_cmp_lt_i32_e32 vcc, v2, v1
	v_lshlrev_b32_e32 v32, 4, v85
	v_add_u32_e32 v30, 0, v32
	v_cndmask_b32_e32 v2, v0, v2, vcc
	v_lshlrev_b32_e32 v84, 2, v2
	v_xor_b32_e32 v2, 16, v0
	v_cmp_lt_i32_e32 vcc, v2, v1
	v_or_b32_e32 v20, 0x1000, v32
	v_mov_b32_e32 v21, v33
	v_cndmask_b32_e32 v2, v0, v2, vcc
	v_lshlrev_b32_e32 v86, 2, v2
	v_xor_b32_e32 v2, 8, v0
	v_cmp_lt_i32_e32 vcc, v2, v1
	v_lshl_add_u64 v[56:57], s[64:65], 0, v[20:21]
	v_lshl_add_u64 v[38:39], s[64:65], 0, v[32:33]
	v_cndmask_b32_e32 v2, v0, v2, vcc
	v_lshlrev_b32_e32 v87, 2, v2
	v_xor_b32_e32 v2, 4, v0
	v_cmp_lt_i32_e32 vcc, v2, v1
	ds_read_b128 v[8:11], v30 offset:9216
	v_or_b32_e32 v28, 0x1800, v32
	v_cndmask_b32_e32 v2, v0, v2, vcc
	v_lshlrev_b32_e32 v88, 2, v2
	v_xor_b32_e32 v2, 2, v0
	v_cmp_lt_i32_e32 vcc, v2, v1
	s_waitcnt lgkmcnt(0)
	v_pk_add_f32 v[44:45], v[8:9], 1.0 op_sel_hi:[1,0]
	v_pk_add_f32 v[46:47], v[10:11], 1.0 op_sel_hi:[1,0]
	v_cndmask_b32_e32 v2, v0, v2, vcc
	v_lshlrev_b32_e32 v89, 2, v2
	v_xor_b32_e32 v2, 1, v0
	v_cmp_lt_i32_e32 vcc, v2, v1
	v_mov_b32_e32 v29, v33
	v_lshl_add_u64 v[68:69], s[64:65], 0, v[28:29]
	v_cndmask_b32_e32 v4, v0, v2, vcc
	ds_read_b128 v[0:3], v30 offset:8192
	v_lshlrev_b32_e32 v90, 2, v4
	v_ashrrev_i32_e32 v37, 31, v36
	s_lshl_b32 s6, s58, 3
	s_mov_b64 s[8:9], 0x1000
	s_waitcnt lgkmcnt(0)
	v_pk_add_f32 v[40:41], v[0:1], 1.0 op_sel_hi:[1,0]
	v_pk_add_f32 v[42:43], v[2:3], 1.0 op_sel_hi:[1,0]
	ds_read_b128 v[12:15], v30 offset:10240
	ds_read_b128 v[0:3], v30
	ds_read_b128 v[4:7], v30 offset:1024
	ds_read_b128 v[16:19], v30 offset:11264
	s_ashr_i32 s7, s6, 31
	s_waitcnt lgkmcnt(3)
	v_pk_add_f32 v[48:49], v[12:13], 1.0 op_sel_hi:[1,0]
	v_pk_add_f32 v[50:51], v[14:15], 1.0 op_sel_hi:[1,0]
	ds_read_b128 v[8:11], v30 offset:2048
	ds_read_b128 v[12:15], v30 offset:3072
	s_waitcnt lgkmcnt(2)
	v_pk_add_f32 v[52:53], v[16:17], 1.0 op_sel_hi:[1,0]
	v_pk_add_f32 v[54:55], v[18:19], 1.0 op_sel_hi:[1,0]
	ds_read_b128 v[16:19], v30 offset:12288
	ds_read_b128 v[24:27], v30 offset:13312
	s_mov_b64 s[10:11], 0
	s_mov_b32 s2, 0x800000
	s_waitcnt lgkmcnt(1)
	v_pk_add_f32 v[58:59], v[16:17], 1.0 op_sel_hi:[1,0]
	v_or_b32_e32 v16, 0x1400, v32
	v_mov_b32_e32 v17, v33
	v_pk_add_f32 v[60:61], v[18:19], 1.0 op_sel_hi:[1,0]
	v_lshl_add_u64 v[62:63], s[64:65], 0, v[16:17]
	ds_read_b128 v[16:19], v30 offset:4096
	ds_read_b128 v[20:23], v30 offset:5120
	s_waitcnt lgkmcnt(2)
	v_pk_add_f32 v[64:65], v[24:25], 1.0 op_sel_hi:[1,0]
	v_pk_add_f32 v[66:67], v[26:27], 1.0 op_sel_hi:[1,0]
	ds_read_b128 v[24:27], v30 offset:14336
	ds_read_b128 v[76:79], v30 offset:15360
	v_or_b32_e32 v32, 0x1c00, v32
	v_lshl_add_u64 v[74:75], s[64:65], 0, v[32:33]
	v_lshlrev_b32_e32 v32, 3, v85
	s_waitcnt lgkmcnt(1)
	v_pk_add_f32 v[70:71], v[24:25], 1.0 op_sel_hi:[1,0]
	v_pk_add_f32 v[72:73], v[26:27], 1.0 op_sel_hi:[1,0]
	ds_read_b128 v[24:27], v30 offset:6144
	ds_read_b128 v[28:31], v30 offset:7168
	v_lshl_add_u64 v[80:81], s[34:35], 0, v[32:33]
	v_lshlrev_b64 v[32:33], 13, v[36:37]
	v_lshl_or_b32 v32, v85, 4, v32
	v_lshl_add_u64 v[32:33], s[56:57], 0, v[32:33]
	s_waitcnt lgkmcnt(2)
	v_pk_add_f32 v[76:77], v[76:77], 1.0 op_sel_hi:[1,0]
	v_pk_add_f32 v[78:79], v[78:79], 1.0 op_sel_hi:[1,0]
	v_lshl_add_u64 v[82:83], v[32:33], 0, s[8:9]
	s_lshl_b64 s[8:9], s[6:7], 13
	v_mov_b32_e32 v37, 0x358637bd
	s_movk_i32 s7, 0x7ff
	global_load_dwordx4 v[180:183], v[38:39], off offset:1024
	global_load_dwordx4 v[184:187], v[38:39], off offset:2048
	global_load_dwordx4 v[188:191], v[38:39], off offset:3072
	global_load_dwordx4 v[192:195], v[56:57], off
	global_load_dwordx4 v[196:199], v[62:63], off
	global_load_dwordx4 v[200:203], v[68:69], off
	global_load_dwordx4 v[204:207], v[74:75], off
.LBB0_142:
	global_load_dwordx4 v[92:95], v[82:83], off offset:-4096 nt
	global_load_dwordx4 v[96:99], v[82:83], off offset:-3072 nt
	global_load_dwordx4 v[100:103], v[82:83], off offset:-2048 nt
	global_load_dwordx4 v[104:107], v[82:83], off offset:-1024 nt
	global_load_dwordx4 v[108:111], v[82:83], off nt
	global_load_dwordx4 v[112:115], v[82:83], off offset:1024 nt
	global_load_dwordx4 v[116:119], v[82:83], off offset:2048 nt
	global_load_dwordx4 v[32:35], v[82:83], off offset:3072 nt
	global_load_dwordx4 v[120:123], v[38:39], off
	v_add_u32_e32 v126, 0x4000, v36
	v_ashrrev_i32_e32 v127, 31, v126
	v_lshlrev_b64 v[126:127], 12, v[126:127]
	v_lshl_add_u64 v[126:127], v[80:81], 0, v[126:127]
	v_add_u32_e32 v36, s6, v36
	v_lshl_add_u64 v[82:83], v[82:83], 0, s[8:9]
	s_waitcnt vmcnt(8)
	v_mul_f32_e32 v91, v93, v93
	s_waitcnt vmcnt(7)
	v_mul_f32_e32 v124, v97, v97
	s_waitcnt vmcnt(6)
	v_mul_f32_e32 v145, v101, v101
	v_fmac_f32_e32 v91, v92, v92
	v_fmac_f32_e32 v124, v96, v96
	s_waitcnt vmcnt(5)
	v_mul_f32_e32 v146, v105, v105
	s_waitcnt vmcnt(4)
	v_mov_b32_e32 v130, v109
	s_waitcnt vmcnt(3)
	v_mov_b32_e32 v131, v113
	v_fmac_f32_e32 v145, v100, v100
	v_fmac_f32_e32 v91, v94, v94
	v_fmac_f32_e32 v124, v98, v98
	v_mov_b32_e32 v128, v108
	v_mov_b32_e32 v129, v112
	v_fmac_f32_e32 v146, v104, v104
	v_pk_mul_f32 v[130:131], v[130:131], v[130:131]
	v_fmac_f32_e32 v145, v102, v102
	v_fmac_f32_e32 v91, v95, v95
	v_fmac_f32_e32 v124, v99, v99
	v_mov_b32_e32 v132, v110
	v_mov_b32_e32 v133, v114
	s_waitcnt vmcnt(2)
	v_mov_b32_e32 v138, v117
	s_waitcnt vmcnt(1)
	v_mov_b32_e32 v139, v33
	v_fmac_f32_e32 v146, v106, v106
	v_pk_fma_f32 v[128:129], v[128:129], v[128:129], v[130:131]
	v_fmac_f32_e32 v145, v103, v103
	v_add_f32_e32 v91, v91, v124
	v_mov_b32_e32 v134, v111
	v_mov_b32_e32 v135, v115
	v_mov_b32_e32 v136, v116
	v_mov_b32_e32 v137, v32
	v_pk_mul_f32 v[138:139], v[138:139], v[138:139]
	v_fmac_f32_e32 v146, v107, v107
	v_pk_fma_f32 v[128:129], v[132:133], v[132:133], v[128:129]
	v_add_f32_e32 v91, v91, v145
	v_mov_b32_e32 v140, v118
	v_mov_b32_e32 v141, v34
	v_pk_fma_f32 v[130:131], v[136:137], v[136:137], v[138:139]
	v_pk_fma_f32 v[128:129], v[134:135], v[134:135], v[128:129]
	v_add_f32_e32 v91, v91, v146
	v_mov_b32_e32 v142, v119
	v_mov_b32_e32 v143, v35
	v_pk_fma_f32 v[130:131], v[140:141], v[140:141], v[130:131]
	v_add_f32_e32 v91, v91, v128
	v_pk_fma_f32 v[130:131], v[142:143], v[142:143], v[130:131]
	v_add_f32_e32 v91, v91, v129
	v_add_f32_e32 v91, v91, v130
	v_add_f32_e32 v91, v91, v131
	ds_bpermute_b32 v124, v84, v91
	s_waitcnt lgkmcnt(0)
	v_add_f32_e32 v91, v91, v124
	ds_bpermute_b32 v124, v86, v91
	s_waitcnt lgkmcnt(0)
	v_add_f32_e32 v91, v91, v124
	ds_bpermute_b32 v124, v87, v91
	s_waitcnt lgkmcnt(0)
	v_add_f32_e32 v91, v91, v124
	ds_bpermute_b32 v124, v88, v91
	s_waitcnt lgkmcnt(0)
	v_add_f32_e32 v91, v91, v124
	ds_bpermute_b32 v124, v89, v91
	s_waitcnt lgkmcnt(0)
	v_add_f32_e32 v91, v91, v124
	ds_bpermute_b32 v124, v90, v91
	s_waitcnt lgkmcnt(0)
	v_add_f32_e32 v91, v91, v124
	v_fmamk_f32 v91, v91, 0x3a000000, v37
	v_mul_f32_e32 v124, 0x4b800000, v91
	v_cmp_gt_f32_e32 vcc, s2, v91
	s_nop 1
	v_cndmask_b32_e32 v91, v91, v124, vcc
	v_rsq_f32_e32 v91, v91
	s_nop 0
	v_mul_f32_e32 v124, 0x45800000, v91
	v_cndmask_b32_e32 v124, v91, v124, vcc
	v_pk_mul_f32 v[92:93], v[92:93], v[124:125] op_sel_hi:[1,0]
	v_pk_mul_f32 v[94:95], v[94:95], v[124:125] op_sel_hi:[1,0]
	s_waitcnt vmcnt(0)
	v_pk_mul_f32 v[92:93], v[120:121], v[92:93]
	v_pk_mul_f32 v[94:95], v[122:123], v[94:95]
	v_pk_fma_f32 v[92:93], v[40:41], v[92:93], v[0:1]
	v_pk_fma_f32 v[94:95], v[42:43], v[94:95], v[2:3]
	v_cvt_pk_bf16_f32 v92, v92, v93
	v_cvt_pk_bf16_f32 v93, v94, v95
	global_store_dwordx2 v[126:127], v[92:93], off
	v_pk_mul_f32 v[96:97], v[96:97], v[124:125] op_sel_hi:[1,0]
	v_pk_mul_f32 v[98:99], v[98:99], v[124:125] op_sel_hi:[1,0]
	v_pk_mul_f32 v[32:33], v[32:33], v[124:125] op_sel_hi:[1,0]
	v_pk_mul_f32 v[34:35], v[34:35], v[124:125] op_sel_hi:[1,0]
	v_cmp_lt_i32_e32 vcc, s7, v36
	s_or_b64 s[10:11], vcc, s[10:11]
	v_pk_mul_f32 v[92:93], v[180:181], v[96:97]
	v_pk_mul_f32 v[94:95], v[182:183], v[98:99]
	v_pk_fma_f32 v[92:93], v[44:45], v[92:93], v[4:5]
	v_pk_fma_f32 v[94:95], v[46:47], v[94:95], v[6:7]
	v_cvt_pk_bf16_f32 v92, v92, v93
	v_cvt_pk_bf16_f32 v93, v94, v95
	global_store_dwordx2 v[126:127], v[92:93], off offset:512
	v_pk_mul_f32 v[96:97], v[100:101], v[124:125] op_sel_hi:[1,0]
	v_pk_mul_f32 v[98:99], v[102:103], v[124:125] op_sel_hi:[1,0]
	v_pk_mul_f32 v[92:93], v[184:185], v[96:97]
	v_pk_mul_f32 v[94:95], v[186:187], v[98:99]
	v_pk_fma_f32 v[92:93], v[48:49], v[92:93], v[8:9]
	v_pk_fma_f32 v[94:95], v[50:51], v[94:95], v[10:11]
	v_cvt_pk_bf16_f32 v92, v92, v93
	v_cvt_pk_bf16_f32 v93, v94, v95
	global_store_dwordx2 v[126:127], v[92:93], off offset:1024
	v_pk_mul_f32 v[96:97], v[104:105], v[124:125] op_sel_hi:[1,0]
	v_pk_mul_f32 v[98:99], v[106:107], v[124:125] op_sel_hi:[1,0]
	v_pk_mul_f32 v[92:93], v[96:97], v[188:189]
	v_pk_mul_f32 v[94:95], v[98:99], v[190:191]
	v_pk_fma_f32 v[92:93], v[92:93], v[52:53], v[12:13]
	v_pk_fma_f32 v[94:95], v[94:95], v[54:55], v[14:15]
	v_cvt_pk_bf16_f32 v92, v92, v93
	v_cvt_pk_bf16_f32 v93, v94, v95
	global_store_dwordx2 v[126:127], v[92:93], off offset:1536
	v_pk_mul_f32 v[96:97], v[108:109], v[124:125] op_sel_hi:[1,0]
	v_pk_mul_f32 v[98:99], v[110:111], v[124:125] op_sel_hi:[1,0]
	v_pk_mul_f32 v[92:93], v[96:97], v[192:193]
	v_pk_mul_f32 v[94:95], v[98:99], v[194:195]
	v_pk_fma_f32 v[92:93], v[92:93], v[58:59], v[16:17]
	v_pk_fma_f32 v[94:95], v[94:95], v[60:61], v[18:19]
	v_cvt_pk_bf16_f32 v92, v92, v93
	v_cvt_pk_bf16_f32 v93, v94, v95
	global_store_dwordx2 v[126:127], v[92:93], off offset:2048
	v_pk_mul_f32 v[96:97], v[112:113], v[124:125] op_sel_hi:[1,0]
	v_pk_mul_f32 v[98:99], v[114:115], v[124:125] op_sel_hi:[1,0]
	v_pk_mul_f32 v[92:93], v[96:97], v[196:197]
	v_pk_mul_f32 v[94:95], v[98:99], v[198:199]
	v_pk_fma_f32 v[92:93], v[92:93], v[64:65], v[20:21]
	v_pk_fma_f32 v[94:95], v[94:95], v[66:67], v[22:23]
	v_cvt_pk_bf16_f32 v92, v92, v93
	v_cvt_pk_bf16_f32 v93, v94, v95
	global_store_dwordx2 v[126:127], v[92:93], off offset:2560
	v_pk_mul_f32 v[96:97], v[116:117], v[124:125] op_sel_hi:[1,0]
	v_pk_mul_f32 v[98:99], v[118:119], v[124:125] op_sel_hi:[1,0]
	v_pk_mul_f32 v[92:93], v[96:97], v[200:201]
	v_pk_mul_f32 v[94:95], v[98:99], v[202:203]
	v_pk_fma_f32 v[92:93], v[92:93], v[70:71], v[24:25]
	v_pk_fma_f32 v[94:95], v[94:95], v[72:73], v[26:27]
	v_cvt_pk_bf16_f32 v92, v92, v93
	v_cvt_pk_bf16_f32 v93, v94, v95
	global_store_dwordx2 v[126:127], v[92:93], off offset:3072
	v_pk_mul_f32 v[32:33], v[32:33], v[204:205]
	v_pk_mul_f32 v[34:35], v[34:35], v[206:207]
	v_pk_fma_f32 v[32:33], v[32:33], v[76:77], v[28:29]
	v_pk_fma_f32 v[34:35], v[34:35], v[78:79], v[30:31]
	v_cvt_pk_bf16_f32 v32, v32, v33
	v_cvt_pk_bf16_f32 v33, v34, v35
	global_store_dwordx2 v[126:127], v[32:33], off offset:3584
	s_andn2_b64 exec, exec, s[10:11]
	s_cbranch_execnz .LBB0_142

.LBB0_150:
	s_cmp_ge_i32 s0, s6
	s_cbranch_scc1 .LBB0_159
	v_lshlrev_b32_e32 v68, 2, v144
	v_mov_b32_e32 v69, 0
	v_lshlrev_b32_e32 v70, 2, v85
	v_or_b32_e32 v2, 0x1000, v68
	v_mov_b32_e32 v3, v69
	v_add_u32_e32 v71, 0, v68
	v_or_b32_e32 v78, 0x400, v70
	v_lshl_add_u64 v[86:87], s[62:63], 0, v[68:69]
	v_lshl_add_u64 v[88:89], s[54:55], 0, v[68:69]
	v_lshl_add_u64 v[90:91], s[62:63], 0, v[2:3]
	v_lshl_add_u64 v[92:93], s[54:55], 0, v[2:3]
	v_or_b32_e32 v2, 0x2000, v68
	v_or_b32_e32 v68, 0x3000, v68
	v_or_b32_e32 v80, 0x500, v70
	v_lshl_add_u64 v[106:107], s[62:63], 0, v[68:69]
	v_lshl_add_u64 v[108:109], s[54:55], 0, v[68:69]
	v_lshlrev_b32_e32 v68, 2, v78
	v_or_b32_e32 v82, 0x600, v70
	s_mov_b64 s[8:9], 0x1800
	v_lshl_add_u64 v[116:117], s[64:65], 0, v[68:69]
	v_lshlrev_b32_e32 v68, 2, v80
	v_or_b32_e32 v84, 0x700, v70
	v_lshlrev_b32_e32 v0, 4, v85
	v_lshl_add_u64 v[94:95], v[86:87], 0, s[8:9]
	v_lshl_add_u64 v[96:97], v[88:89], 0, s[8:9]
	s_mov_b64 s[8:9], 0x2800
	v_mov_b32_e32 v1, v69
	v_lshl_add_u64 v[118:119], s[64:65], 0, v[68:69]
	v_lshlrev_b32_e32 v68, 2, v82
	v_add_u32_e32 v73, 0, v0
	v_lshl_add_u64 v[102:103], v[86:87], 0, s[8:9]
	v_lshl_add_u64 v[104:105], v[88:89], 0, s[8:9]
	s_mov_b64 s[8:9], 0x3800
	v_lshl_add_u64 v[114:115], s[64:65], 0, v[0:1]
	v_lshl_add_u64 v[120:121], s[64:65], 0, v[68:69]
	v_lshlrev_b32_e32 v68, 2, v84
	v_mbcnt_lo_u32_b32 v0, -1, 0
	v_or_b32_e32 v72, 0x100, v70
	v_or_b32_e32 v74, 0x200, v70
	v_or_b32_e32 v76, 0x300, v70
	v_lshl_add_u64 v[98:99], s[62:63], 0, v[2:3]
	v_lshl_add_u64 v[100:101], s[54:55], 0, v[2:3]
	v_lshl_add_u64 v[110:111], v[86:87], 0, s[8:9]
	v_lshl_add_u64 v[112:113], v[88:89], 0, s[8:9]
	v_lshl_add_u64 v[122:123], s[64:65], 0, v[68:69]
	s_mov_b32 s2, -1
	v_mov_b32_e32 v124, 0x358637bd
	s_mov_b32 s8, 0x3a000000
	s_mov_b32 s1, 0x800000
	s_mov_b64 s[10:11], 0x10000
	s_mov_b64 s[12:13], 0x8000
	v_mov_b32_e32 v75, 0xc000
	v_mbcnt_hi_u32_b32 v77, -1, v0
	global_load_dwordx4 v[180:183], v[114:115], off
	global_load_dwordx4 v[184:187], v[114:115], off offset:1024
	global_load_dwordx4 v[188:191], v[114:115], off offset:2048
	global_load_dwordx4 v[192:195], v[114:115], off offset:3072
	global_load_dwordx4 v[196:199], v[116:117], off
	global_load_dwordx4 v[200:203], v[118:119], off
	global_load_dwordx4 v[204:207], v[120:121], off
	global_load_dwordx4 v[208:211], v[122:123], off
	s_branch .LBB0_153

.LBB0_158:
	v_mov_b32_e32 v47, v69
	v_lshl_add_u64 v[4:5], v[54:55], 0, v[46:47]
	v_mov_b32_e32 v53, v69
	global_load_dwordx4 v[48:51], v[4:5], off nt
	v_lshl_add_u64 v[4:5], v[54:55], 0, v[52:53]
	v_mov_b32_e32 v35, v69
	global_load_dwordx4 v[40:43], v[4:5], off nt
	v_mov_b32_e32 v33, v69
	v_lshl_add_u64 v[4:5], v[54:55], 0, v[34:35]
	v_lshl_add_u64 v[130:131], v[54:55], 0, s[10:11]
	v_lshl_add_u64 v[6:7], v[54:55], 0, v[32:33]
	global_load_dwordx4 v[36:39], v[4:5], off nt
	global_load_dwordx4 v[28:31], v[6:7], off nt
	v_lshl_add_u64 v[4:5], v[130:131], 0, v[52:53]
	v_lshl_add_u64 v[8:9], v[130:131], 0, v[68:69]
	global_load_dwordx4 v[4:7], v[4:5], off nt
	v_lshlrev_b32_e32 v68, 2, v72
	global_load_dwordx4 v[24:27], v[8:9], off nt
	v_lshl_add_u64 v[8:9], v[130:131], 0, v[46:47]
	v_lshl_add_u64 v[12:13], v[130:131], 0, v[68:69]
	global_load_dwordx4 v[8:11], v[8:9], off nt
	s_nop 0
	global_load_dwordx4 v[20:23], v[12:13], off nt
	global_load_dwordx4 v[60:63], v[44:45], off offset:1024 nt
	v_lshlrev_b32_e32 v68, 2, v74
	v_lshl_add_u64 v[12:13], v[130:131], 0, v[68:69]
	global_load_dwordx4 v[16:19], v[12:13], off nt
	global_load_dwordx4 v[56:59], v[44:45], off offset:2048 nt
	global_load_dwordx4 v[52:55], v[44:45], off offset:3072 nt
	v_lshlrev_b32_e32 v68, 2, v76
	v_lshl_add_u64 v[12:13], v[130:131], 0, v[68:69]
	global_load_dwordx4 v[12:15], v[12:13], off nt
	v_and_b32_e32 v44, 64, v77
	v_lshl_add_u64 v[34:35], v[130:131], 0, v[34:35]
	v_lshl_add_u64 v[32:33], v[130:131], 0, v[32:33]
	global_load_dwordx4 v[64:67], v[114:115], off
	v_add_u32_e32 v81, 64, v44
	global_load_dwordx4 v[44:47], v[34:35], off nt
	s_nop 0
	global_load_dwordx4 v[32:35], v[32:33], off nt
	s_waitcnt vmcnt(16)
	v_mov_b32_e32 v135, v1
	v_mov_b32_e32 v133, v0
	v_mov_b32_e32 v137, v2
	v_mov_b32_e32 v139, v3
	v_xor_b32_e32 v68, 32, v77
	v_cmp_lt_i32_e32 vcc, v68, v81
	v_xor_b32_e32 v79, 16, v77
	v_mov_b32_e32 v127, v69
	v_cndmask_b32_e32 v68, v77, v68, vcc
	v_lshlrev_b32_e32 v68, 2, v68
	v_cmp_lt_i32_e32 vcc, v79, v81
	s_mov_b32 s7, s0
	s_waitcnt vmcnt(15)
	v_mov_b32_e32 v140, v49
	v_mov_b32_e32 v130, v48
	v_mov_b32_e32 v142, v50
	s_waitcnt vmcnt(14)
	v_mov_b32_e32 v141, v41
	v_mov_b32_e32 v131, v40
	v_pk_mul_f32 v[140:141], v[140:141], v[140:141]
	v_mov_b32_e32 v143, v42
	s_waitcnt vmcnt(13)
	v_mov_b32_e32 v150, v37
	s_waitcnt vmcnt(12)
	v_mov_b32_e32 v151, v29
	v_mov_b32_e32 v148, v36
	v_mov_b32_e32 v149, v28
	v_pk_mul_f32 v[150:151], v[150:151], v[150:151]
	v_mov_b32_e32 v152, v38
	s_waitcnt vmcnt(10)
	v_mov_b32_e32 v134, v25
	v_mov_b32_e32 v132, v24
	v_pk_mul_f32 v[134:135], v[134:135], v[134:135]
	v_mov_b32_e32 v153, v30
	v_mov_b32_e32 v136, v26
	v_pk_fma_f32 v[130:131], v[130:131], v[130:131], v[140:141]
	v_pk_fma_f32 v[140:141], v[148:149], v[148:149], v[150:151]
	v_pk_fma_f32 v[132:133], v[132:133], v[132:133], v[134:135]
	v_mov_b32_e32 v138, v27
	v_pk_fma_f32 v[134:135], v[152:153], v[152:153], v[140:141]
	v_pk_fma_f32 v[132:133], v[136:137], v[136:137], v[132:133]
	s_waitcnt vmcnt(8)
	v_mov_b32_e32 v140, v21
	s_waitcnt vmcnt(7)
	v_mov_b32_e32 v141, v61
	v_pk_fma_f32 v[132:133], v[138:139], v[138:139], v[132:133]
	v_mov_b32_e32 v138, v20
	v_mov_b32_e32 v139, v60
	v_pk_mul_f32 v[140:141], v[140:141], v[140:141]
	v_mov_b32_e32 v159, v5
	v_pk_fma_f32 v[138:139], v[138:139], v[138:139], v[140:141]
	v_mov_b32_e32 v140, v22
	v_mov_b32_e32 v141, v62
	v_pk_fma_f32 v[138:139], v[140:141], v[140:141], v[138:139]
	v_mov_b32_e32 v140, v23
	v_mov_b32_e32 v141, v63
	v_pk_fma_f32 v[138:139], v[140:141], v[140:141], v[138:139]
	s_waitcnt vmcnt(6)
	v_mov_b32_e32 v140, v17
	s_waitcnt vmcnt(5)
	v_mov_b32_e32 v141, v57
	v_pk_add_f32 v[132:133], v[132:133], v[138:139]
	v_mov_b32_e32 v138, v16
	v_mov_b32_e32 v139, v56
	v_pk_mul_f32 v[140:141], v[140:141], v[140:141]
	v_mov_b32_e32 v158, v9
	v_pk_fma_f32 v[138:139], v[138:139], v[138:139], v[140:141]
	v_mov_b32_e32 v140, v18
	v_mov_b32_e32 v141, v58
	v_pk_fma_f32 v[138:139], v[140:141], v[140:141], v[138:139]
	v_mov_b32_e32 v140, v19
	v_mov_b32_e32 v141, v59
	v_pk_fma_f32 v[138:139], v[140:141], v[140:141], v[138:139]
	s_waitcnt vmcnt(3)
	v_mov_b32_e32 v140, v13
	v_mov_b32_e32 v141, v53
	v_mov_b32_e32 v157, v4
	v_mov_b32_e32 v156, v8
	v_pk_mul_f32 v[136:137], v[158:159], v[158:159]
	v_pk_add_f32 v[132:133], v[132:133], v[138:139]
	v_mov_b32_e32 v138, v12
	v_mov_b32_e32 v139, v52
	v_pk_mul_f32 v[140:141], v[140:141], v[140:141]
	v_mov_b32_e32 v161, v6
	v_mov_b32_e32 v160, v10
	v_pk_fma_f32 v[136:137], v[156:157], v[156:157], v[136:137]
	v_pk_fma_f32 v[138:139], v[138:139], v[138:139], v[140:141]
	v_mov_b32_e32 v140, v14
	v_mov_b32_e32 v141, v54
	v_mov_b32_e32 v146, v51
	v_mov_b32_e32 v147, v43
	v_mov_b32_e32 v163, v7
	v_pk_fma_f32 v[130:131], v[142:143], v[142:143], v[130:131]
	v_mov_b32_e32 v162, v11
	v_pk_fma_f32 v[136:137], v[160:161], v[160:161], v[136:137]
	v_pk_fma_f32 v[138:139], v[140:141], v[140:141], v[138:139]
	v_mov_b32_e32 v140, v15
	v_mov_b32_e32 v141, v55
	v_pk_fma_f32 v[130:131], v[146:147], v[146:147], v[130:131]
	v_pk_fma_f32 v[136:137], v[162:163], v[162:163], v[136:137]
	v_pk_fma_f32 v[138:139], v[140:141], v[140:141], v[138:139]
	s_waitcnt vmcnt(1)
	v_mov_b32_e32 v140, v45
	v_pk_add_f32 v[132:133], v[132:133], v[138:139]
	v_mov_b32_e32 v138, v136
	v_mov_b32_e32 v139, v130
	s_waitcnt vmcnt(0)
	v_mov_b32_e32 v141, v33
	v_pk_add_f32 v[132:133], v[132:133], v[138:139]
	v_mov_b32_e32 v138, v44
	v_mov_b32_e32 v139, v32
	v_pk_mul_f32 v[140:141], v[140:141], v[140:141]
	v_mov_b32_e32 v154, v39
	v_pk_fma_f32 v[138:139], v[138:139], v[138:139], v[140:141]
	v_mov_b32_e32 v140, v46
	v_mov_b32_e32 v141, v34
	v_mov_b32_e32 v155, v31
	v_pk_fma_f32 v[138:139], v[140:141], v[140:141], v[138:139]
	v_mov_b32_e32 v140, v47
	v_mov_b32_e32 v141, v35
	v_pk_fma_f32 v[134:135], v[154:155], v[154:155], v[134:135]
	v_pk_fma_f32 v[138:139], v[140:141], v[140:141], v[138:139]
	v_mov_b32_e32 v130, v137
	v_pk_add_f32 v[130:131], v[132:133], v[130:131]
	v_mov_b32_e32 v132, v138
	v_mov_b32_e32 v133, v134
	v_pk_add_f32 v[130:131], v[130:131], v[132:133]
	v_mov_b32_e32 v134, v139
	v_pk_add_f32 v[130:131], v[130:131], v[134:135]
	ds_bpermute_b32 v133, v68, v131
	ds_bpermute_b32 v132, v68, v130
	v_cndmask_b32_e32 v68, v77, v79, vcc
	v_lshlrev_b32_e32 v68, 2, v68
	v_xor_b32_e32 v79, 8, v77
	v_cmp_lt_i32_e32 vcc, v79, v81
	s_waitcnt lgkmcnt(0)
	v_pk_add_f32 v[130:131], v[130:131], v[132:133]
	ds_bpermute_b32 v133, v68, v131
	ds_bpermute_b32 v132, v68, v130
	v_cndmask_b32_e32 v68, v77, v79, vcc
	v_lshlrev_b32_e32 v68, 2, v68
	v_xor_b32_e32 v79, 4, v77
	v_cmp_lt_i32_e32 vcc, v79, v81
	s_waitcnt lgkmcnt(0)
	v_pk_add_f32 v[130:131], v[130:131], v[132:133]
	ds_bpermute_b32 v133, v68, v131
	ds_bpermute_b32 v132, v68, v130
	v_cndmask_b32_e32 v68, v77, v79, vcc
	v_lshlrev_b32_e32 v68, 2, v68
	v_xor_b32_e32 v79, 2, v77
	v_cmp_lt_i32_e32 vcc, v79, v81
	s_waitcnt lgkmcnt(0)
	v_pk_add_f32 v[130:131], v[130:131], v[132:133]
	ds_bpermute_b32 v133, v68, v131
	ds_bpermute_b32 v132, v68, v130
	v_cndmask_b32_e32 v68, v77, v79, vcc
	v_lshlrev_b32_e32 v68, 2, v68
	v_xor_b32_e32 v79, 1, v77
	v_cmp_lt_i32_e32 vcc, v79, v81
	s_waitcnt lgkmcnt(0)
	v_pk_add_f32 v[134:135], v[130:131], v[132:133]
	ds_bpermute_b32 v137, v68, v135
	ds_bpermute_b32 v136, v68, v134
	v_cndmask_b32_e32 v68, v77, v79, vcc
	v_lshlrev_b32_e32 v68, 2, v68
	ds_read_b128 v[130:133], v73 offset:8192
	v_lshl_add_u64 v[154:155], v[128:129], 0, v[126:127]
	s_waitcnt lgkmcnt(1)
	v_pk_add_f32 v[138:139], v[134:135], v[136:137]
	ds_bpermute_b32 v141, v68, v139
	ds_bpermute_b32 v140, v68, v138
	ds_read_b128 v[134:137], v73 offset:9216
	s_waitcnt lgkmcnt(3)
	v_pk_add_f32 v[142:143], v[130:131], 1.0 op_sel_hi:[1,0]
	v_pk_add_f32 v[150:151], v[132:133], 1.0 op_sel_hi:[1,0]
	s_waitcnt lgkmcnt(1)
	v_pk_add_f32 v[130:131], v[138:139], v[140:141]
	s_nop 0
	v_pk_fma_f32 v[152:153], v[130:131], s[8:9], v[124:125] op_sel_hi:[1,0,0]
	ds_read_b128 v[130:133], v73
	ds_read_b128 v[138:141], v73 offset:1024
	v_mul_f32_e32 v68, 0x4b800000, v153
	v_cmp_gt_f32_e32 vcc, s1, v153
	s_waitcnt lgkmcnt(2)
	v_pk_add_f32 v[156:157], v[134:135], 1.0 op_sel_hi:[1,0]
	v_pk_add_f32 v[158:159], v[136:137], 1.0 op_sel_hi:[1,0]
	v_cndmask_b32_e32 v68, v153, v68, vcc
	v_rsq_f32_e32 v68, v68
	s_nop 0
	v_mul_f32_e32 v79, 0x45800000, v68
	v_cndmask_b32_e32 v68, v68, v79, vcc
	v_pk_mul_f32 v[0:1], v[0:1], v[68:69] op_sel_hi:[1,0]
	v_pk_mul_f32 v[2:3], v[2:3], v[68:69] op_sel_hi:[1,0]
	v_pk_mul_f32 v[0:1], v[64:65], v[0:1]
	v_pk_mul_f32 v[2:3], v[66:67], v[2:3]
	s_waitcnt lgkmcnt(1)
	v_pk_fma_f32 v[0:1], v[142:143], v[0:1], v[130:131]
	v_pk_fma_f32 v[2:3], v[150:151], v[2:3], v[132:133]
	v_cvt_pk_bf16_f32 v0, v0, v1
	v_cvt_pk_bf16_f32 v1, v2, v3
	global_store_dwordx2 v[154:155], v[0:1], off
	v_pk_mul_f32 v[60:61], v[60:61], v[68:69] op_sel_hi:[1,0]
	v_pk_mul_f32 v[62:63], v[62:63], v[68:69] op_sel_hi:[1,0]
	v_pk_mul_f32 v[56:57], v[56:57], v[68:69] op_sel_hi:[1,0]
	v_pk_mul_f32 v[58:59], v[58:59], v[68:69] op_sel_hi:[1,0]
	v_pk_mul_f32 v[52:53], v[52:53], v[68:69] op_sel_hi:[1,0]
	v_pk_mul_f32 v[54:55], v[54:55], v[68:69] op_sel_hi:[1,0]
	v_pk_mul_f32 v[48:49], v[48:49], v[68:69] op_sel_hi:[1,0]
	v_pk_mul_f32 v[50:51], v[50:51], v[68:69] op_sel_hi:[1,0]
	v_pk_mul_f32 v[40:41], v[40:41], v[68:69] op_sel_hi:[1,0]
	v_pk_mul_f32 v[42:43], v[42:43], v[68:69] op_sel_hi:[1,0]
	v_pk_mul_f32 v[36:37], v[36:37], v[68:69] op_sel_hi:[1,0]
	v_pk_mul_f32 v[38:39], v[38:39], v[68:69] op_sel_hi:[1,0]
	v_pk_mul_f32 v[28:29], v[28:29], v[68:69] op_sel_hi:[1,0]
	v_pk_mul_f32 v[30:31], v[30:31], v[68:69] op_sel_hi:[1,0]
	v_cmp_gt_f32_e32 vcc, s1, v152
	v_lshlrev_b32_e32 v68, 1, v72
	v_pk_mul_f32 v[0:1], v[184:185], v[60:61]
	v_pk_mul_f32 v[2:3], v[186:187], v[62:63]
	s_waitcnt lgkmcnt(0)
	v_pk_fma_f32 v[0:1], v[156:157], v[0:1], v[138:139]
	v_pk_fma_f32 v[2:3], v[158:159], v[2:3], v[140:141]
	v_cvt_pk_bf16_f32 v0, v0, v1
	v_cvt_pk_bf16_f32 v1, v2, v3
	global_store_dwordx2 v[154:155], v[0:1], off offset:512
	ds_read_b128 v[60:63], v73 offset:10240
	ds_read_b128 v[64:67], v73 offset:11264
	ds_read_b128 v[134:137], v73 offset:2048
	ds_read_b128 v[146:149], v73 offset:3072
	s_waitcnt lgkmcnt(3)
	v_pk_add_f32 v[160:161], v[60:61], 1.0 op_sel_hi:[1,0]
	v_pk_add_f32 v[162:163], v[62:63], 1.0 op_sel_hi:[1,0]
	s_waitcnt lgkmcnt(2)
	v_pk_add_f32 v[164:165], v[64:65], 1.0 op_sel_hi:[1,0]
	v_pk_add_f32 v[166:167], v[66:67], 1.0 op_sel_hi:[1,0]
	v_pk_mul_f32 v[0:1], v[56:57], v[188:189]
	v_pk_mul_f32 v[2:3], v[58:59], v[190:191]
	s_waitcnt lgkmcnt(1)
	v_pk_fma_f32 v[0:1], v[0:1], v[160:161], v[134:135]
	v_pk_fma_f32 v[2:3], v[2:3], v[162:163], v[136:137]
	v_cvt_pk_bf16_f32 v0, v0, v1
	v_cvt_pk_bf16_f32 v1, v2, v3
	global_store_dwordx2 v[154:155], v[0:1], off offset:1024
	v_pk_mul_f32 v[0:1], v[52:53], v[192:193]
	v_pk_mul_f32 v[2:3], v[54:55], v[194:195]
	s_waitcnt lgkmcnt(0)
	v_pk_fma_f32 v[0:1], v[0:1], v[164:165], v[146:147]
	v_pk_fma_f32 v[2:3], v[2:3], v[166:167], v[148:149]
	v_cvt_pk_bf16_f32 v0, v0, v1
	v_cvt_pk_bf16_f32 v1, v2, v3
	global_store_dwordx2 v[154:155], v[0:1], off offset:1536
	ds_read_b128 v[52:55], v73 offset:12288
	ds_read_b128 v[56:59], v73 offset:13312
	ds_read_b128 v[60:63], v73 offset:4096
	ds_read_b128 v[64:67], v73 offset:5120
	s_waitcnt lgkmcnt(3)
	v_pk_add_f32 v[168:169], v[52:53], 1.0 op_sel_hi:[1,0]
	v_pk_add_f32 v[170:171], v[54:55], 1.0 op_sel_hi:[1,0]
	s_waitcnt lgkmcnt(2)
	v_pk_add_f32 v[172:173], v[56:57], 1.0 op_sel_hi:[1,0]
	v_pk_add_f32 v[174:175], v[58:59], 1.0 op_sel_hi:[1,0]
	v_pk_mul_f32 v[0:1], v[48:49], v[196:197]
	v_pk_mul_f32 v[2:3], v[50:51], v[198:199]
	s_waitcnt lgkmcnt(1)
	v_pk_fma_f32 v[0:1], v[0:1], v[168:169], v[60:61]
	v_pk_fma_f32 v[2:3], v[2:3], v[170:171], v[62:63]
	v_cvt_pk_bf16_f32 v0, v0, v1
	v_cvt_pk_bf16_f32 v1, v2, v3
	global_store_dwordx2 v[154:155], v[0:1], off offset:2048
	v_pk_mul_f32 v[0:1], v[40:41], v[200:201]
	v_pk_mul_f32 v[2:3], v[42:43], v[202:203]
	s_waitcnt lgkmcnt(0)
	v_pk_fma_f32 v[0:1], v[0:1], v[172:173], v[64:65]
	v_pk_fma_f32 v[2:3], v[2:3], v[174:175], v[66:67]
	v_cvt_pk_bf16_f32 v0, v0, v1
	v_cvt_pk_bf16_f32 v1, v2, v3
	global_store_dwordx2 v[154:155], v[0:1], off offset:2560
	ds_read_b128 v[40:43], v73 offset:14336
	ds_read_b128 v[48:51], v73 offset:15360
	ds_read_b128 v[52:55], v73 offset:6144
	ds_read_b128 v[56:59], v73 offset:7168
	s_waitcnt lgkmcnt(3)
	v_pk_add_f32 v[40:41], v[40:41], 1.0 op_sel_hi:[1,0]
	v_pk_add_f32 v[42:43], v[42:43], 1.0 op_sel_hi:[1,0]
	v_pk_mul_f32 v[0:1], v[36:37], v[204:205]
	v_pk_mul_f32 v[2:3], v[38:39], v[206:207]
	s_waitcnt lgkmcnt(1)
	v_pk_fma_f32 v[0:1], v[0:1], v[40:41], v[52:53]
	v_pk_fma_f32 v[2:3], v[2:3], v[42:43], v[54:55]
	v_cvt_pk_bf16_f32 v0, v0, v1
	v_cvt_pk_bf16_f32 v1, v2, v3
	global_store_dwordx2 v[154:155], v[0:1], off offset:3072
	v_pk_add_f32 v[36:37], v[48:49], 1.0 op_sel_hi:[1,0]
	v_pk_add_f32 v[38:39], v[50:51], 1.0 op_sel_hi:[1,0]
	v_pk_mul_f32 v[0:1], v[28:29], v[208:209]
	v_pk_mul_f32 v[2:3], v[30:31], v[210:211]
	s_waitcnt lgkmcnt(0)
	v_pk_fma_f32 v[0:1], v[0:1], v[36:37], v[56:57]
	v_pk_fma_f32 v[2:3], v[2:3], v[38:39], v[58:59]
	v_cvt_pk_bf16_f32 v0, v0, v1
	v_cvt_pk_bf16_f32 v1, v2, v3
	global_store_dwordx2 v[154:155], v[0:1], off offset:3584
	v_mul_f32_e32 v28, 0x4b800000, v152
	v_cndmask_b32_e32 v28, v152, v28, vcc
	v_rsq_f32_e32 v48, v28
	v_lshl_add_u64 v[28:29], v[128:129], 0, s[12:13]
	v_lshl_add_u64 v[30:31], v[28:29], 0, v[126:127]
	v_mul_f32_e32 v49, 0x45800000, v48
	v_cndmask_b32_e32 v48, v48, v49, vcc
	v_pk_mul_f32 v[24:25], v[24:25], v[48:49] op_sel_hi:[1,0]
	v_pk_mul_f32 v[26:27], v[26:27], v[48:49] op_sel_hi:[1,0]
	v_pk_mul_f32 v[20:21], v[20:21], v[48:49] op_sel_hi:[1,0]
	v_pk_mul_f32 v[22:23], v[22:23], v[48:49] op_sel_hi:[1,0]
	v_pk_mul_f32 v[16:17], v[16:17], v[48:49] op_sel_hi:[1,0]
	v_pk_mul_f32 v[18:19], v[18:19], v[48:49] op_sel_hi:[1,0]
	v_pk_mul_f32 v[12:13], v[12:13], v[48:49] op_sel_hi:[1,0]
	v_pk_mul_f32 v[14:15], v[14:15], v[48:49] op_sel_hi:[1,0]
	v_pk_mul_f32 v[8:9], v[8:9], v[48:49] op_sel_hi:[1,0]
	v_pk_mul_f32 v[10:11], v[10:11], v[48:49] op_sel_hi:[1,0]
	v_pk_mul_f32 v[4:5], v[4:5], v[48:49] op_sel_hi:[1,0]
	v_pk_mul_f32 v[6:7], v[6:7], v[48:49] op_sel_hi:[1,0]
	v_pk_mul_f32 v[0:1], v[180:181], v[24:25]
	v_pk_mul_f32 v[2:3], v[182:183], v[26:27]
	v_pk_fma_f32 v[0:1], v[142:143], v[0:1], v[130:131]
	v_pk_fma_f32 v[2:3], v[150:151], v[2:3], v[132:133]
	v_cvt_pk_bf16_f32 v0, v0, v1
	v_cvt_pk_bf16_f32 v1, v2, v3
	global_store_dwordx2 v[30:31], v[0:1], off
	v_lshl_add_u64 v[24:25], v[28:29], 0, v[68:69]
	v_lshlrev_b32_e32 v68, 1, v74
	v_pk_mul_f32 v[0:1], v[184:185], v[20:21]
	v_pk_mul_f32 v[2:3], v[186:187], v[22:23]
	v_pk_fma_f32 v[0:1], v[156:157], v[0:1], v[138:139]
	v_pk_fma_f32 v[2:3], v[158:159], v[2:3], v[140:141]
	v_cvt_pk_bf16_f32 v0, v0, v1
	v_cvt_pk_bf16_f32 v1, v2, v3
	global_store_dwordx2 v[24:25], v[0:1], off
	v_lshl_add_u64 v[20:21], v[28:29], 0, v[68:69]
	v_lshlrev_b32_e32 v68, 1, v76
	v_pk_mul_f32 v[0:1], v[188:189], v[16:17]
	v_pk_mul_f32 v[2:3], v[190:191], v[18:19]
	v_pk_fma_f32 v[0:1], v[160:161], v[0:1], v[134:135]
	v_pk_fma_f32 v[2:3], v[162:163], v[2:3], v[136:137]
	v_cvt_pk_bf16_f32 v0, v0, v1
	v_cvt_pk_bf16_f32 v1, v2, v3
	global_store_dwordx2 v[20:21], v[0:1], off
	v_lshl_add_u64 v[16:17], v[28:29], 0, v[68:69]
	v_lshlrev_b32_e32 v68, 1, v78
	v_pk_mul_f32 v[0:1], v[192:193], v[12:13]
	v_pk_mul_f32 v[2:3], v[194:195], v[14:15]
	v_pk_fma_f32 v[0:1], v[164:165], v[0:1], v[146:147]
	v_pk_fma_f32 v[2:3], v[166:167], v[2:3], v[148:149]
	v_cvt_pk_bf16_f32 v0, v0, v1
	v_cvt_pk_bf16_f32 v1, v2, v3
	global_store_dwordx2 v[16:17], v[0:1], off
	v_lshl_add_u64 v[12:13], v[28:29], 0, v[68:69]
	v_lshlrev_b32_e32 v68, 1, v80
	v_pk_mul_f32 v[0:1], v[8:9], v[196:197]
	v_pk_mul_f32 v[2:3], v[10:11], v[198:199]
	v_pk_fma_f32 v[0:1], v[168:169], v[0:1], v[60:61]
	v_pk_fma_f32 v[2:3], v[170:171], v[2:3], v[62:63]
	v_cvt_pk_bf16_f32 v0, v0, v1
	v_cvt_pk_bf16_f32 v1, v2, v3
	global_store_dwordx2 v[12:13], v[0:1], off
	v_lshl_add_u64 v[8:9], v[28:29], 0, v[68:69]
	v_lshlrev_b32_e32 v68, 1, v82
	v_pk_mul_f32 v[0:1], v[4:5], v[200:201]
	v_pk_mul_f32 v[2:3], v[6:7], v[202:203]
	v_pk_fma_f32 v[0:1], v[172:173], v[0:1], v[64:65]
	v_pk_fma_f32 v[2:3], v[174:175], v[2:3], v[66:67]
	v_cvt_pk_bf16_f32 v0, v0, v1
	v_cvt_pk_bf16_f32 v1, v2, v3
	global_store_dwordx2 v[8:9], v[0:1], off
	v_pk_mul_f32 v[6:7], v[44:45], v[48:49] op_sel_hi:[1,0]
	v_pk_mul_f32 v[8:9], v[46:47], v[48:49] op_sel_hi:[1,0]
	v_lshl_add_u64 v[4:5], v[28:29], 0, v[68:69]
	v_lshlrev_b32_e32 v68, 1, v84
	v_pk_mul_f32 v[0:1], v[6:7], v[204:205]
	v_pk_mul_f32 v[2:3], v[8:9], v[206:207]
	v_pk_fma_f32 v[0:1], v[40:41], v[0:1], v[52:53]
	v_pk_fma_f32 v[2:3], v[42:43], v[2:3], v[54:55]
	v_cvt_pk_bf16_f32 v0, v0, v1
	v_cvt_pk_bf16_f32 v1, v2, v3
	global_store_dwordx2 v[4:5], v[0:1], off
	v_pk_mul_f32 v[6:7], v[32:33], v[48:49] op_sel_hi:[1,0]
	v_pk_mul_f32 v[8:9], v[34:35], v[48:49] op_sel_hi:[1,0]
	v_lshl_add_u64 v[4:5], v[28:29], 0, v[68:69]
	v_pk_mul_f32 v[0:1], v[6:7], v[208:209]
	v_pk_mul_f32 v[2:3], v[8:9], v[210:211]
	v_pk_fma_f32 v[0:1], v[36:37], v[0:1], v[56:57]
	v_pk_fma_f32 v[2:3], v[38:39], v[2:3], v[58:59]
	v_cvt_pk_bf16_f32 v0, v0, v1
	v_cvt_pk_bf16_f32 v1, v2, v3
	global_store_dwordx2 v[4:5], v[0:1], off
	s_branch .LBB0_152

.LBB0_333:
	s_andn2_b64 vcc, exec, s[0:1]
	v_ashrrev_i32_e32 v155, 4, v148
	s_cbranch_vccnz .LBB0_335
	v_cvt_pk_bf16_f32 v124, v124, v125
	v_cvt_pk_bf16_f32 v125, v126, v127
	v_cvt_pk_bf16_f32 v126, v120, v121
	v_mad_i64_i32 v[120:121], s[0:1], v155, s77, v[146:147]
	v_lshlrev_b64 v[120:121], 5, v[120:121]
	v_cvt_pk_bf16_f32 v127, v122, v123
	v_lshl_add_u64 v[120:121], v[136:137], 0, v[120:121]
	global_store_dwordx4 v[120:121], v[124:127], off sc0 sc1

.LBB0_366:
	v_cvt_pk_bf16_f32 v116, v116, v117
	v_cvt_pk_bf16_f32 v117, v118, v119
	v_cvt_pk_bf16_f32 v118, v112, v113
	v_mad_i64_i32 v[112:113], s[28:29], v120, s77, v[146:147]
	v_lshlrev_b64 v[112:113], 5, v[112:113]
	v_cvt_pk_bf16_f32 v119, v114, v115
	v_lshl_add_u64 v[112:113], v[136:137], 0, v[112:113]
	global_store_dwordx4 v[112:113], v[116:119], off sc0 sc1
	s_and_b64 vcc, exec, s[0:1]
	s_mov_b64 s[28:29], -1
	s_cbranch_vccz .LBB0_338

.LBB0_368:
	v_cvt_pk_bf16_f32 v108, v108, v109
	v_cvt_pk_bf16_f32 v109, v110, v111
	v_cvt_pk_bf16_f32 v110, v104, v105
	v_mad_i64_i32 v[104:105], s[28:29], v155, s77, v[112:113]
	v_lshlrev_b64 v[104:105], 5, v[104:105]
	v_cvt_pk_bf16_f32 v111, v106, v107
	v_lshl_add_u64 v[104:105], v[136:137], 0, v[104:105]
	global_store_dwordx4 v[104:105], v[108:111], off sc0 sc1
	s_and_b64 vcc, exec, s[0:1]
	s_mov_b64 s[28:29], -1
	s_cbranch_vccz .LBB0_340

.LBB0_370:
	v_cvt_pk_bf16_f32 v100, v100, v101
	v_cvt_pk_bf16_f32 v101, v102, v103
	v_cvt_pk_bf16_f32 v102, v96, v97
	v_mad_i64_i32 v[96:97], s[28:29], v120, s77, v[112:113]
	v_lshlrev_b64 v[96:97], 5, v[96:97]
	v_cvt_pk_bf16_f32 v103, v98, v99
	v_lshl_add_u64 v[96:97], v[136:137], 0, v[96:97]
	global_store_dwordx4 v[96:97], v[100:103], off sc0 sc1
	s_and_b64 vcc, exec, s[0:1]
	s_mov_b64 s[28:29], -1
	s_cbranch_vccz .LBB0_342

.LBB0_372:
	v_cvt_pk_bf16_f32 v92, v92, v93
	v_cvt_pk_bf16_f32 v93, v94, v95
	v_cvt_pk_bf16_f32 v94, v88, v89
	v_mad_i64_i32 v[88:89], s[28:29], v155, s77, v[96:97]
	v_lshlrev_b64 v[88:89], 5, v[88:89]
	v_cvt_pk_bf16_f32 v95, v90, v91
	v_lshl_add_u64 v[88:89], v[136:137], 0, v[88:89]
	global_store_dwordx4 v[88:89], v[92:95], off sc0 sc1
	s_and_b64 vcc, exec, s[0:1]
	s_mov_b64 s[28:29], -1
	s_cbranch_vccz .LBB0_344

.LBB0_374:
	v_cvt_pk_bf16_f32 v84, v84, v85
	v_cvt_pk_bf16_f32 v85, v86, v87
	v_cvt_pk_bf16_f32 v86, v80, v81
	v_mad_i64_i32 v[80:81], s[28:29], v120, s77, v[96:97]
	v_lshlrev_b64 v[80:81], 5, v[80:81]
	v_cvt_pk_bf16_f32 v87, v82, v83
	v_lshl_add_u64 v[80:81], v[136:137], 0, v[80:81]
	global_store_dwordx4 v[80:81], v[84:87], off sc0 sc1
	s_and_b64 vcc, exec, s[0:1]
	s_mov_b64 s[28:29], -1
	s_cbranch_vccz .LBB0_346

.LBB0_376:
	v_cvt_pk_bf16_f32 v76, v76, v77
	v_cvt_pk_bf16_f32 v77, v78, v79
	v_cvt_pk_bf16_f32 v78, v72, v73
	v_mad_i64_i32 v[72:73], s[28:29], v155, s77, v[80:81]
	v_lshlrev_b64 v[72:73], 5, v[72:73]
	v_cvt_pk_bf16_f32 v79, v74, v75
	v_lshl_add_u64 v[72:73], v[136:137], 0, v[72:73]
	global_store_dwordx4 v[72:73], v[76:79], off sc0 sc1
	s_and_b64 vcc, exec, s[0:1]
	s_mov_b64 s[28:29], -1
	s_cbranch_vccz .LBB0_348

.LBB0_378:
	v_cvt_pk_bf16_f32 v68, v68, v69
	v_cvt_pk_bf16_f32 v69, v70, v71
	v_cvt_pk_bf16_f32 v70, v64, v65
	v_mad_i64_i32 v[64:65], s[28:29], v120, s77, v[80:81]
	v_lshlrev_b64 v[64:65], 5, v[64:65]
	v_cvt_pk_bf16_f32 v71, v66, v67
	v_lshl_add_u64 v[64:65], v[136:137], 0, v[64:65]
	global_store_dwordx4 v[64:65], v[68:71], off sc0 sc1
	s_and_b64 vcc, exec, s[0:1]
	s_mov_b64 s[28:29], -1
	s_cbranch_vccz .LBB0_350

.LBB0_380:
	v_cvt_pk_bf16_f32 v60, v60, v61
	v_cvt_pk_bf16_f32 v61, v62, v63
	v_cvt_pk_bf16_f32 v62, v56, v57
	v_mad_i64_i32 v[56:57], s[28:29], v155, s77, v[64:65]
	v_lshlrev_b64 v[56:57], 5, v[56:57]
	v_cvt_pk_bf16_f32 v63, v58, v59
	v_lshl_add_u64 v[56:57], v[136:137], 0, v[56:57]
	global_store_dwordx4 v[56:57], v[60:63], off sc0 sc1
	s_and_b64 vcc, exec, s[0:1]
	s_mov_b64 s[28:29], -1
	s_cbranch_vccz .LBB0_352

.LBB0_382:
	v_cvt_pk_bf16_f32 v52, v52, v53
	v_cvt_pk_bf16_f32 v53, v54, v55
	v_cvt_pk_bf16_f32 v54, v48, v49
	v_mad_i64_i32 v[48:49], s[28:29], v120, s77, v[64:65]
	v_lshlrev_b64 v[48:49], 5, v[48:49]
	v_cvt_pk_bf16_f32 v55, v50, v51
	v_lshl_add_u64 v[48:49], v[136:137], 0, v[48:49]
	global_store_dwordx4 v[48:49], v[52:55], off sc0 sc1
	s_and_b64 vcc, exec, s[0:1]
	s_mov_b64 s[28:29], -1
	s_cbranch_vccz .LBB0_354

.LBB0_384:
	v_cvt_pk_bf16_f32 v44, v44, v45
	v_cvt_pk_bf16_f32 v45, v46, v47
	v_cvt_pk_bf16_f32 v46, v40, v41
	v_mad_i64_i32 v[40:41], s[28:29], v155, s77, v[48:49]
	v_lshlrev_b64 v[40:41], 5, v[40:41]
	v_cvt_pk_bf16_f32 v47, v42, v43
	v_lshl_add_u64 v[40:41], v[136:137], 0, v[40:41]
	global_store_dwordx4 v[40:41], v[44:47], off sc0 sc1
	s_and_b64 vcc, exec, s[0:1]
	s_mov_b64 s[28:29], -1
	s_cbranch_vccz .LBB0_356

.LBB0_386:
	v_cvt_pk_bf16_f32 v36, v36, v37
	v_cvt_pk_bf16_f32 v37, v38, v39
	v_cvt_pk_bf16_f32 v38, v32, v33
	v_mad_i64_i32 v[32:33], s[28:29], v120, s77, v[48:49]
	v_lshlrev_b64 v[32:33], 5, v[32:33]
	v_cvt_pk_bf16_f32 v39, v34, v35
	v_lshl_add_u64 v[32:33], v[136:137], 0, v[32:33]
	global_store_dwordx4 v[32:33], v[36:39], off sc0 sc1
	s_and_b64 vcc, exec, s[0:1]
	s_mov_b64 s[28:29], -1
	s_cbranch_vccz .LBB0_358

.LBB0_388:
	v_cvt_pk_bf16_f32 v28, v28, v29
	v_cvt_pk_bf16_f32 v29, v30, v31
	v_cvt_pk_bf16_f32 v30, v24, v25
	v_mad_i64_i32 v[24:25], s[28:29], v155, s77, v[32:33]
	v_lshlrev_b64 v[24:25], 5, v[24:25]
	v_cvt_pk_bf16_f32 v31, v26, v27
	v_lshl_add_u64 v[24:25], v[136:137], 0, v[24:25]
	global_store_dwordx4 v[24:25], v[28:31], off sc0 sc1
	s_and_b64 vcc, exec, s[0:1]
	s_mov_b64 s[28:29], -1
	s_cbranch_vccz .LBB0_360

.LBB0_390:
	v_cvt_pk_bf16_f32 v20, v20, v21
	v_cvt_pk_bf16_f32 v21, v22, v23
	v_cvt_pk_bf16_f32 v22, v16, v17
	v_mad_i64_i32 v[16:17], s[28:29], v120, s77, v[32:33]
	v_lshlrev_b64 v[16:17], 5, v[16:17]
	v_cvt_pk_bf16_f32 v23, v18, v19
	v_lshl_add_u64 v[16:17], v[136:137], 0, v[16:17]
	global_store_dwordx4 v[16:17], v[20:23], off sc0 sc1
	s_and_b64 vcc, exec, s[0:1]
	s_mov_b64 s[28:29], -1
	s_cbranch_vccz .LBB0_362

.LBB0_392:
	v_cvt_pk_bf16_f32 v12, v12, v13
	v_cvt_pk_bf16_f32 v13, v14, v15
	v_cvt_pk_bf16_f32 v14, v8, v9
	v_mad_i64_i32 v[8:9], s[28:29], v155, s77, v[16:17]
	v_lshlrev_b64 v[8:9], 5, v[8:9]
	v_cvt_pk_bf16_f32 v15, v10, v11
	v_lshl_add_u64 v[8:9], v[136:137], 0, v[8:9]
	global_store_dwordx4 v[8:9], v[12:15], off sc0 sc1
	s_and_b64 vcc, exec, s[0:1]
	s_mov_b64 s[0:1], -1
	s_cbranch_vccz .LBB0_364

.LBB0_394:
	v_cvt_pk_bf16_f32 v4, v4, v5
	v_cvt_pk_bf16_f32 v5, v6, v7
	v_cvt_pk_bf16_f32 v6, v0, v1
	v_mad_i64_i32 v[0:1], s[0:1], v120, s77, v[16:17]
	v_lshlrev_b64 v[0:1], 5, v[0:1]
	v_cvt_pk_bf16_f32 v7, v2, v3
	v_lshl_add_u64 v[0:1], v[136:137], 0, v[0:1]
	global_store_dwordx4 v[0:1], v[4:7], off sc0 sc1
	s_branch .LBB0_319

.LBB0_938:
	s_cmpk_gt_i32 s3, 0xff
	s_cbranch_scc1 .LBB0_943
	s_waitcnt vmcnt(0)
	v_mbcnt_lo_u32_b32 v1, -1, 0
	v_mbcnt_hi_u32_b32 v1, -1, v1
	v_and_b32_e32 v2, 64, v1
	v_add_u32_e32 v2, 64, v2
	v_xor_b32_e32 v3, 32, v1
	v_cmp_lt_i32_e32 vcc, v3, v2
	v_lshlrev_b32_e32 v0, 3, v144
	v_lshrrev_b32_e32 v7, 6, v144
	v_cndmask_b32_e32 v3, v1, v3, vcc
	v_lshlrev_b32_e32 v8, 2, v3
	v_xor_b32_e32 v3, 16, v1
	v_cmp_lt_i32_e32 vcc, v3, v2
	v_and_b32_e32 v0, 56, v0
	v_mul_u32_u24_e32 v5, 0x804, v0
	v_cndmask_b32_e32 v3, v1, v3, vcc
	v_lshlrev_b32_e32 v9, 2, v3
	v_xor_b32_e32 v3, 8, v1
	v_cmp_lt_i32_e32 vcc, v3, v2
	v_lshlrev_b32_e32 v0, 1, v0
	v_and_b32_e32 v4, 63, v144
	v_cndmask_b32_e32 v3, v1, v3, vcc
	v_lshlrev_b32_e32 v10, 2, v3
	v_xor_b32_e32 v3, 4, v1
	v_cmp_lt_i32_e32 vcc, v3, v2
	s_waitcnt lgkmcnt(0)
	v_readlane_b32 s36, v248, 24
	v_readlane_b32 s46, v248, 34
	v_cndmask_b32_e32 v3, v1, v3, vcc
	v_lshlrev_b32_e32 v11, 2, v3
	v_xor_b32_e32 v3, 2, v1
	v_cmp_lt_i32_e32 vcc, v3, v2
	v_readlane_b32 s47, v248, 35
	v_lshlrev_b32_e32 v15, 3, v7
	v_cndmask_b32_e32 v3, v1, v3, vcc
	v_lshlrev_b32_e32 v12, 2, v3
	v_xor_b32_e32 v3, 1, v1
	v_cmp_lt_i32_e32 vcc, v3, v2
	v_and_b32_e32 v2, 14, v145
	v_lshlrev_b32_e32 v16, 5, v4
	v_cndmask_b32_e32 v1, v1, v3, vcc
	v_lshlrev_b32_e32 v13, 2, v1
	v_mov_b32_e32 v1, 0
	v_lshl_add_u32 v3, v7, 4, 0
	v_add3_u32 v14, v3, v2, v5
	v_lshl_add_u64 v[2:3], s[22:23], 0, v[0:1]
	v_lshlrev_b32_e32 v0, 12, v144
	v_and_b32_e32 v0, 0x38000, v0
	v_lshl_or_b32 v0, v7, 18, v0
	v_lshl_add_u64 v[2:3], v[2:3], 0, v[0:1]
	v_lshlrev_b32_e32 v0, 6, v4
	v_lshlrev_b32_e32 v6, 4, v4
	s_mov_b64 s[6:7], 0x12a00000
	v_lshl_add_u64 v[4:5], s[46:47], 0, v[0:1]
	v_mul_u32_u24_e32 v0, 0x4020, v7
	v_lshl_add_u64 v[2:3], v[2:3], 0, s[6:7]
	v_lshl_add_u32 v15, s3, 6, v15
	s_lshl_b32 s2, s26, 6
	v_add3_u32 v16, v0, v16, 0
	s_mov_b32 s8, 0x800000
	v_mov_b32_e32 v17, 0x358637bd
	v_lshlrev_b32_e32 v0, 1, v6
	s_mov_b64 s[6:7], 0x5e00800
	s_mov_b32 s9, s3
	v_readlane_b32 s37, v248, 25
	v_readlane_b32 s38, v248, 26
	v_readlane_b32 s39, v248, 27
	v_readlane_b32 s40, v248, 28
	v_readlane_b32 s41, v248, 29
	v_readlane_b32 s42, v248, 30
	v_readlane_b32 s43, v248, 31
	v_readlane_b32 s44, v248, 32
	v_readlane_b32 s45, v248, 33
	v_readlane_b32 s48, v248, 36
	v_readlane_b32 s49, v248, 37
	v_readlane_b32 s50, v248, 38
	v_readlane_b32 s51, v248, 39
	global_load_dwordx4 v[180:183], v[4:5], off
	global_load_dwordx4 v[184:187], v[4:5], off offset:16
	global_load_dwordx4 v[188:191], v[4:5], off offset:32
	global_load_dwordx4 v[192:195], v[4:5], off offset:48

.LBB0_941:
	v_add_u32_e32 v40, s10, v16
	ds_read2_b32 v[34:35], v40 offset1:1
	ds_read2_b32 v[36:37], v40 offset0:2 offset1:3
	ds_read2_b32 v[38:39], v40 offset0:4 offset1:5
	ds_read2_b32 v[40:41], v40 offset0:6 offset1:7
	v_ashrrev_i32_e32 v7, 31, v6
	s_waitcnt lgkmcnt(3)
	v_lshlrev_b32_e32 v46, 16, v34
	v_and_b32_e32 v47, 0xffff0000, v34
	v_lshlrev_b32_e32 v34, 16, v35
	v_and_b32_e32 v35, 0xffff0000, v35
	s_waitcnt lgkmcnt(2)
	v_lshlrev_b32_e32 v48, 16, v36
	v_and_b32_e32 v49, 0xffff0000, v36
	v_pk_mul_f32 v[66:67], v[34:35], v[34:35]
	v_pk_mul_f32 v[68:69], v[46:47], v[46:47]
	v_lshlrev_b64 v[42:43], 12, v[6:7]
	v_lshlrev_b32_e32 v36, 16, v37
	v_and_b32_e32 v37, 0xffff0000, v37
	s_waitcnt lgkmcnt(1)
	v_lshlrev_b32_e32 v50, 16, v38
	v_and_b32_e32 v51, 0xffff0000, v38
	v_lshlrev_b32_e32 v38, 16, v39
	v_and_b32_e32 v39, 0xffff0000, v39
	s_waitcnt lgkmcnt(0)
	v_lshlrev_b32_e32 v52, 16, v40
	v_and_b32_e32 v53, 0xffff0000, v40
	v_lshlrev_b32_e32 v40, 16, v41
	v_and_b32_e32 v41, 0xffff0000, v41
	v_pk_mul_f32 v[64:65], v[48:49], v[48:49]
	v_add_f32_e32 v7, v66, v67
	v_add_f32_e32 v66, v68, v69
	v_mov_b32_e32 v56, v53
	v_mov_b32_e32 v57, v41
	v_mov_b32_e32 v60, v51
	v_mov_b32_e32 v61, v39
	v_pk_mul_f32 v[62:63], v[36:37], v[36:37]
	v_add_f32_e32 v64, v64, v65
	v_add_f32_e32 v7, v66, v7
	v_mov_b32_e32 v54, v52
	v_mov_b32_e32 v55, v40
	v_mov_b32_e32 v58, v50
	v_mov_b32_e32 v59, v38
	v_pk_mul_f32 v[56:57], v[56:57], v[56:57]
	v_pk_mul_f32 v[60:61], v[60:61], v[60:61]
	v_add_f32_e32 v62, v62, v63
	v_add_f32_e32 v7, v7, v64
	v_pk_fma_f32 v[54:55], v[54:55], v[54:55], v[56:57]
	v_pk_fma_f32 v[56:57], v[58:59], v[58:59], v[60:61]
	v_add_f32_e32 v7, v7, v62
	v_add_f32_e32 v7, v7, v56
	v_add_f32_e32 v7, v7, v57
	v_add_f32_e32 v7, v7, v54
	v_add_f32_e32 v7, v7, v55
	ds_bpermute_b32 v54, v8, v7
	v_lshl_add_u64 v[42:43], s[22:23], 0, v[42:43]
	v_lshl_add_u64 v[42:43], v[42:43], 0, v[0:1]
	v_lshl_add_u64 v[44:45], v[42:43], 0, s[6:7]
	v_add_co_u32_e32 v42, vcc, 0x5e00000, v42
	s_waitcnt lgkmcnt(0)
	v_add_f32_e32 v7, v7, v54
	ds_bpermute_b32 v54, v9, v7
	v_addc_co_u32_e32 v43, vcc, 0, v43, vcc
	s_addk_i32 s10, 0x804
	v_add_u32_e32 v6, 1, v6
	s_waitcnt lgkmcnt(0)
	v_add_f32_e32 v7, v7, v54
	ds_bpermute_b32 v54, v10, v7
	s_cmpk_eq_i32 s10, 0x4020
	s_waitcnt lgkmcnt(0)
	v_add_f32_e32 v7, v7, v54
	ds_bpermute_b32 v54, v11, v7
	s_waitcnt lgkmcnt(0)
	v_add_f32_e32 v7, v7, v54
	ds_bpermute_b32 v54, v12, v7
	s_waitcnt lgkmcnt(0)
	v_add_f32_e32 v7, v7, v54
	ds_bpermute_b32 v54, v13, v7
	s_waitcnt lgkmcnt(0)
	v_add_f32_e32 v7, v7, v54
	v_fmamk_f32 v7, v7, 0x3a800000, v17
	v_mul_f32_e32 v54, 0x4b800000, v7
	v_cmp_gt_f32_e32 vcc, s8, v7
	s_nop 1
	v_cndmask_b32_e32 v7, v7, v54, vcc
	v_rsq_f32_e32 v7, v7
	s_nop 0
	v_mul_f32_e32 v54, 0x45800000, v7
	v_cndmask_b32_e32 v54, v7, v54, vcc
	v_pk_mul_f32 v[46:47], v[54:55], v[46:47] op_sel_hi:[0,1]
	v_pk_mul_f32 v[34:35], v[54:55], v[34:35] op_sel_hi:[0,1]
	v_pk_mul_f32 v[48:49], v[54:55], v[48:49] op_sel_hi:[0,1]
	v_pk_mul_f32 v[36:37], v[54:55], v[36:37] op_sel_hi:[0,1]
	v_pk_mul_f32 v[50:51], v[54:55], v[50:51] op_sel_hi:[0,1]
	v_pk_mul_f32 v[38:39], v[54:55], v[38:39] op_sel_hi:[0,1]
	v_pk_mul_f32 v[52:53], v[54:55], v[52:53] op_sel_hi:[0,1]
	v_pk_mul_f32 v[40:41], v[54:55], v[40:41] op_sel_hi:[0,1]
	v_pk_mul_f32 v[30:31], v[180:181], v[46:47]
	v_pk_mul_f32 v[32:33], v[182:183], v[34:35]
	v_pk_mul_f32 v[26:27], v[184:185], v[48:49]
	v_pk_mul_f32 v[28:29], v[186:187], v[36:37]
	v_pk_mul_f32 v[22:23], v[188:189], v[50:51]
	v_pk_mul_f32 v[24:25], v[190:191], v[38:39]
	v_pk_mul_f32 v[34:35], v[52:53], v[192:193]
	v_pk_mul_f32 v[36:37], v[40:41], v[194:195]
	v_cvt_pk_bf16_f32 v18, v30, v31
	v_cvt_pk_bf16_f32 v19, v32, v33
	v_cvt_pk_bf16_f32 v20, v26, v27
	v_cvt_pk_bf16_f32 v21, v28, v29
	v_cvt_pk_bf16_f32 v22, v22, v23
	v_cvt_pk_bf16_f32 v23, v24, v25
	v_cvt_pk_bf16_f32 v24, v34, v35
	v_cvt_pk_bf16_f32 v25, v36, v37
	global_store_dwordx4 v[42:43], v[18:21], off offset:2048
	global_store_dwordx4 v[44:45], v[22:25], off offset:16
	s_cbranch_scc0 .LBB0_941
	s_add_i32 s9, s9, s26
	s_cmpk_gt_i32 s9, 0xff
	v_add_u32_e32 v15, s2, v15
	s_barrier
	s_cbranch_scc0 .LBB0_940

.LBB0_997:
	s_cmp_lt_i32 s24, 6
	s_cselect_b64 s[0:1], -1, 0
	s_and_b64 s[6:7], s[0:1], s[6:7]
	s_andn2_b64 vcc, exec, s[6:7]
	v_lshrrev_b32_e32 v145, 4, v144
	s_cbranch_vccnz .LBB0_1002
	s_waitcnt vmcnt(0)
	v_and_b32_e32 v0, 60, v145
	v_lshl_add_u32 v0, s3, 5, v0
	s_movk_i32 s0, 0x4000
	v_cmp_gt_i32_e32 vcc, s0, v0
	s_and_saveexec_b64 s[8:9], vcc
	s_cbranch_execz .LBB0_1001
	v_lshlrev_b32_e32 v1, 4, v144
	v_and_b32_e32 v1, 0x3f0, v1
	s_waitcnt lgkmcnt(0)
	v_readlane_b32 s36, v248, 24
	v_lshlrev_b32_e32 v4, 2, v1
	v_mov_b32_e32 v5, 0
	v_readlane_b32 s44, v248, 32
	v_readlane_b32 s45, v248, 33
	s_mov_b64 s[0:1], 0x5e00000
	s_lshl_b32 s2, s26, 5
	v_lshl_add_u64 v[2:3], s[44:45], 0, v[4:5]
	v_lshlrev_b32_e32 v4, 1, v1
	v_mbcnt_lo_u32_b32 v1, -1, 0
	v_mbcnt_hi_u32_b32 v1, -1, v1
	v_and_b32_e32 v6, 64, v1
	v_add_u32_e32 v6, 64, v6
	v_xor_b32_e32 v7, 32, v1
	v_cmp_lt_i32_e32 vcc, v7, v6
	v_lshl_add_u64 v[4:5], s[22:23], 0, v[4:5]
	v_lshl_add_u64 v[4:5], v[4:5], 0, s[0:1]
	v_cndmask_b32_e32 v7, v1, v7, vcc
	v_lshlrev_b32_e32 v30, 2, v7
	v_xor_b32_e32 v7, 16, v1
	v_cmp_lt_i32_e32 vcc, v7, v6
	s_mov_b32 s0, 0x358637bd
	s_mov_b64 s[10:11], 0
	v_cndmask_b32_e32 v7, v1, v7, vcc
	v_lshlrev_b32_e32 v31, 2, v7
	v_xor_b32_e32 v7, 8, v1
	v_cmp_lt_i32_e32 vcc, v7, v6
	s_mov_b32 s12, 0x3a800000
	s_mov_b32 s13, 0x800000
	v_cndmask_b32_e32 v7, v1, v7, vcc
	v_lshlrev_b32_e32 v32, 2, v7
	v_xor_b32_e32 v7, 4, v1
	v_cmp_lt_i32_e32 vcc, v7, v6
	s_movk_i32 s14, 0x3fff
	v_readlane_b32 s37, v248, 25
	v_cndmask_b32_e32 v7, v1, v7, vcc
	v_lshlrev_b32_e32 v33, 2, v7
	v_xor_b32_e32 v7, 2, v1
	v_cmp_lt_i32_e32 vcc, v7, v6
	v_readlane_b32 s38, v248, 26
	v_readlane_b32 s39, v248, 27
	v_cndmask_b32_e32 v7, v1, v7, vcc
	v_lshlrev_b32_e32 v34, 2, v7
	v_xor_b32_e32 v7, 1, v1
	v_cmp_lt_i32_e32 vcc, v7, v6
	v_readlane_b32 s40, v248, 28
	v_readlane_b32 s41, v248, 29
	v_cndmask_b32_e32 v1, v1, v7, vcc
	v_lshlrev_b32_e32 v35, 2, v1
	v_mov_b64_e32 v[6:7], s[0:1]
	v_readlane_b32 s42, v248, 30
	v_readlane_b32 s43, v248, 31
	v_readlane_b32 s46, v248, 34
	v_readlane_b32 s47, v248, 35
	v_readlane_b32 s48, v248, 36
	v_readlane_b32 s49, v248, 37
	v_readlane_b32 s50, v248, 38
	v_readlane_b32 s51, v248, 39
	global_load_dwordx4 v[180:183], v[2:3], off
	global_load_dwordx4 v[184:187], v[2:3], off offset:16
	global_load_dwordx4 v[188:191], v[2:3], off offset:32
	global_load_dwordx4 v[192:195], v[2:3], off offset:48
.LBB0_1000:
	v_ashrrev_i32_e32 v1, 31, v0
	v_lshlrev_b64 v[8:9], 12, v[0:1]
	v_lshl_add_u64 v[10:11], v[4:5], 0, v[8:9]
	global_load_dwordx4 v[12:15], v[10:11], off offset:16
	global_load_dwordx4 v[16:19], v[10:11], off
	v_add_u32_e32 v8, 1, v0
	v_ashrrev_i32_e32 v9, 31, v8
	v_lshlrev_b64 v[8:9], 12, v[8:9]
	v_lshl_add_u64 v[8:9], v[4:5], 0, v[8:9]
	global_load_dwordx4 v[22:25], v[8:9], off offset:16
	global_load_dwordx4 v[36:39], v[8:9], off
	global_load_dwordx4 v[40:43], v[2:3], off offset:48
	global_load_dwordx4 v[44:47], v[2:3], off offset:32
	global_load_dwordx4 v[48:51], v[2:3], off offset:16
	global_load_dwordx4 v[52:55], v[2:3], off
	s_waitcnt vmcnt(7)
	v_lshlrev_b32_e32 v56, 16, v15
	v_and_b32_e32 v57, 0xffff0000, v15
	v_lshlrev_b32_e32 v58, 16, v14
	v_and_b32_e32 v59, 0xffff0000, v14
	s_waitcnt vmcnt(6)
	v_lshlrev_b32_e32 v64, 16, v19
	v_and_b32_e32 v65, 0xffff0000, v19
	v_lshlrev_b32_e32 v66, 16, v18
	v_and_b32_e32 v67, 0xffff0000, v18
	v_and_b32_e32 v69, 0xffff0000, v17
	s_waitcnt vmcnt(5)
	v_lshlrev_b32_e32 v14, 16, v25
	v_and_b32_e32 v15, 0xffff0000, v25
	v_lshlrev_b32_e32 v18, 16, v23
	v_and_b32_e32 v19, 0xffff0000, v23
	s_waitcnt vmcnt(4)
	v_and_b32_e32 v23, 0xffff0000, v39
	v_and_b32_e32 v25, 0xffff0000, v38
	v_and_b32_e32 v27, 0xffff0000, v37
	v_lshlrev_b32_e32 v68, 16, v17
	v_lshlrev_b32_e32 v70, 16, v16
	v_and_b32_e32 v71, 0xffff0000, v16
	v_lshlrev_b32_e32 v16, 16, v24
	v_and_b32_e32 v17, 0xffff0000, v24
	v_lshlrev_b32_e32 v20, 16, v22
	v_and_b32_e32 v21, 0xffff0000, v22
	v_lshlrev_b32_e32 v22, 16, v39
	v_lshlrev_b32_e32 v24, 16, v38
	v_lshlrev_b32_e32 v26, 16, v37
	v_mov_b32_e32 v39, v65
	v_mov_b32_e32 v81, v67
	v_mov_b32_e32 v85, v69
	v_mov_b32_e32 v38, v23
	v_mov_b32_e32 v80, v25
	v_mov_b32_e32 v84, v27
	v_lshlrev_b32_e32 v28, 16, v36
	v_and_b32_e32 v29, 0xffff0000, v36
	v_mov_b32_e32 v37, v64
	v_mov_b32_e32 v79, v66
	v_mov_b32_e32 v83, v68
	v_mov_b32_e32 v36, v22
	v_mov_b32_e32 v78, v24
	v_mov_b32_e32 v82, v26
	v_pk_mul_f32 v[38:39], v[38:39], v[38:39]
	v_pk_mul_f32 v[80:81], v[80:81], v[80:81]
	v_pk_mul_f32 v[84:85], v[84:85], v[84:85]
	v_and_b32_e32 v61, 0xffff0000, v13
	v_and_b32_e32 v63, 0xffff0000, v12
	v_pk_fma_f32 v[36:37], v[36:37], v[36:37], v[38:39]
	v_pk_fma_f32 v[38:39], v[78:79], v[78:79], v[80:81]
	v_pk_fma_f32 v[78:79], v[82:83], v[82:83], v[84:85]
	v_mov_b32_e32 v82, v29
	v_mov_b32_e32 v83, v71
	v_lshlrev_b32_e32 v60, 16, v13
	v_lshlrev_b32_e32 v62, 16, v12
	v_mov_b32_e32 v72, v57
	v_mov_b32_e32 v73, v59
	v_mov_b32_e32 v76, v61
	v_mov_b32_e32 v77, v63
	v_mov_b32_e32 v80, v28
	v_mov_b32_e32 v81, v70
	v_pk_mul_f32 v[82:83], v[82:83], v[82:83]
	v_mov_b32_e32 v12, v56
	v_mov_b32_e32 v13, v58
	v_mov_b32_e32 v74, v60
	v_mov_b32_e32 v75, v62
	v_pk_mul_f32 v[72:73], v[72:73], v[72:73]
	v_pk_mul_f32 v[76:77], v[76:77], v[76:77]
	v_mov_b32_e32 v92, v19
	v_mov_b32_e32 v93, v21
	v_pk_fma_f32 v[80:81], v[80:81], v[80:81], v[82:83]
	v_mov_b32_e32 v90, v18
	v_mov_b32_e32 v91, v20
	v_pk_fma_f32 v[12:13], v[12:13], v[12:13], v[72:73]
	v_pk_fma_f32 v[72:73], v[74:75], v[74:75], v[76:77]
	v_pk_mul_f32 v[76:77], v[92:93], v[92:93]
	v_pk_add_f32 v[78:79], v[80:81], v[78:79]
	v_mov_b32_e32 v88, v15
	v_mov_b32_e32 v89, v17
	v_pk_fma_f32 v[76:77], v[90:91], v[90:91], v[76:77]
	v_pk_add_f32 v[38:39], v[38:39], v[78:79]
	v_mov_b32_e32 v86, v14
	v_mov_b32_e32 v87, v16
	v_pk_mul_f32 v[74:75], v[88:89], v[88:89]
	v_pk_add_f32 v[36:37], v[36:37], v[38:39]
	v_mov_b32_e32 v38, v77
	v_mov_b32_e32 v39, v73
	v_pk_fma_f32 v[74:75], v[86:87], v[86:87], v[74:75]
	v_pk_add_f32 v[36:37], v[38:39], v[36:37]
	v_mov_b32_e32 v77, v72
	v_pk_add_f32 v[36:37], v[76:77], v[36:37]
	v_mov_b32_e32 v38, v75
	v_mov_b32_e32 v39, v13
	v_pk_add_f32 v[36:37], v[38:39], v[36:37]
	v_mov_b32_e32 v75, v12
	v_pk_add_f32 v[12:13], v[74:75], v[36:37]
	ds_bpermute_b32 v37, v30, v13
	ds_bpermute_b32 v36, v30, v12
	s_waitcnt lgkmcnt(0)
	v_pk_add_f32 v[12:13], v[12:13], v[36:37]
	ds_bpermute_b32 v37, v31, v13
	ds_bpermute_b32 v36, v31, v12
	s_waitcnt lgkmcnt(0)
	v_pk_add_f32 v[12:13], v[12:13], v[36:37]
	ds_bpermute_b32 v37, v32, v13
	ds_bpermute_b32 v36, v32, v12
	s_waitcnt lgkmcnt(0)
	v_pk_add_f32 v[12:13], v[12:13], v[36:37]
	ds_bpermute_b32 v37, v33, v13
	ds_bpermute_b32 v36, v33, v12
	s_waitcnt lgkmcnt(0)
	v_pk_add_f32 v[12:13], v[12:13], v[36:37]
	ds_bpermute_b32 v37, v34, v13
	ds_bpermute_b32 v36, v34, v12
	s_waitcnt lgkmcnt(0)
	v_pk_add_f32 v[36:37], v[12:13], v[36:37]
	ds_bpermute_b32 v39, v35, v37
	ds_bpermute_b32 v38, v35, v36
	v_add_u32_e32 v12, 2, v0
	v_ashrrev_i32_e32 v13, 31, v12
	v_lshlrev_b64 v[12:13], 12, v[12:13]
	v_lshl_add_u64 v[12:13], v[4:5], 0, v[12:13]
	s_waitcnt lgkmcnt(0)
	v_pk_add_f32 v[36:37], v[36:37], v[38:39]
	s_nop 0
	v_pk_fma_f32 v[72:73], v[36:37], s[12:13], v[6:7] op_sel_hi:[1,0,0]
	global_load_dwordx4 v[36:39], v[12:13], off offset:16
	v_mul_f32_e32 v1, 0x4b800000, v73
	v_cmp_gt_f32_e32 vcc, s13, v73
	s_nop 1
	v_cndmask_b32_e32 v1, v73, v1, vcc
	v_rsq_f32_e32 v1, v1
	s_nop 0
	v_mul_f32_e32 v73, 0x45800000, v1
	v_cndmask_b32_e32 v74, v1, v73, vcc
	v_pk_mul_f32 v[70:71], v[74:75], v[70:71] op_sel_hi:[0,1]
	v_pk_mul_f32 v[68:69], v[74:75], v[68:69] op_sel_hi:[0,1]
	s_waitcnt vmcnt(1)
	v_pk_mul_f32 v[52:53], v[52:53], v[70:71]
	v_pk_mul_f32 v[54:55], v[54:55], v[68:69]
	v_cvt_pk_bf16_f32 v52, v52, v53
	v_cvt_pk_bf16_f32 v53, v54, v55
	v_pk_mul_f32 v[54:55], v[74:75], v[66:67] op_sel_hi:[0,1]
	v_pk_mul_f32 v[48:49], v[48:49], v[54:55]
	v_mul_f32_e32 v1, 0x4b800000, v72
	v_cvt_pk_bf16_f32 v54, v48, v49
	v_pk_mul_f32 v[48:49], v[74:75], v[64:65] op_sel_hi:[0,1]
	v_pk_mul_f32 v[48:49], v[50:51], v[48:49]
	v_cmp_gt_f32_e32 vcc, s13, v72
	v_cvt_pk_bf16_f32 v55, v48, v49
	v_pk_mul_f32 v[48:49], v[74:75], v[62:63] op_sel_hi:[0,1]
	v_pk_mul_f32 v[44:45], v[44:45], v[48:49]
	v_pk_mul_f32 v[48:49], v[74:75], v[60:61] op_sel_hi:[0,1]
	v_pk_mul_f32 v[46:47], v[46:47], v[48:49]
	v_cvt_pk_bf16_f32 v44, v44, v45
	v_cvt_pk_bf16_f32 v45, v46, v47
	v_pk_mul_f32 v[46:47], v[74:75], v[58:59] op_sel_hi:[0,1]
	v_pk_mul_f32 v[40:41], v[46:47], v[40:41]
	v_cndmask_b32_e32 v1, v72, v1, vcc
	v_cvt_pk_bf16_f32 v46, v40, v41
	v_pk_mul_f32 v[40:41], v[74:75], v[56:57] op_sel_hi:[0,1]
	v_pk_mul_f32 v[40:41], v[40:41], v[42:43]
	v_rsq_f32_e32 v1, v1
	v_cvt_pk_bf16_f32 v47, v40, v41
	global_store_dwordx4 v[10:11], v[52:55], off
	global_store_dwordx4 v[10:11], v[44:47], off offset:16
	s_nop 0
	global_load_dwordx4 v[56:59], v[12:13], off
	v_add_u32_e32 v10, 3, v0
	v_ashrrev_i32_e32 v11, 31, v10
	v_lshlrev_b64 v[10:11], 12, v[10:11]
	v_lshl_add_u64 v[10:11], v[4:5], 0, v[10:11]
	global_load_dwordx4 v[60:63], v[10:11], off offset:16
	global_load_dwordx4 v[64:67], v[10:11], off
	v_mul_f32_e32 v73, 0x45800000, v1
	v_add_u32_e32 v0, s2, v0
	v_cmp_lt_i32_e64 s[0:1], s14, v0
	s_or_b64 s[10:11], s[0:1], s[10:11]
	s_waitcnt vmcnt(5)
	v_and_b32_e32 v69, 0xffff0000, v39
	v_and_b32_e32 v71, 0xffff0000, v38
	v_lshlrev_b32_e32 v68, 16, v39
	v_lshlrev_b32_e32 v70, 16, v38
	v_mov_b32_e32 v76, v69
	v_mov_b32_e32 v77, v71
	v_lshlrev_b32_e32 v38, 16, v37
	v_and_b32_e32 v39, 0xffff0000, v37
	v_lshlrev_b32_e32 v74, 16, v36
	v_and_b32_e32 v75, 0xffff0000, v36
	v_mov_b32_e32 v36, v68
	v_mov_b32_e32 v37, v70
	v_pk_mul_f32 v[76:77], v[76:77], v[76:77]
	v_mov_b32_e32 v72, v39
	v_pk_fma_f32 v[36:37], v[36:37], v[36:37], v[76:77]
	v_cndmask_b32_e32 v76, v1, v73, vcc
	v_pk_mul_f32 v[28:29], v[76:77], v[28:29] op_sel_hi:[0, 1]
	v_pk_mul_f32 v[26:27], v[76:77], v[26:27] op_sel_hi:[0, 1]
	v_pk_mul_f32 v[24:25], v[76:77], v[24:25] op_sel_hi:[0, 1]
	v_pk_mul_f32 v[22:23], v[76:77], v[22:23] op_sel_hi:[0, 1]
	v_pk_mul_f32 v[20:21], v[76:77], v[20:21] op_sel_hi:[0, 1]
	v_pk_mul_f32 v[18:19], v[76:77], v[18:19] op_sel_hi:[0, 1]
	v_pk_mul_f32 v[16:17], v[76:77], v[16:17] op_sel_hi:[0, 1]
	v_pk_mul_f32 v[14:15], v[76:77], v[14:15] op_sel_hi:[0, 1]
	v_mov_b32_e32 v73, v75
	v_mov_b32_e32 v78, v38
	v_mov_b32_e32 v79, v74
	s_waitcnt vmcnt(5)
	v_pk_mul_f32 v[28:29], v[180:181], v[28:29]
	v_pk_mul_f32 v[26:27], v[182:183], v[26:27]
	s_waitcnt vmcnt(5)
	v_pk_mul_f32 v[24:25], v[184:185], v[24:25]
	v_pk_mul_f32 v[22:23], v[186:187], v[22:23]
	s_waitcnt vmcnt(5)
	v_pk_mul_f32 v[20:21], v[188:189], v[20:21]
	v_pk_mul_f32 v[40:41], v[18:19], v[190:191]
	s_waitcnt vmcnt(5)
	v_pk_mul_f32 v[42:43], v[16:17], v[192:193]
	v_pk_mul_f32 v[44:45], v[14:15], v[194:195]
	v_cvt_pk_bf16_f32 v14, v28, v29
	v_cvt_pk_bf16_f32 v15, v26, v27
	v_cvt_pk_bf16_f32 v16, v24, v25
	v_cvt_pk_bf16_f32 v17, v22, v23
	v_cvt_pk_bf16_f32 v18, v20, v21
	v_cvt_pk_bf16_f32 v19, v40, v41
	v_cvt_pk_bf16_f32 v20, v42, v43
	v_cvt_pk_bf16_f32 v21, v44, v45
	global_store_dwordx4 v[8:9], v[14:17], off
	global_store_dwordx4 v[8:9], v[18:21], off offset:16
	s_nop 0
	s_waitcnt vmcnt(3)
	v_and_b32_e32 v49, 0xffff0000, v63
	v_and_b32_e32 v51, 0xffff0000, v62
	v_lshlrev_b32_e32 v48, 16, v63
	v_lshlrev_b32_e32 v50, 16, v62
	v_mov_b32_e32 v54, v49
	v_mov_b32_e32 v55, v51
	v_mov_b32_e32 v52, v48
	v_mov_b32_e32 v53, v50
	v_pk_mul_f32 v[54:55], v[54:55], v[54:55]
	v_lshlrev_b32_e32 v44, 16, v57
	v_and_b32_e32 v45, 0xffff0000, v57
	v_pk_fma_f32 v[52:53], v[52:53], v[52:53], v[54:55]
	v_and_b32_e32 v55, 0xffff0000, v61
	v_and_b32_e32 v57, 0xffff0000, v60
	v_lshlrev_b32_e32 v46, 16, v56
	v_and_b32_e32 v47, 0xffff0000, v56
	v_lshlrev_b32_e32 v54, 16, v61
	v_lshlrev_b32_e32 v56, 16, v60
	v_mov_b32_e32 v60, v55
	v_mov_b32_e32 v61, v57
	v_lshlrev_b32_e32 v40, 16, v59
	v_and_b32_e32 v41, 0xffff0000, v59
	v_lshlrev_b32_e32 v42, 16, v58
	v_and_b32_e32 v43, 0xffff0000, v58
	v_mov_b32_e32 v58, v54
	v_mov_b32_e32 v59, v56
	v_pk_mul_f32 v[60:61], v[60:61], v[60:61]
	v_pk_mul_f32 v[8:9], v[72:73], v[72:73]
	v_pk_fma_f32 v[58:59], v[58:59], v[58:59], v[60:61]
	s_waitcnt vmcnt(2)
	v_and_b32_e32 v61, 0xffff0000, v67
	v_lshlrev_b32_e32 v60, 16, v67
	v_and_b32_e32 v63, 0xffff0000, v66
	v_mov_b32_e32 v76, v61
	v_mov_b32_e32 v77, v41
	v_pk_fma_f32 v[8:9], v[78:79], v[78:79], v[8:9]
	v_lshlrev_b32_e32 v62, 16, v66
	v_lshlrev_b32_e32 v66, 16, v65
	v_and_b32_e32 v67, 0xffff0000, v65
	v_lshlrev_b32_e32 v72, 16, v64
	v_and_b32_e32 v73, 0xffff0000, v64
	v_mov_b32_e32 v64, v60
	v_mov_b32_e32 v65, v40
	v_pk_mul_f32 v[76:77], v[76:77], v[76:77]
	v_mov_b32_e32 v78, v63
	v_mov_b32_e32 v79, v43
	v_pk_fma_f32 v[64:65], v[64:65], v[64:65], v[76:77]
	v_mov_b32_e32 v76, v62
	v_mov_b32_e32 v77, v42
	v_pk_mul_f32 v[78:79], v[78:79], v[78:79]
	v_mov_b32_e32 v80, v67
	v_mov_b32_e32 v81, v45
	v_pk_fma_f32 v[76:77], v[76:77], v[76:77], v[78:79]
	v_mov_b32_e32 v78, v66
	v_mov_b32_e32 v79, v44
	v_pk_mul_f32 v[80:81], v[80:81], v[80:81]
	v_mov_b32_e32 v82, v73
	v_mov_b32_e32 v83, v47
	v_pk_fma_f32 v[78:79], v[78:79], v[78:79], v[80:81]
	v_mov_b32_e32 v80, v72
	v_mov_b32_e32 v81, v46
	v_pk_mul_f32 v[82:83], v[82:83], v[82:83]
	s_nop 0
	v_pk_fma_f32 v[80:81], v[80:81], v[80:81], v[82:83]
	s_nop 0
	v_pk_add_f32 v[78:79], v[80:81], v[78:79]
	s_nop 0
	v_pk_add_f32 v[76:77], v[76:77], v[78:79]
	s_nop 0
	v_pk_add_f32 v[64:65], v[64:65], v[76:77]
	v_mov_b32_e32 v76, v59
	v_mov_b32_e32 v77, v9
	v_pk_add_f32 v[64:65], v[76:77], v[64:65]
	v_mov_b32_e32 v59, v8
	v_pk_add_f32 v[8:9], v[58:59], v[64:65]
	v_mov_b32_e32 v58, v53
	v_mov_b32_e32 v59, v37
	v_pk_add_f32 v[8:9], v[58:59], v[8:9]
	v_mov_b32_e32 v53, v36
	v_pk_add_f32 v[8:9], v[52:53], v[8:9]
	ds_bpermute_b32 v37, v30, v9
	ds_bpermute_b32 v36, v30, v8
	s_waitcnt lgkmcnt(0)
	v_pk_add_f32 v[8:9], v[8:9], v[36:37]
	ds_bpermute_b32 v37, v31, v9
	ds_bpermute_b32 v36, v31, v8
	s_waitcnt lgkmcnt(0)
	v_pk_add_f32 v[8:9], v[8:9], v[36:37]
	ds_bpermute_b32 v37, v32, v9
	ds_bpermute_b32 v36, v32, v8
	s_waitcnt lgkmcnt(0)
	v_pk_add_f32 v[8:9], v[8:9], v[36:37]
	ds_bpermute_b32 v37, v33, v9
	ds_bpermute_b32 v36, v33, v8
	s_waitcnt lgkmcnt(0)
	v_pk_add_f32 v[8:9], v[8:9], v[36:37]
	ds_bpermute_b32 v37, v34, v9
	ds_bpermute_b32 v36, v34, v8
	s_waitcnt lgkmcnt(0)
	v_pk_add_f32 v[8:9], v[8:9], v[36:37]
	ds_bpermute_b32 v37, v35, v9
	ds_bpermute_b32 v36, v35, v8
	s_waitcnt lgkmcnt(0)
	v_pk_add_f32 v[8:9], v[8:9], v[36:37]
	s_nop 0
	v_pk_fma_f32 v[8:9], v[8:9], s[12:13], v[6:7] op_sel_hi:[1, 0, 0]
	s_nop 0
	v_mul_f32_e32 v1, 0x4b800000, v9
	v_cmp_gt_f32_e32 vcc, s13, v9
	s_nop 1
	v_cndmask_b32_e32 v1, v9, v1, vcc
	v_rsq_f32_e32 v1, v1
	s_nop 0
	v_mul_f32_e32 v9, 0x45800000, v1
	v_cndmask_b32_e32 v36, v1, v9, vcc
	v_pk_mul_f32 v[46:47], v[36:37], v[46:47] op_sel_hi:[0, 1]
	v_pk_mul_f32 v[44:45], v[36:37], v[44:45] op_sel_hi:[0, 1]
	s_waitcnt vmcnt(2)
	v_pk_mul_f32 v[26:27], v[180:181], v[46:47]
	v_pk_mul_f32 v[28:29], v[182:183], v[44:45]
	v_cvt_pk_bf16_f32 v26, v26, v27
	v_cvt_pk_bf16_f32 v27, v28, v29
	v_pk_mul_f32 v[28:29], v[36:37], v[42:43] op_sel_hi:[0, 1]
	v_pk_mul_f32 v[22:23], v[184:185], v[28:29]
	v_mul_f32_e32 v1, 0x4b800000, v8
	v_cvt_pk_bf16_f32 v28, v22, v23
	v_pk_mul_f32 v[22:23], v[36:37], v[40:41] op_sel_hi:[0, 1]
	v_pk_mul_f32 v[22:23], v[186:187], v[22:23]
	v_cmp_gt_f32_e32 vcc, s13, v8
	v_cvt_pk_bf16_f32 v29, v22, v23
	v_pk_mul_f32 v[22:23], v[36:37], v[74:75] op_sel_hi:[0, 1]
	v_pk_mul_f32 v[18:19], v[188:189], v[22:23]
	v_pk_mul_f32 v[22:23], v[36:37], v[38:39] op_sel_hi:[0, 1]
	v_pk_mul_f32 v[20:21], v[22:23], v[190:191]
	v_cvt_pk_bf16_f32 v18, v18, v19
	v_cvt_pk_bf16_f32 v19, v20, v21
	v_pk_mul_f32 v[20:21], v[36:37], v[70:71] op_sel_hi:[0, 1]
	v_pk_mul_f32 v[14:15], v[20:21], v[192:193]
	v_cndmask_b32_e32 v1, v8, v1, vcc
	v_cvt_pk_bf16_f32 v20, v14, v15
	v_pk_mul_f32 v[14:15], v[36:37], v[68:69] op_sel_hi:[0, 1]
	v_pk_mul_f32 v[14:15], v[14:15], v[194:195]
	v_rsq_f32_e32 v1, v1
	v_cvt_pk_bf16_f32 v21, v14, v15
	global_store_dwordx4 v[12:13], v[26:29], off
	global_store_dwordx4 v[12:13], v[18:21], off offset:16
	s_nop 0
	v_mul_f32_e32 v8, 0x45800000, v1
	v_cndmask_b32_e32 v8, v1, v8, vcc
	v_pk_mul_f32 v[28:29], v[8:9], v[72:73] op_sel_hi:[0, 1]
	v_pk_mul_f32 v[36:37], v[8:9], v[66:67] op_sel_hi:[0, 1]
	v_pk_mul_f32 v[38:39], v[8:9], v[62:63] op_sel_hi:[0, 1]
	v_pk_mul_f32 v[40:41], v[8:9], v[60:61] op_sel_hi:[0, 1]
	v_pk_mul_f32 v[42:43], v[8:9], v[56:57] op_sel_hi:[0, 1]
	v_pk_mul_f32 v[44:45], v[8:9], v[54:55] op_sel_hi:[0, 1]
	v_pk_mul_f32 v[46:47], v[8:9], v[50:51] op_sel_hi:[0, 1]
	v_pk_mul_f32 v[8:9], v[8:9], v[48:49] op_sel_hi:[0, 1]
	s_waitcnt vmcnt(4)
	v_pk_mul_f32 v[12:13], v[180:181], v[28:29]
	v_pk_mul_f32 v[14:15], v[182:183], v[36:37]
	s_waitcnt vmcnt(4)
	v_pk_mul_f32 v[16:17], v[184:185], v[38:39]
	v_pk_mul_f32 v[18:19], v[186:187], v[40:41]
	s_waitcnt vmcnt(4)
	v_pk_mul_f32 v[20:21], v[188:189], v[42:43]
	v_pk_mul_f32 v[22:23], v[44:45], v[190:191]
	s_waitcnt vmcnt(4)
	v_pk_mul_f32 v[24:25], v[46:47], v[192:193]
	v_pk_mul_f32 v[8:9], v[8:9], v[194:195]
	v_cvt_pk_bf16_f32 v12, v12, v13
	v_cvt_pk_bf16_f32 v13, v14, v15
	v_cvt_pk_bf16_f32 v14, v16, v17
	v_cvt_pk_bf16_f32 v15, v18, v19
	v_cvt_pk_bf16_f32 v16, v20, v21
	v_cvt_pk_bf16_f32 v17, v22, v23
	v_cvt_pk_bf16_f32 v18, v24, v25
	v_cvt_pk_bf16_f32 v19, v8, v9
	global_store_dwordx4 v[10:11], v[12:15], off
	global_store_dwordx4 v[10:11], v[16:19], off offset:16
	s_andn2_b64 exec, exec, s[10:11]
	s_cbranch_execnz .LBB0_1000

.LBB0_1137:
	v_ashrrev_i32_e32 v13, 31, v12
	v_lshlrev_b64 v[50:51], 12, v[12:13]
	v_lshl_add_u64 v[0:1], v[26:27], 0, v[50:51]
	global_load_dwordx2 v[56:57], v[0:1], off
	global_load_dwordx2 v[58:59], v[0:1], off offset:512
	global_load_dwordx2 v[64:65], v[0:1], off offset:1024
	global_load_dwordx2 v[66:67], v[0:1], off offset:1536
	global_load_dwordx2 v[74:75], v[0:1], off offset:2048
	global_load_dwordx2 v[80:81], v[0:1], off offset:2560
	global_load_dwordx2 v[82:83], v[0:1], off offset:3072
	global_load_dwordx2 v[84:85], v[0:1], off offset:3584
	v_add_u32_e32 v0, 1, v12
	v_ashrrev_i32_e32 v1, 31, v0
	v_lshlrev_b64 v[90:91], 12, v[0:1]
	v_lshl_add_u64 v[4:5], v[26:27], 0, v[90:91]
	global_load_dwordx2 v[86:87], v[4:5], off
	global_load_dwordx2 v[88:89], v[4:5], off offset:512
	global_load_dwordx2 v[92:93], v[4:5], off offset:1024
	global_load_dwordx4 v[0:3], v[16:17], off
	global_load_dwordx2 v[94:95], v[4:5], off offset:1536
	global_load_dwordx2 v[96:97], v[4:5], off offset:2048
	global_load_dwordx2 v[98:99], v[4:5], off offset:2560
	global_load_dwordx2 v[108:109], v[4:5], off offset:3072
	global_load_dwordx2 v[62:63], v[4:5], off offset:3584
	v_ashrrev_i32_e32 v6, 11, v12
	v_mul_hi_i32_i24_e32 v7, 0xc000, v6
	v_mul_i32_i24_e32 v6, 0xc000, v6
	v_lshl_add_u64 v[6:7], s[8:9], 0, v[6:7]
	v_lshl_add_u64 v[76:77], v[6:7], 0, s[12:13]
	v_lshl_add_u64 v[60:61], v[6:7], 0, s[14:15]
	v_lshl_add_u64 v[46:47], v[76:77], 0, v[30:31]
	v_lshl_add_u64 v[48:49], v[60:61], 0, v[30:31]
	global_load_dwordx4 v[4:7], v[46:47], off
	global_load_dwordx4 v[8:11], v[48:49], off
	v_lshl_add_u64 v[156:157], v[28:29], 0, v[50:51]
	s_waitcnt vmcnt(18)
	v_lshlrev_b32_e32 v52, 16, v57
	s_waitcnt vmcnt(17)
	v_lshlrev_b32_e32 v68, 16, v59
	v_and_b32_e32 v69, 0xffff0000, v59
	v_lshlrev_b32_e32 v120, 16, v58
	s_waitcnt vmcnt(14)
	v_and_b32_e32 v79, 0xffff0000, v74
	s_waitcnt vmcnt(13)
	v_and_b32_e32 v149, 0xffff0000, v80
	s_waitcnt vmcnt(12)
	v_and_b32_e32 v143, 0xffff0000, v82
	s_waitcnt vmcnt(11)
	v_and_b32_e32 v129, 0xffff0000, v84
	v_lshlrev_b32_e32 v78, 16, v74
	v_lshlrev_b32_e32 v148, 16, v80
	v_lshlrev_b32_e32 v140, 16, v83
	v_and_b32_e32 v141, 0xffff0000, v83
	v_lshlrev_b32_e32 v142, 16, v82
	v_lshlrev_b32_e32 v128, 16, v84
	v_mov_b32_e32 v82, v79
	v_mov_b32_e32 v83, v149
	v_mov_b32_e32 v104, v143
	v_mov_b32_e32 v105, v129
	v_and_b32_e32 v121, 0xffff0000, v58
	v_lshlrev_b32_e32 v58, 16, v75
	v_and_b32_e32 v59, 0xffff0000, v75
	v_lshlrev_b32_e32 v74, 16, v81
	v_and_b32_e32 v75, 0xffff0000, v81
	v_lshlrev_b32_e32 v124, 16, v85
	v_mov_b32_e32 v80, v78
	v_mov_b32_e32 v81, v148
	v_mov_b32_e32 v102, v142
	v_mov_b32_e32 v103, v128
	v_pk_mul_f32 v[82:83], v[82:83], v[82:83]
	v_pk_mul_f32 v[104:105], v[104:105], v[104:105]
	v_lshlrev_b32_e32 v70, 16, v65
	v_and_b32_e32 v71, 0xffff0000, v65
	v_lshlrev_b32_e32 v116, 16, v64
	v_and_b32_e32 v117, 0xffff0000, v64
	v_and_b32_e32 v125, 0xffff0000, v85
	v_mov_b32_e32 v64, v58
	v_mov_b32_e32 v65, v74
	v_mov_b32_e32 v84, v140
	v_mov_b32_e32 v85, v124
	v_pk_fma_f32 v[80:81], v[80:81], v[80:81], v[82:83]
	v_pk_fma_f32 v[82:83], v[102:103], v[102:103], v[104:105]
	s_waitcnt vmcnt(5)
	v_and_b32_e32 v107, 0xffff0000, v96
	s_waitcnt vmcnt(4)
	v_and_b32_e32 v103, 0xffff0000, v98
	v_and_b32_e32 v53, 0xffff0000, v57
	v_lshlrev_b32_e32 v54, 16, v56
	v_and_b32_e32 v55, 0xffff0000, v56
	v_lshlrev_b32_e32 v56, 16, v67
	v_and_b32_e32 v57, 0xffff0000, v67
	v_lshlrev_b32_e32 v72, 16, v66
	v_and_b32_e32 v73, 0xffff0000, v66
	v_mov_b32_e32 v66, v59
	v_mov_b32_e32 v67, v75
	v_mov_b32_e32 v100, v141
	v_mov_b32_e32 v101, v125
	v_pk_fma_f32 v[64:65], v[64:65], v[64:65], v[80:81]
	v_pk_fma_f32 v[80:81], v[84:85], v[84:85], v[82:83]
	v_lshlrev_b32_e32 v136, 16, v87
	v_and_b32_e32 v137, 0xffff0000, v87
	v_lshlrev_b32_e32 v138, 16, v86
	v_and_b32_e32 v139, 0xffff0000, v86
	v_lshlrev_b32_e32 v106, 16, v96
	v_lshlrev_b32_e32 v102, 16, v98
	v_mov_b32_e32 v86, v107
	v_mov_b32_e32 v87, v103
	v_pk_fma_f32 v[64:65], v[66:67], v[66:67], v[64:65]
	v_pk_fma_f32 v[66:67], v[100:101], v[100:101], v[80:81]
	v_lshlrev_b32_e32 v104, 16, v97
	v_lshlrev_b32_e32 v100, 16, v99
	v_mov_b32_e32 v84, v106
	v_mov_b32_e32 v85, v102
	v_pk_mul_f32 v[86:87], v[86:87], v[86:87]
	v_lshlrev_b32_e32 v132, 16, v89
	v_and_b32_e32 v133, 0xffff0000, v89
	v_lshlrev_b32_e32 v134, 16, v88
	v_and_b32_e32 v135, 0xffff0000, v88
	v_and_b32_e32 v105, 0xffff0000, v97
	v_and_b32_e32 v101, 0xffff0000, v99
	v_mov_b32_e32 v80, v104
	v_mov_b32_e32 v81, v100
	v_pk_fma_f32 v[84:85], v[84:85], v[84:85], v[86:87]
	v_mov_b32_e32 v88, v139
	v_mov_b32_e32 v89, v55
	v_mov_b32_e32 v82, v105
	v_mov_b32_e32 v83, v101
	v_pk_fma_f32 v[80:81], v[80:81], v[80:81], v[84:85]
	v_mov_b32_e32 v86, v138
	v_mov_b32_e32 v87, v54
	v_pk_mul_f32 v[88:89], v[88:89], v[88:89]
	v_lshlrev_b32_e32 v122, 16, v93
	v_and_b32_e32 v123, 0xffff0000, v93
	v_lshlrev_b32_e32 v126, 16, v92
	v_and_b32_e32 v127, 0xffff0000, v92
	v_pk_fma_f32 v[80:81], v[82:83], v[82:83], v[80:81]
	v_mov_b32_e32 v82, v136
	v_mov_b32_e32 v83, v52
	v_pk_fma_f32 v[86:87], v[86:87], v[86:87], v[88:89]
	v_mov_b32_e32 v92, v135
	v_mov_b32_e32 v93, v121
	v_mov_b32_e32 v84, v137
	v_mov_b32_e32 v85, v53
	v_pk_fma_f32 v[82:83], v[82:83], v[82:83], v[86:87]
	v_mov_b32_e32 v88, v134
	v_mov_b32_e32 v89, v120
	v_pk_mul_f32 v[92:93], v[92:93], v[92:93]
	v_pk_fma_f32 v[82:83], v[84:85], v[84:85], v[82:83]
	v_mov_b32_e32 v84, v132
	v_mov_b32_e32 v85, v68
	v_pk_fma_f32 v[88:89], v[88:89], v[88:89], v[92:93]
	v_mov_b32_e32 v86, v133
	v_mov_b32_e32 v87, v69
	v_pk_fma_f32 v[84:85], v[84:85], v[84:85], v[88:89]
	v_mov_b32_e32 v92, v127
	v_mov_b32_e32 v93, v117
	v_pk_fma_f32 v[84:85], v[86:87], v[86:87], v[84:85]
	v_mov_b32_e32 v88, v126
	v_mov_b32_e32 v89, v116
	v_pk_mul_f32 v[92:93], v[92:93], v[92:93]
	v_and_b32_e32 v115, 0xffff0000, v94
	v_pk_add_f32 v[82:83], v[82:83], v[84:85]
	v_mov_b32_e32 v84, v122
	v_mov_b32_e32 v85, v70
	v_pk_fma_f32 v[88:89], v[88:89], v[88:89], v[92:93]
	v_lshlrev_b32_e32 v114, 16, v94
	v_mov_b32_e32 v86, v123
	v_mov_b32_e32 v87, v71
	v_pk_fma_f32 v[84:85], v[84:85], v[84:85], v[88:89]
	v_mov_b32_e32 v92, v115
	v_mov_b32_e32 v93, v73
	v_lshlrev_b32_e32 v110, 16, v95
	v_pk_fma_f32 v[84:85], v[86:87], v[86:87], v[84:85]
	v_mov_b32_e32 v88, v114
	v_mov_b32_e32 v89, v72
	v_pk_mul_f32 v[92:93], v[92:93], v[92:93]
	v_and_b32_e32 v111, 0xffff0000, v95
	v_pk_add_f32 v[82:83], v[82:83], v[84:85]
	v_mov_b32_e32 v84, v110
	v_mov_b32_e32 v85, v56
	v_pk_fma_f32 v[88:89], v[88:89], v[88:89], v[92:93]
	v_mov_b32_e32 v86, v111
	v_mov_b32_e32 v87, v57
	v_pk_fma_f32 v[84:85], v[84:85], v[84:85], v[88:89]
	s_waitcnt vmcnt(3)
	v_and_b32_e32 v89, 0xffff0000, v108
	v_pk_fma_f32 v[84:85], v[86:87], v[86:87], v[84:85]
	v_lshlrev_b32_e32 v88, 16, v108
	v_pk_add_f32 v[82:83], v[82:83], v[84:85]
	v_mov_b32_e32 v84, v80
	v_mov_b32_e32 v85, v64
	v_pk_add_f32 v[92:93], v[82:83], v[84:85]
	s_waitcnt vmcnt(2)
	v_and_b32_e32 v85, 0xffff0000, v62
	v_lshlrev_b32_e32 v84, 16, v62
	v_mov_b32_e32 v98, v89
	v_mov_b32_e32 v99, v85
	v_lshlrev_b32_e32 v86, 16, v109
	v_lshlrev_b32_e32 v82, 16, v63
	v_mov_b32_e32 v96, v88
	v_mov_b32_e32 v97, v84
	v_pk_mul_f32 v[98:99], v[98:99], v[98:99]
	v_and_b32_e32 v87, 0xffff0000, v109
	v_and_b32_e32 v83, 0xffff0000, v63
	v_mov_b32_e32 v62, v86
	v_mov_b32_e32 v63, v82
	v_pk_fma_f32 v[96:97], v[96:97], v[96:97], v[98:99]
	v_mov_b32_e32 v94, v87
	v_mov_b32_e32 v95, v83
	v_pk_fma_f32 v[62:63], v[62:63], v[62:63], v[96:97]
	v_mov_b32_e32 v64, v81
	v_pk_fma_f32 v[62:63], v[94:95], v[94:95], v[62:63]
	v_pk_add_f32 v[64:65], v[92:93], v[64:65]
	v_mov_b32_e32 v80, v62
	v_mov_b32_e32 v81, v66
	v_pk_add_f32 v[64:65], v[64:65], v[80:81]
	v_mov_b32_e32 v66, v63
	v_pk_add_f32 v[62:63], v[64:65], v[66:67]
	ds_bpermute_b32 v65, v176, v63
	ds_bpermute_b32 v64, v176, v62
	v_add_u32_e32 v66, 2, v12
	v_ashrrev_i32_e32 v67, 31, v66
	v_lshlrev_b64 v[80:81], 12, v[66:67]
	s_waitcnt vmcnt(0)
	v_pk_add_f32 v[8:9], v[8:9], 1.0 op_sel_hi:[1,0]
	s_waitcnt lgkmcnt(0)
	v_pk_add_f32 v[62:63], v[62:63], v[64:65]
	ds_bpermute_b32 v65, v177, v63
	ds_bpermute_b32 v64, v177, v62
	v_pk_add_f32 v[10:11], v[10:11], 1.0 op_sel_hi:[1,0]
	v_lshl_add_u64 v[146:147], v[26:27], 0, v[80:81]
	global_load_dwordx2 v[130:131], v[146:147], off
	global_load_dwordx2 v[118:119], v[146:147], off offset:512
	global_load_dwordx2 v[112:113], v[146:147], off offset:1024
	global_load_dwordx2 v[108:109], v[146:147], off offset:1536
	v_lshl_add_u64 v[80:81], v[28:29], 0, v[80:81]
	s_waitcnt lgkmcnt(0)
	v_pk_add_f32 v[62:63], v[62:63], v[64:65]
	ds_bpermute_b32 v65, v178, v63
	ds_bpermute_b32 v64, v178, v62
	s_waitcnt lgkmcnt(0)
	v_pk_add_f32 v[62:63], v[62:63], v[64:65]
	ds_bpermute_b32 v65, v179, v63
	ds_bpermute_b32 v64, v179, v62
	s_waitcnt lgkmcnt(0)
	v_pk_add_f32 v[62:63], v[62:63], v[64:65]
	ds_bpermute_b32 v67, v180, v63
	ds_bpermute_b32 v66, v180, v62
	v_add_u32_e32 v64, 3, v12
	v_ashrrev_i32_e32 v65, 31, v64
	v_lshlrev_b64 v[64:65], 12, v[64:65]
	v_lshl_add_u64 v[152:153], v[26:27], 0, v[64:65]
	s_waitcnt lgkmcnt(0)
	v_pk_add_f32 v[62:63], v[62:63], v[66:67]
	ds_bpermute_b32 v67, v181, v63
	ds_bpermute_b32 v66, v181, v62
	global_load_dwordx2 v[98:99], v[152:153], off
	global_load_dwordx2 v[96:97], v[152:153], off offset:512
	global_load_dwordx2 v[94:95], v[152:153], off offset:1024
	global_load_dwordx2 v[92:93], v[152:153], off offset:1536
	v_add_u32_e32 v12, s2, v12
	s_waitcnt lgkmcnt(0)
	v_pk_add_f32 v[62:63], v[62:63], v[66:67]
	s_nop 0
	v_pk_fma_f32 v[154:155], v[62:63], s[16:17], v[44:45] op_sel_hi:[1,0,0]
	v_lshl_add_u64 v[62:63], v[76:77], 0, v[32:33]
	v_mul_f32_e32 v13, 0x4b800000, v155
	v_cmp_gt_f32_e32 vcc, s17, v155
	v_lshl_add_u64 v[66:67], v[60:61], 0, v[32:33]
	s_waitcnt vmcnt(7)
	v_and_b32_e32 v167, 0xffff0000, v130
	v_cndmask_b32_e32 v13, v155, v13, vcc
	v_rsq_f32_e32 v13, v13
	s_waitcnt vmcnt(6)
	v_lshlrev_b32_e32 v160, 16, v119
	v_and_b32_e32 v161, 0xffff0000, v119
	v_and_b32_e32 v165, 0xffff0000, v118
	v_mul_f32_e32 v50, 0x45800000, v13
	v_cndmask_b32_e32 v158, v13, v50, vcc
	v_pk_mul_f32 v[50:51], v[158:159], v[54:55] op_sel_hi:[0,1]
	v_pk_mul_f32 v[0:1], v[0:1], v[50:51]
	v_pk_mul_f32 v[50:51], v[158:159], v[120:121] op_sel_hi:[0,1]
	v_pk_fma_f32 v[0:1], v[8:9], v[0:1], v[4:5]
	v_pk_mul_f32 v[4:5], v[158:159], v[52:53] op_sel_hi:[0,1]
	v_pk_mul_f32 v[2:3], v[2:3], v[4:5]
	v_cvt_pk_bf16_f32 v226, v0, v1
	v_pk_fma_f32 v[2:3], v[10:11], v[2:3], v[6:7]
	v_lshl_add_u64 v[54:55], v[60:61], 0, v[34:35]
	v_cvt_pk_bf16_f32 v227, v2, v3
	global_load_dwordx4 v[0:3], v[16:17], off offset:1024
	s_nop 0
	global_load_dwordx4 v[4:7], v[66:67], off
	global_load_dwordx4 v[8:11], v[62:63], off
	global_store_dwordx2 v[156:157], v[226:227], off
	v_pk_mul_f32 v[70:71], v[158:159], v[70:71] op_sel_hi:[0,1]
	v_lshl_add_u64 v[52:53], v[60:61], 0, v[36:37]
	v_pk_mul_f32 v[72:73], v[158:159], v[72:73] op_sel_hi:[0,1]
	v_pk_mul_f32 v[56:57], v[158:159], v[56:57] op_sel_hi:[0,1]
	v_pk_mul_f32 v[78:79], v[158:159], v[78:79] op_sel_hi:[0,1]
	v_pk_mul_f32 v[58:59], v[158:159], v[58:59] op_sel_hi:[0,1]
	v_pk_mul_f32 v[148:149], v[158:159], v[148:149] op_sel_hi:[0,1]
	v_pk_mul_f32 v[74:75], v[158:159], v[74:75] op_sel_hi:[0,1]
	v_pk_mul_f32 v[142:143], v[158:159], v[142:143] op_sel_hi:[0,1]
	v_pk_mul_f32 v[140:141], v[158:159], v[140:141] op_sel_hi:[0,1]
	v_pk_mul_f32 v[128:129], v[158:159], v[128:129] op_sel_hi:[0,1]
	v_pk_mul_f32 v[124:125], v[158:159], v[124:125] op_sel_hi:[0,1]
	v_mul_f32_e32 v13, 0x4b800000, v154
	v_cmp_gt_f32_e32 vcc, s17, v154
	s_waitcnt vmcnt(6)
	v_and_b32_e32 v119, 0xffff0000, v96
	v_lshlrev_b32_e32 v166, 16, v130
	v_cndmask_b32_e32 v13, v154, v13, vcc
	v_rsq_f32_e32 v13, v13
	v_lshlrev_b32_e32 v164, 16, v118
	v_lshlrev_b32_e32 v118, 16, v96
	v_mov_b32_e32 v193, v167
	v_mov_b32_e32 v200, v119
	v_mov_b32_e32 v201, v165
	v_lshlrev_b32_e32 v162, 16, v131
	v_and_b32_e32 v155, 0xffff0000, v108
	v_mov_b32_e32 v191, v166
	v_mov_b32_e32 v198, v118
	v_mov_b32_e32 v199, v164
	v_pk_mul_f32 v[200:201], v[200:201], v[200:201]
	v_and_b32_e32 v163, 0xffff0000, v131
	v_lshlrev_b32_e32 v154, 16, v108
	v_mov_b32_e32 v187, v162
	v_mov_b32_e32 v195, v160
	v_mov_b32_e32 v217, v155
	v_mov_b32_e32 v189, v163
	v_mov_b32_e32 v197, v161
	v_mov_b32_e32 v215, v154
	s_waitcnt vmcnt(3)
	v_pk_mul_f32 v[0:1], v[0:1], v[50:51]
	s_waitcnt vmcnt(2)
	v_pk_add_f32 v[4:5], v[4:5], 1.0 op_sel_hi:[1,0]
	v_pk_mul_f32 v[50:51], v[158:159], v[116:117] op_sel_hi:[0,1]
	s_waitcnt vmcnt(1)
	v_pk_fma_f32 v[0:1], v[4:5], v[0:1], v[8:9]
	v_pk_mul_f32 v[4:5], v[158:159], v[68:69] op_sel_hi:[0,1]
	v_pk_mul_f32 v[2:3], v[2:3], v[4:5]
	v_pk_add_f32 v[4:5], v[6:7], 1.0 op_sel_hi:[1,0]
	v_cvt_pk_bf16_f32 v226, v0, v1
	v_pk_fma_f32 v[2:3], v[4:5], v[2:3], v[10:11]
	v_lshl_add_u64 v[68:69], v[76:77], 0, v[34:35]
	v_cvt_pk_bf16_f32 v227, v2, v3
	global_load_dwordx4 v[0:3], v[16:17], off offset:2048
	s_nop 0
	global_load_dwordx4 v[4:7], v[54:55], off
	global_load_dwordx4 v[8:11], v[68:69], off
	global_store_dwordx2 v[156:157], v[226:227], off offset:512
	v_and_b32_e32 v159, 0xffff0000, v112
	v_lshlrev_b32_e32 v158, 16, v112
	v_lshlrev_b32_e32 v112, 16, v94
	v_mov_b32_e32 v209, v159
	v_mov_b32_e32 v206, v112
	v_mov_b32_e32 v207, v158
	s_waitcnt vmcnt(3)
	v_pk_mul_f32 v[0:1], v[0:1], v[50:51]
	s_waitcnt vmcnt(2)
	v_pk_add_f32 v[4:5], v[4:5], 1.0 op_sel_hi:[1,0]
	v_pk_mul_f32 v[2:3], v[2:3], v[70:71]
	v_pk_add_f32 v[6:7], v[6:7], 1.0 op_sel_hi:[1,0]
	s_waitcnt vmcnt(1)
	v_pk_fma_f32 v[0:1], v[0:1], v[4:5], v[8:9]
	v_pk_fma_f32 v[2:3], v[2:3], v[6:7], v[10:11]
	v_cvt_pk_bf16_f32 v226, v0, v1
	v_cvt_pk_bf16_f32 v227, v2, v3
	global_load_dwordx4 v[0:3], v[16:17], off offset:3072
	s_nop 0
	global_load_dwordx4 v[4:7], v[52:53], off
	v_lshl_add_u64 v[70:71], v[76:77], 0, v[36:37]
	global_load_dwordx4 v[8:11], v[70:71], off
	global_store_dwordx2 v[156:157], v[226:227], off offset:1024
	v_lshl_add_u64 v[50:51], v[60:61], 0, v[14:15]
	s_waitcnt vmcnt(3)
	v_pk_mul_f32 v[0:1], v[72:73], v[0:1]
	s_waitcnt vmcnt(2)
	v_pk_add_f32 v[4:5], v[4:5], 1.0 op_sel_hi:[1,0]
	v_pk_mul_f32 v[2:3], v[56:57], v[2:3]
	v_pk_add_f32 v[6:7], v[6:7], 1.0 op_sel_hi:[1,0]
	s_waitcnt vmcnt(1)
	v_pk_fma_f32 v[0:1], v[0:1], v[4:5], v[8:9]
	v_pk_fma_f32 v[2:3], v[2:3], v[6:7], v[10:11]
	v_cvt_pk_bf16_f32 v226, v0, v1
	v_cvt_pk_bf16_f32 v227, v2, v3
	global_load_dwordx4 v[0:3], v[18:19], off
	s_nop 0
	global_load_dwordx4 v[4:7], v[50:51], off
	v_lshl_add_u64 v[72:73], v[76:77], 0, v[14:15]
	global_load_dwordx4 v[8:11], v[72:73], off
	global_load_dwordx2 v[174:175], v[146:147], off offset:2048
	global_load_dwordx2 v[172:173], v[146:147], off offset:2560
	global_load_dwordx2 v[170:171], v[146:147], off offset:3072
	global_load_dwordx2 v[168:169], v[146:147], off offset:3584
	global_load_dwordx2 v[150:151], v[152:153], off offset:2048
	s_nop 0
	global_load_dwordx2 v[146:147], v[152:153], off offset:2560
	global_load_dwordx2 v[120:121], v[152:153], off offset:3072
	global_load_dwordx2 v[116:117], v[152:153], off offset:3584
	global_store_dwordx2 v[156:157], v[226:227], off offset:1536
	v_lshl_add_u64 v[56:57], v[60:61], 0, v[38:39]
	v_lshlrev_b32_e32 v152, 16, v109
	v_and_b32_e32 v153, 0xffff0000, v109
	v_mov_b32_e32 v211, v152
	v_mov_b32_e32 v213, v153
	s_waitcnt vmcnt(5)
	v_lshlrev_b32_e32 v130, 16, v169
	v_pk_mul_f32 v[0:1], v[78:79], v[0:1]
	v_pk_add_f32 v[4:5], v[4:5], 1.0 op_sel_hi:[1,0]
	v_pk_mul_f32 v[2:3], v[58:59], v[2:3]
	v_pk_add_f32 v[6:7], v[6:7], 1.0 op_sel_hi:[1,0]
	v_pk_fma_f32 v[0:1], v[0:1], v[4:5], v[8:9]
	v_pk_fma_f32 v[2:3], v[2:3], v[6:7], v[10:11]
	v_cvt_pk_bf16_f32 v226, v0, v1
	v_cvt_pk_bf16_f32 v227, v2, v3
	global_load_dwordx4 v[0:3], v[20:21], off
	s_nop 0
	global_load_dwordx4 v[4:7], v[56:57], off
	v_lshl_add_u64 v[78:79], v[76:77], 0, v[38:39]
	global_load_dwordx4 v[8:11], v[78:79], off
	global_store_dwordx2 v[156:157], v[226:227], off offset:2048
	v_lshl_add_u64 v[58:59], v[60:61], 0, v[40:41]
	v_lshl_add_u64 v[60:61], v[60:61], 0, v[42:43]
	v_and_b32_e32 v131, 0xffff0000, v169
	s_waitcnt vmcnt(5)
	v_lshlrev_b32_e32 v96, 16, v116
	v_mov_b32_e32 v169, v130
	v_lshlrev_b32_e32 v108, 16, v120
	v_and_b32_e32 v109, 0xffff0000, v120
	v_mov_b32_e32 v224, v109
	v_mov_b32_e32 v222, v108
	v_mov_b32_e32 v223, v96
	s_waitcnt vmcnt(3)
	v_pk_mul_f32 v[0:1], v[148:149], v[0:1]
	s_waitcnt vmcnt(2)
	v_pk_add_f32 v[4:5], v[4:5], 1.0 op_sel_hi:[1,0]
	v_pk_mul_f32 v[2:3], v[74:75], v[2:3]
	v_pk_add_f32 v[6:7], v[6:7], 1.0 op_sel_hi:[1,0]
	s_waitcnt vmcnt(1)
	v_pk_fma_f32 v[0:1], v[0:1], v[4:5], v[8:9]
	v_pk_fma_f32 v[2:3], v[2:3], v[6:7], v[10:11]
	v_cvt_pk_bf16_f32 v226, v0, v1
	v_cvt_pk_bf16_f32 v227, v2, v3
	global_load_dwordx4 v[0:3], v[22:23], off
	s_nop 0
	global_load_dwordx4 v[4:7], v[58:59], off
	v_lshl_add_u64 v[74:75], v[76:77], 0, v[40:41]
	global_load_dwordx4 v[8:11], v[74:75], off
	global_store_dwordx2 v[156:157], v[226:227], off offset:2560
	v_lshl_add_u64 v[76:77], v[76:77], 0, v[42:43]
	v_and_b32_e32 v149, 0xffff0000, v174
	v_lshlrev_b32_e32 v148, 16, v174
	s_waitcnt vmcnt(3)
	v_pk_mul_f32 v[0:1], v[142:143], v[0:1]
	s_waitcnt vmcnt(2)
	v_pk_add_f32 v[4:5], v[4:5], 1.0 op_sel_hi:[1,0]
	v_pk_mul_f32 v[2:3], v[140:141], v[2:3]
	v_pk_add_f32 v[6:7], v[6:7], 1.0 op_sel_hi:[1,0]
	s_waitcnt vmcnt(1)
	v_pk_fma_f32 v[0:1], v[0:1], v[4:5], v[8:9]
	v_pk_fma_f32 v[2:3], v[2:3], v[6:7], v[10:11]
	v_cvt_pk_bf16_f32 v226, v0, v1
	v_cvt_pk_bf16_f32 v227, v2, v3
	global_load_dwordx4 v[0:3], v[24:25], off
	s_nop 0
	global_load_dwordx4 v[4:7], v[60:61], off
	global_load_dwordx4 v[8:11], v[76:77], off
	global_store_dwordx2 v[156:157], v[226:227], off offset:3072
	v_and_b32_e32 v141, 0xffff0000, v172
	v_lshlrev_b32_e32 v140, 16, v172
	v_lshlrev_b32_e32 v142, 16, v175
	v_and_b32_e32 v143, 0xffff0000, v175
	v_mov_b32_e32 v120, v143
	s_waitcnt vmcnt(3)
	v_pk_mul_f32 v[0:1], v[128:129], v[0:1]
	s_waitcnt vmcnt(2)
	v_pk_add_f32 v[4:5], v[4:5], 1.0 op_sel_hi:[1,0]
	v_pk_mul_f32 v[2:3], v[124:125], v[2:3]
	v_pk_add_f32 v[6:7], v[6:7], 1.0 op_sel_hi:[1,0]
	s_waitcnt vmcnt(1)
	v_pk_fma_f32 v[0:1], v[0:1], v[4:5], v[8:9]
	v_pk_fma_f32 v[2:3], v[2:3], v[6:7], v[10:11]
	v_cvt_pk_bf16_f32 v226, v0, v1
	v_cvt_pk_bf16_f32 v227, v2, v3
	global_load_dwordx4 v[0:3], v[48:49], off
	s_nop 0
	global_load_dwordx4 v[4:7], v[16:17], off
	global_load_dwordx4 v[8:11], v[46:47], off
	global_store_dwordx2 v[156:157], v[226:227], off offset:3584
	v_lshl_add_u64 v[124:125], v[28:29], 0, v[90:91]
	v_mul_f32_e32 v90, 0x45800000, v13
	v_cndmask_b32_e32 v128, v13, v90, vcc
	v_pk_mul_f32 v[90:91], v[128:129], v[138:139] op_sel_hi:[0,1]
	v_pk_mul_f32 v[136:137], v[128:129], v[136:137] op_sel_hi:[0,1]
	v_pk_mul_f32 v[132:133], v[128:129], v[132:133] op_sel_hi:[0,1]
	v_pk_mul_f32 v[122:123], v[128:129], v[122:123] op_sel_hi:[0,1]
	v_pk_mul_f32 v[110:111], v[128:129], v[110:111] op_sel_hi:[0,1]
	v_pk_mul_f32 v[104:105], v[128:129], v[104:105] op_sel_hi:[0,1]
	v_pk_mul_f32 v[100:101], v[128:129], v[100:101] op_sel_hi:[0,1]
	v_pk_mul_f32 v[88:89], v[128:129], v[88:89] op_sel_hi:[0,1]
	v_pk_mul_f32 v[86:87], v[128:129], v[86:87] op_sel_hi:[0,1]
	v_pk_mul_f32 v[84:85], v[128:129], v[84:85] op_sel_hi:[0,1]
	v_pk_mul_f32 v[82:83], v[128:129], v[82:83] op_sel_hi:[0,1]
	v_and_b32_e32 v139, 0xffff0000, v170
	v_lshlrev_b32_e32 v156, 16, v113
	v_and_b32_e32 v157, 0xffff0000, v113
	v_lshlrev_b32_e32 v138, 16, v170
	v_and_b32_e32 v113, 0xffff0000, v94
	v_mov_b32_e32 v170, v139
	v_mov_b32_e32 v208, v113
	v_lshlrev_b32_e32 v94, 16, v117
	v_pk_mul_f32 v[208:209], v[208:209], v[208:209]
	v_mov_b32_e32 v203, v156
	v_mov_b32_e32 v205, v157
	v_mov_b32_e32 v219, v94
	s_waitcnt vmcnt(3)
	v_pk_add_f32 v[0:1], v[0:1], 1.0 op_sel_hi:[1,0]
	v_pk_add_f32 v[2:3], v[2:3], 1.0 op_sel_hi:[1,0]
	s_waitcnt vmcnt(2)
	v_pk_mul_f32 v[4:5], v[4:5], v[90:91]
	v_pk_mul_f32 v[6:7], v[6:7], v[136:137]
	s_waitcnt vmcnt(1)
	v_pk_fma_f32 v[0:1], v[0:1], v[4:5], v[8:9]
	v_pk_fma_f32 v[2:3], v[2:3], v[6:7], v[10:11]
	v_cvt_pk_bf16_f32 v226, v0, v1
	v_cvt_pk_bf16_f32 v227, v2, v3
	global_load_dwordx4 v[0:3], v[16:17], off offset:1024
	s_nop 0
	global_load_dwordx4 v[4:7], v[66:67], off
	global_load_dwordx4 v[8:11], v[62:63], off
	global_store_dwordx2 v[124:125], v[226:227], off
	v_pk_mul_f32 v[90:91], v[128:129], v[134:135] op_sel_hi:[0,1]
	v_lshlrev_b32_e32 v134, 16, v171
	v_and_b32_e32 v135, 0xffff0000, v171
	v_lshlrev_b32_e32 v136, 16, v173
	v_and_b32_e32 v137, 0xffff0000, v173
	s_waitcnt vmcnt(3)
	v_pk_mul_f32 v[0:1], v[0:1], v[90:91]
	s_waitcnt vmcnt(2)
	v_pk_add_f32 v[4:5], v[4:5], 1.0 op_sel_hi:[1,0]
	v_pk_mul_f32 v[2:3], v[2:3], v[132:133]
	v_pk_add_f32 v[6:7], v[6:7], 1.0 op_sel_hi:[1,0]
	s_waitcnt vmcnt(1)
	v_pk_fma_f32 v[0:1], v[4:5], v[0:1], v[8:9]
	v_pk_fma_f32 v[2:3], v[6:7], v[2:3], v[10:11]
	v_cvt_pk_bf16_f32 v226, v0, v1
	v_cvt_pk_bf16_f32 v227, v2, v3
	global_load_dwordx4 v[0:3], v[16:17], off offset:2048
	s_nop 0
	global_load_dwordx4 v[4:7], v[54:55], off
	global_load_dwordx4 v[8:11], v[68:69], off
	global_store_dwordx2 v[124:125], v[226:227], off offset:512
	v_pk_mul_f32 v[90:91], v[128:129], v[126:127] op_sel_hi:[0,1]
	v_and_b32_e32 v133, 0xffff0000, v168
	v_and_b32_e32 v127, 0xffff0000, v98
	v_lshlrev_b32_e32 v132, 16, v168
	v_lshlrev_b32_e32 v126, 16, v98
	v_lshlrev_b32_e32 v98, 16, v151
	v_mov_b32_e32 v171, v133
	v_mov_b32_e32 v192, v127
	v_mov_b32_e32 v190, v126
	v_pk_mul_f32 v[170:171], v[170:171], v[170:171]
	v_pk_mul_f32 v[192:193], v[192:193], v[192:193]
	v_mov_b32_e32 v168, v134
	v_mov_b32_e32 v172, v98
	s_waitcnt vmcnt(3)
	v_pk_mul_f32 v[0:1], v[0:1], v[90:91]
	s_waitcnt vmcnt(2)
	v_pk_add_f32 v[4:5], v[4:5], 1.0 op_sel_hi:[1,0]
	v_pk_mul_f32 v[2:3], v[2:3], v[122:123]
	v_pk_add_f32 v[6:7], v[6:7], 1.0 op_sel_hi:[1,0]
	s_waitcnt vmcnt(1)
	v_pk_fma_f32 v[0:1], v[0:1], v[4:5], v[8:9]
	v_pk_fma_f32 v[2:3], v[2:3], v[6:7], v[10:11]
	v_cvt_pk_bf16_f32 v226, v0, v1
	v_cvt_pk_bf16_f32 v227, v2, v3
	global_load_dwordx4 v[0:3], v[16:17], off offset:3072
	s_nop 0
	global_load_dwordx4 v[4:7], v[52:53], off
	global_load_dwordx4 v[8:11], v[70:71], off
	global_store_dwordx2 v[124:125], v[226:227], off offset:1024
	v_pk_mul_f32 v[90:91], v[128:129], v[114:115] op_sel_hi:[0,1]
	v_lshlrev_b32_e32 v122, 16, v99
	v_and_b32_e32 v123, 0xffff0000, v99
	v_and_b32_e32 v99, 0xffff0000, v151
	v_mov_b32_e32 v151, v141
	v_lshlrev_b32_e32 v114, 16, v97
	v_and_b32_e32 v115, 0xffff0000, v97
	v_and_b32_e32 v97, 0xffff0000, v116
	v_mov_b32_e32 v116, v142
	v_mov_b32_e32 v186, v122
	v_mov_b32_e32 v194, v114
	v_mov_b32_e32 v188, v123
	v_mov_b32_e32 v196, v115
	v_mov_b32_e32 v225, v97
	v_mov_b32_e32 v174, v99
	v_pk_mul_f32 v[224:225], v[224:225], v[224:225]
	s_waitcnt vmcnt(3)
	v_pk_mul_f32 v[0:1], v[90:91], v[0:1]
	s_waitcnt vmcnt(2)
	v_pk_add_f32 v[4:5], v[4:5], 1.0 op_sel_hi:[1,0]
	v_pk_mul_f32 v[2:3], v[110:111], v[2:3]
	v_pk_add_f32 v[6:7], v[6:7], 1.0 op_sel_hi:[1,0]
	s_waitcnt vmcnt(1)
	v_pk_fma_f32 v[0:1], v[0:1], v[4:5], v[8:9]
	v_pk_fma_f32 v[2:3], v[2:3], v[6:7], v[10:11]
	v_cvt_pk_bf16_f32 v226, v0, v1
	v_cvt_pk_bf16_f32 v227, v2, v3
	global_load_dwordx4 v[0:3], v[18:19], off
	s_nop 0
	global_load_dwordx4 v[4:7], v[50:51], off
	global_load_dwordx4 v[8:11], v[72:73], off
	global_store_dwordx2 v[124:125], v[226:227], off offset:1536
	v_pk_mul_f32 v[90:91], v[128:129], v[106:107] op_sel_hi:[0,1]
	v_lshlrev_b32_e32 v106, 16, v92
	v_and_b32_e32 v107, 0xffff0000, v92
	v_lshlrev_b32_e32 v92, 16, v146
	v_mov_b32_e32 v183, v92
	v_lshlrev_b32_e32 v110, 16, v95
	v_and_b32_e32 v111, 0xffff0000, v95
	v_and_b32_e32 v95, 0xffff0000, v117
	v_mov_b32_e32 v117, v136
	v_mov_b32_e32 v216, v107
	v_mov_b32_e32 v202, v110
	v_mov_b32_e32 v214, v106
	v_pk_mul_f32 v[216:217], v[216:217], v[216:217]
	v_mov_b32_e32 v204, v111
	v_mov_b32_e32 v221, v95
	s_waitcnt vmcnt(3)
	v_pk_mul_f32 v[0:1], v[90:91], v[0:1]
	s_waitcnt vmcnt(2)
	v_pk_add_f32 v[4:5], v[4:5], 1.0 op_sel_hi:[1,0]
	v_pk_mul_f32 v[2:3], v[104:105], v[2:3]
	v_pk_add_f32 v[6:7], v[6:7], 1.0 op_sel_hi:[1,0]
	s_waitcnt vmcnt(1)
	v_pk_fma_f32 v[0:1], v[0:1], v[4:5], v[8:9]
	v_pk_fma_f32 v[2:3], v[2:3], v[6:7], v[10:11]
	v_cvt_pk_bf16_f32 v226, v0, v1
	v_cvt_pk_bf16_f32 v227, v2, v3
	global_load_dwordx4 v[0:3], v[20:21], off
	s_nop 0
	global_load_dwordx4 v[4:7], v[56:57], off
	global_load_dwordx4 v[8:11], v[78:79], off
	global_store_dwordx2 v[124:125], v[226:227], off offset:2048
	v_pk_mul_f32 v[90:91], v[128:129], v[102:103] op_sel_hi:[0,1]
	v_lshlrev_b32_e32 v102, 16, v93
	v_and_b32_e32 v103, 0xffff0000, v93
	v_and_b32_e32 v93, 0xffff0000, v146
	v_mov_b32_e32 v185, v93
	v_mov_b32_e32 v146, v148
	v_lshlrev_b32_e32 v104, 16, v121
	v_and_b32_e32 v105, 0xffff0000, v121
	v_mov_b32_e32 v121, v137
	v_mov_b32_e32 v210, v102
	v_mov_b32_e32 v212, v103
	v_mov_b32_e32 v218, v104
	v_mov_b32_e32 v220, v105
	s_waitcnt vmcnt(3)
	v_pk_mul_f32 v[0:1], v[90:91], v[0:1]
	s_waitcnt vmcnt(2)
	v_pk_add_f32 v[4:5], v[4:5], 1.0 op_sel_hi:[1,0]
	v_pk_mul_f32 v[2:3], v[100:101], v[2:3]
	v_pk_add_f32 v[6:7], v[6:7], 1.0 op_sel_hi:[1,0]
	s_waitcnt vmcnt(1)
	v_pk_fma_f32 v[0:1], v[0:1], v[4:5], v[8:9]
	v_pk_fma_f32 v[2:3], v[2:3], v[6:7], v[10:11]
	v_cvt_pk_bf16_f32 v226, v0, v1
	v_cvt_pk_bf16_f32 v227, v2, v3
	global_load_dwordx4 v[0:3], v[22:23], off
	s_nop 0
	global_load_dwordx4 v[8:11], v[58:59], off
	global_load_dwordx4 v[4:7], v[74:75], off
	global_store_dwordx2 v[124:125], v[226:227], off offset:2560
	v_and_b32_e32 v101, 0xffff0000, v150
	v_lshlrev_b32_e32 v100, 16, v150
	v_mov_b32_e32 v150, v149
	v_mov_b32_e32 v184, v101
	v_lshlrev_b32_e32 v90, 16, v147
	v_and_b32_e32 v91, 0xffff0000, v147
	v_mov_b32_e32 v147, v140
	v_mov_b32_e32 v182, v100
	v_pk_mul_f32 v[150:151], v[150:151], v[150:151]
	v_pk_mul_f32 v[184:185], v[184:185], v[184:185]
	v_mov_b32_e32 v173, v90
	v_pk_fma_f32 v[146:147], v[146:147], v[146:147], v[150:151]
	v_pk_fma_f32 v[150:151], v[182:183], v[182:183], v[184:185]
	v_pk_fma_f32 v[182:183], v[198:199], v[198:199], v[200:201]
	v_pk_fma_f32 v[184:185], v[206:207], v[206:207], v[208:209]
	v_pk_fma_f32 v[116:117], v[116:117], v[116:117], v[146:147]
	v_pk_fma_f32 v[146:147], v[172:173], v[172:173], v[150:151]
	v_pk_fma_f32 v[116:117], v[120:121], v[120:121], v[116:117]
	v_mov_b32_e32 v175, v91
	s_waitcnt vmcnt(3)
	v_pk_mul_f32 v[0:1], v[88:89], v[0:1]
	s_waitcnt vmcnt(2)
	v_pk_add_f32 v[8:9], v[8:9], 1.0 op_sel_hi:[1,0]
	v_pk_mul_f32 v[2:3], v[86:87], v[2:3]
	v_pk_add_f32 v[10:11], v[10:11], 1.0 op_sel_hi:[1,0]
	s_waitcnt vmcnt(1)
	v_pk_fma_f32 v[0:1], v[0:1], v[8:9], v[4:5]
	v_pk_fma_f32 v[2:3], v[2:3], v[10:11], v[6:7]
	v_cvt_pk_bf16_f32 v226, v0, v1
	v_cvt_pk_bf16_f32 v227, v2, v3
	global_load_dwordx4 v[0:3], v[24:25], off
	s_nop 0
	global_load_dwordx4 v[4:7], v[76:77], off
	global_load_dwordx4 v[8:11], v[60:61], off
	global_store_dwordx2 v[124:125], v[226:227], off offset:3072
	v_mov_b32_e32 v88, v138
	v_mov_b32_e32 v89, v132
	v_pk_fma_f32 v[88:89], v[88:89], v[88:89], v[170:171]
	v_pk_fma_f32 v[170:171], v[190:191], v[190:191], v[192:193]
	v_pk_fma_f32 v[88:89], v[168:169], v[168:169], v[88:89]
	v_pk_fma_f32 v[150:151], v[186:187], v[186:187], v[170:171]
	v_pk_fma_f32 v[168:169], v[194:195], v[194:195], v[182:183]
	v_pk_fma_f32 v[190:191], v[214:215], v[214:215], v[216:217]
	v_pk_fma_f32 v[120:121], v[188:189], v[188:189], v[150:151]
	v_pk_fma_f32 v[128:129], v[196:197], v[196:197], v[168:169]
	v_mov_b32_e32 v86, v135
	v_mov_b32_e32 v87, v131
	v_pk_add_f32 v[120:121], v[120:121], v[128:129]
	v_pk_fma_f32 v[192:193], v[222:223], v[222:223], v[224:225]
	v_pk_fma_f32 v[86:87], v[86:87], v[86:87], v[88:89]
	v_pk_fma_f32 v[88:89], v[174:175], v[174:175], v[146:147]
	v_mov_b32_e32 v129, v116
	v_mov_b32_e32 v128, v88
	v_mov_b32_e32 v116, v89
	v_mov_b32_e32 v89, v86
	s_waitcnt vmcnt(3)
	v_pk_mul_f32 v[0:1], v[84:85], v[0:1]
	v_pk_mul_f32 v[2:3], v[82:83], v[2:3]
	s_waitcnt vmcnt(1)
	v_pk_add_f32 v[8:9], v[8:9], 1.0 op_sel_hi:[1,0]
	v_pk_add_f32 v[10:11], v[10:11], 1.0 op_sel_hi:[1,0]
	v_pk_fma_f32 v[0:1], v[0:1], v[8:9], v[4:5]
	v_pk_fma_f32 v[2:3], v[2:3], v[10:11], v[6:7]
	v_cvt_pk_bf16_f32 v226, v0, v1
	v_cvt_pk_bf16_f32 v227, v2, v3
	global_load_dwordx4 v[0:3], v[46:47], off
	s_nop 0
	global_load_dwordx4 v[4:7], v[48:49], off
	global_load_dwordx4 v[8:11], v[16:17], off
	global_store_dwordx2 v[124:125], v[226:227], off offset:3584
	v_pk_fma_f32 v[82:83], v[202:203], v[202:203], v[184:185]
	v_pk_fma_f32 v[84:85], v[210:211], v[210:211], v[190:191]
	v_pk_fma_f32 v[82:83], v[204:205], v[204:205], v[82:83]
	v_pk_fma_f32 v[84:85], v[212:213], v[212:213], v[84:85]
	v_pk_add_f32 v[82:83], v[120:121], v[82:83]
	v_pk_fma_f32 v[124:125], v[218:219], v[218:219], v[192:193]
	v_pk_add_f32 v[82:83], v[82:83], v[84:85]
	v_pk_fma_f32 v[124:125], v[220:221], v[220:221], v[124:125]
	v_pk_add_f32 v[82:83], v[82:83], v[128:129]
	v_mov_b32_e32 v88, v124
	v_pk_add_f32 v[82:83], v[82:83], v[116:117]
	v_mov_b32_e32 v86, v125
	v_pk_add_f32 v[82:83], v[82:83], v[88:89]
	s_waitcnt vmcnt(2)
	v_pk_add_f32 v[4:5], v[4:5], 1.0 op_sel_hi:[1,0]
	v_pk_add_f32 v[82:83], v[82:83], v[86:87]
	ds_bpermute_b32 v85, v176, v83
	ds_bpermute_b32 v84, v176, v82
	v_pk_add_f32 v[6:7], v[6:7], 1.0 op_sel_hi:[1,0]
	s_waitcnt lgkmcnt(0)
	v_pk_add_f32 v[82:83], v[82:83], v[84:85]
	ds_bpermute_b32 v85, v177, v83
	ds_bpermute_b32 v84, v177, v82
	s_waitcnt lgkmcnt(0)
	v_pk_add_f32 v[82:83], v[82:83], v[84:85]
	ds_bpermute_b32 v85, v178, v83
	ds_bpermute_b32 v84, v178, v82
	s_waitcnt lgkmcnt(0)
	v_pk_add_f32 v[82:83], v[82:83], v[84:85]
	ds_bpermute_b32 v85, v179, v83
	ds_bpermute_b32 v84, v179, v82
	s_waitcnt lgkmcnt(0)
	v_pk_add_f32 v[82:83], v[82:83], v[84:85]
	ds_bpermute_b32 v85, v180, v83
	ds_bpermute_b32 v84, v180, v82
	s_waitcnt lgkmcnt(0)
	v_pk_add_f32 v[82:83], v[82:83], v[84:85]
	ds_bpermute_b32 v85, v181, v83
	ds_bpermute_b32 v84, v181, v82
	s_waitcnt lgkmcnt(0)
	v_pk_add_f32 v[82:83], v[82:83], v[84:85]
	s_nop 0
	v_pk_fma_f32 v[82:83], v[82:83], s[16:17], v[44:45] op_sel_hi:[1,0,0]
	s_nop 0
	v_mul_f32_e32 v13, 0x4b800000, v83
	v_cmp_gt_f32_e32 vcc, s17, v83
	s_nop 1
	v_cndmask_b32_e32 v13, v83, v13, vcc
	v_rsq_f32_e32 v13, v13
	s_nop 0
	v_mul_f32_e32 v83, 0x45800000, v13
	v_cndmask_b32_e32 v84, v13, v83, vcc
	v_pk_mul_f32 v[86:87], v[84:85], v[166:167] op_sel_hi:[0,1]
	v_pk_mul_f32 v[88:89], v[84:85], v[162:163] op_sel_hi:[0,1]
	s_waitcnt vmcnt(1)
	v_pk_mul_f32 v[8:9], v[8:9], v[86:87]
	v_pk_mul_f32 v[10:11], v[10:11], v[88:89]
	v_pk_fma_f32 v[0:1], v[4:5], v[8:9], v[0:1]
	v_pk_fma_f32 v[2:3], v[6:7], v[10:11], v[2:3]
	v_cvt_pk_bf16_f32 v226, v0, v1
	v_cvt_pk_bf16_f32 v227, v2, v3
	global_load_dwordx4 v[0:3], v[16:17], off offset:1024
	s_nop 0
	global_load_dwordx4 v[4:7], v[66:67], off
	global_load_dwordx4 v[8:11], v[62:63], off
	global_store_dwordx2 v[80:81], v[226:227], off
	v_pk_mul_f32 v[86:87], v[84:85], v[164:165] op_sel_hi:[0,1]
	v_pk_mul_f32 v[88:89], v[84:85], v[160:161] op_sel_hi:[0,1]
	v_mul_f32_e32 v13, 0x4b800000, v82
	v_cmp_gt_f32_e32 vcc, s17, v82
	s_waitcnt vmcnt(3)
	v_pk_mul_f32 v[0:1], v[0:1], v[86:87]
	s_waitcnt vmcnt(2)
	v_pk_add_f32 v[4:5], v[4:5], 1.0 op_sel_hi:[1,0]
	v_pk_mul_f32 v[2:3], v[2:3], v[88:89]
	v_pk_add_f32 v[6:7], v[6:7], 1.0 op_sel_hi:[1,0]
	s_waitcnt vmcnt(1)
	v_pk_fma_f32 v[0:1], v[4:5], v[0:1], v[8:9]
	v_pk_fma_f32 v[2:3], v[6:7], v[2:3], v[10:11]
	v_cvt_pk_bf16_f32 v226, v0, v1
	v_cvt_pk_bf16_f32 v227, v2, v3
	global_load_dwordx4 v[0:3], v[16:17], off offset:2048
	s_nop 0
	global_load_dwordx4 v[4:7], v[54:55], off
	global_load_dwordx4 v[8:11], v[68:69], off
	global_store_dwordx2 v[80:81], v[226:227], off offset:512
	v_pk_mul_f32 v[86:87], v[84:85], v[158:159] op_sel_hi:[0,1]
	v_pk_mul_f32 v[88:89], v[84:85], v[156:157] op_sel_hi:[0,1]
	v_cndmask_b32_e32 v13, v82, v13, vcc
	v_rsq_f32_e32 v13, v13
	s_waitcnt vmcnt(3)
	v_pk_mul_f32 v[0:1], v[0:1], v[86:87]
	s_waitcnt vmcnt(2)
	v_pk_add_f32 v[4:5], v[4:5], 1.0 op_sel_hi:[1,0]
	v_pk_mul_f32 v[2:3], v[2:3], v[88:89]
	v_pk_add_f32 v[6:7], v[6:7], 1.0 op_sel_hi:[1,0]
	s_waitcnt vmcnt(1)
	v_pk_fma_f32 v[0:1], v[0:1], v[4:5], v[8:9]
	v_pk_fma_f32 v[2:3], v[2:3], v[6:7], v[10:11]
	v_cvt_pk_bf16_f32 v226, v0, v1
	v_cvt_pk_bf16_f32 v227, v2, v3
	global_load_dwordx4 v[0:3], v[16:17], off offset:3072
	s_nop 0
	global_load_dwordx4 v[4:7], v[52:53], off
	global_load_dwordx4 v[8:11], v[70:71], off
	global_store_dwordx2 v[80:81], v[226:227], off offset:1024
	v_pk_mul_f32 v[86:87], v[84:85], v[154:155] op_sel_hi:[0,1]
	v_pk_mul_f32 v[88:89], v[84:85], v[152:153] op_sel_hi:[0,1]
	s_waitcnt vmcnt(3)
	v_pk_mul_f32 v[0:1], v[86:87], v[0:1]
	s_waitcnt vmcnt(2)
	v_pk_add_f32 v[4:5], v[4:5], 1.0 op_sel_hi:[1,0]
	v_pk_mul_f32 v[2:3], v[88:89], v[2:3]
	v_pk_add_f32 v[6:7], v[6:7], 1.0 op_sel_hi:[1,0]
	s_waitcnt vmcnt(1)
	v_pk_fma_f32 v[0:1], v[0:1], v[4:5], v[8:9]
	v_pk_fma_f32 v[2:3], v[2:3], v[6:7], v[10:11]
	v_cvt_pk_bf16_f32 v226, v0, v1
	v_cvt_pk_bf16_f32 v227, v2, v3
	global_load_dwordx4 v[0:3], v[18:19], off
	s_nop 0
	global_load_dwordx4 v[4:7], v[50:51], off
	global_load_dwordx4 v[8:11], v[72:73], off
	global_store_dwordx2 v[80:81], v[226:227], off offset:1536
	v_pk_mul_f32 v[86:87], v[84:85], v[148:149] op_sel_hi:[0,1]
	v_pk_mul_f32 v[88:89], v[84:85], v[142:143] op_sel_hi:[0,1]
	s_waitcnt vmcnt(3)
	v_pk_mul_f32 v[0:1], v[86:87], v[0:1]
	s_waitcnt vmcnt(2)
	v_pk_add_f32 v[4:5], v[4:5], 1.0 op_sel_hi:[1,0]
	v_pk_mul_f32 v[2:3], v[88:89], v[2:3]
	v_pk_add_f32 v[6:7], v[6:7], 1.0 op_sel_hi:[1,0]
	s_waitcnt vmcnt(1)
	v_pk_fma_f32 v[0:1], v[0:1], v[4:5], v[8:9]
	v_pk_fma_f32 v[2:3], v[2:3], v[6:7], v[10:11]
	v_cvt_pk_bf16_f32 v226, v0, v1
	v_cvt_pk_bf16_f32 v227, v2, v3
	global_load_dwordx4 v[0:3], v[20:21], off
	s_nop 0
	global_load_dwordx4 v[4:7], v[56:57], off
	global_load_dwordx4 v[8:11], v[78:79], off
	global_store_dwordx2 v[80:81], v[226:227], off offset:2048
	v_pk_mul_f32 v[86:87], v[84:85], v[140:141] op_sel_hi:[0,1]
	v_pk_mul_f32 v[88:89], v[84:85], v[136:137] op_sel_hi:[0,1]
	s_waitcnt vmcnt(3)
	v_pk_mul_f32 v[0:1], v[86:87], v[0:1]
	s_waitcnt vmcnt(2)
	v_pk_add_f32 v[4:5], v[4:5], 1.0 op_sel_hi:[1,0]
	v_pk_mul_f32 v[2:3], v[88:89], v[2:3]
	v_pk_add_f32 v[6:7], v[6:7], 1.0 op_sel_hi:[1,0]
	s_waitcnt vmcnt(1)
	v_pk_fma_f32 v[0:1], v[0:1], v[4:5], v[8:9]
	v_pk_fma_f32 v[2:3], v[2:3], v[6:7], v[10:11]
	v_cvt_pk_bf16_f32 v226, v0, v1
	v_cvt_pk_bf16_f32 v227, v2, v3
	global_load_dwordx4 v[0:3], v[22:23], off
	s_nop 0
	global_load_dwordx4 v[4:7], v[58:59], off
	global_load_dwordx4 v[8:11], v[74:75], off
	global_store_dwordx2 v[80:81], v[226:227], off offset:2560
	v_pk_mul_f32 v[86:87], v[84:85], v[138:139] op_sel_hi:[0,1]
	v_pk_mul_f32 v[88:89], v[84:85], v[134:135] op_sel_hi:[0,1]
	s_waitcnt vmcnt(3)
	v_pk_mul_f32 v[0:1], v[86:87], v[0:1]
	s_waitcnt vmcnt(2)
	v_pk_add_f32 v[4:5], v[4:5], 1.0 op_sel_hi:[1,0]
	v_pk_mul_f32 v[2:3], v[88:89], v[2:3]
	v_pk_add_f32 v[6:7], v[6:7], 1.0 op_sel_hi:[1,0]
	s_waitcnt vmcnt(1)
	v_pk_fma_f32 v[0:1], v[0:1], v[4:5], v[8:9]
	v_pk_fma_f32 v[2:3], v[2:3], v[6:7], v[10:11]
	v_cvt_pk_bf16_f32 v226, v0, v1
	v_cvt_pk_bf16_f32 v227, v2, v3
	global_load_dwordx4 v[0:3], v[24:25], off
	s_nop 0
	global_load_dwordx4 v[4:7], v[60:61], off
	global_load_dwordx4 v[8:11], v[76:77], off
	global_store_dwordx2 v[80:81], v[226:227], off offset:3072
	v_pk_mul_f32 v[86:87], v[84:85], v[132:133] op_sel_hi:[0,1]
	v_pk_mul_f32 v[84:85], v[84:85], v[130:131] op_sel_hi:[0,1]
	s_waitcnt vmcnt(3)
	v_pk_mul_f32 v[0:1], v[86:87], v[0:1]
	s_waitcnt vmcnt(2)
	v_pk_add_f32 v[4:5], v[4:5], 1.0 op_sel_hi:[1,0]
	v_pk_mul_f32 v[2:3], v[84:85], v[2:3]
	v_pk_add_f32 v[6:7], v[6:7], 1.0 op_sel_hi:[1,0]
	s_waitcnt vmcnt(1)
	v_pk_fma_f32 v[0:1], v[0:1], v[4:5], v[8:9]
	v_pk_fma_f32 v[2:3], v[2:3], v[6:7], v[10:11]
	v_cvt_pk_bf16_f32 v226, v0, v1
	v_cvt_pk_bf16_f32 v227, v2, v3
	global_load_dwordx4 v[0:3], v[48:49], off
	s_nop 0
	global_load_dwordx4 v[4:7], v[16:17], off
	global_load_dwordx4 v[8:11], v[46:47], off
	global_store_dwordx2 v[80:81], v[226:227], off offset:3584
	v_mul_f32_e32 v48, 0x45800000, v13
	v_cndmask_b32_e32 v48, v13, v48, vcc
	v_lshl_add_u64 v[46:47], v[28:29], 0, v[64:65]
	v_pk_mul_f32 v[64:65], v[48:49], v[126:127] op_sel_hi:[0,1]
	v_pk_mul_f32 v[80:81], v[48:49], v[122:123] op_sel_hi:[0,1]
	v_cmp_lt_i32_e32 vcc, s18, v12
	s_or_b64 s[10:11], vcc, s[10:11]
	s_waitcnt vmcnt(3)
	v_pk_add_f32 v[0:1], v[0:1], 1.0 op_sel_hi:[1,0]
	v_pk_add_f32 v[2:3], v[2:3], 1.0 op_sel_hi:[1,0]
	s_waitcnt vmcnt(2)
	v_pk_mul_f32 v[4:5], v[4:5], v[64:65]
	v_pk_mul_f32 v[6:7], v[6:7], v[80:81]
	s_waitcnt vmcnt(1)
	v_pk_fma_f32 v[0:1], v[0:1], v[4:5], v[8:9]
	v_pk_fma_f32 v[2:3], v[2:3], v[6:7], v[10:11]
	v_cvt_pk_bf16_f32 v226, v0, v1
	v_cvt_pk_bf16_f32 v227, v2, v3
	global_load_dwordx4 v[0:3], v[16:17], off offset:1024
	s_nop 0
	global_load_dwordx4 v[4:7], v[66:67], off
	global_load_dwordx4 v[8:11], v[62:63], off
	global_store_dwordx2 v[46:47], v[226:227], off
	v_pk_mul_f32 v[62:63], v[48:49], v[118:119] op_sel_hi:[0,1]
	v_pk_mul_f32 v[64:65], v[48:49], v[114:115] op_sel_hi:[0,1]
	s_waitcnt vmcnt(3)
	v_pk_mul_f32 v[0:1], v[0:1], v[62:63]
	s_waitcnt vmcnt(2)
	v_pk_add_f32 v[4:5], v[4:5], 1.0 op_sel_hi:[1,0]
	v_pk_mul_f32 v[2:3], v[2:3], v[64:65]
	v_pk_add_f32 v[6:7], v[6:7], 1.0 op_sel_hi:[1,0]
	s_waitcnt vmcnt(1)
	v_pk_fma_f32 v[0:1], v[4:5], v[0:1], v[8:9]
	v_pk_fma_f32 v[2:3], v[6:7], v[2:3], v[10:11]
	v_cvt_pk_bf16_f32 v226, v0, v1
	v_cvt_pk_bf16_f32 v227, v2, v3
	global_load_dwordx4 v[0:3], v[16:17], off offset:2048
	s_nop 0
	global_load_dwordx4 v[4:7], v[54:55], off
	global_load_dwordx4 v[8:11], v[68:69], off
	global_store_dwordx2 v[46:47], v[226:227], off offset:512
	v_pk_mul_f32 v[54:55], v[48:49], v[112:113] op_sel_hi:[0,1]
	v_pk_mul_f32 v[62:63], v[48:49], v[110:111] op_sel_hi:[0,1]
	s_waitcnt vmcnt(3)
	v_pk_mul_f32 v[0:1], v[0:1], v[54:55]
	s_waitcnt vmcnt(2)
	v_pk_add_f32 v[4:5], v[4:5], 1.0 op_sel_hi:[1,0]
	v_pk_mul_f32 v[2:3], v[2:3], v[62:63]
	v_pk_add_f32 v[6:7], v[6:7], 1.0 op_sel_hi:[1,0]
	s_waitcnt vmcnt(1)
	v_pk_fma_f32 v[0:1], v[0:1], v[4:5], v[8:9]
	v_pk_fma_f32 v[2:3], v[2:3], v[6:7], v[10:11]
	v_cvt_pk_bf16_f32 v226, v0, v1
	v_cvt_pk_bf16_f32 v227, v2, v3
	global_load_dwordx4 v[0:3], v[16:17], off offset:3072
	s_nop 0
	global_load_dwordx4 v[4:7], v[52:53], off
	global_load_dwordx4 v[8:11], v[70:71], off
	global_store_dwordx2 v[46:47], v[226:227], off offset:1024
	v_pk_mul_f32 v[52:53], v[48:49], v[106:107] op_sel_hi:[0,1]
	v_pk_mul_f32 v[54:55], v[48:49], v[102:103] op_sel_hi:[0,1]
	s_waitcnt vmcnt(3)
	v_pk_mul_f32 v[0:1], v[52:53], v[0:1]
	s_waitcnt vmcnt(2)
	v_pk_add_f32 v[4:5], v[4:5], 1.0 op_sel_hi:[1,0]
	v_pk_mul_f32 v[2:3], v[54:55], v[2:3]
	v_pk_add_f32 v[6:7], v[6:7], 1.0 op_sel_hi:[1,0]
	s_waitcnt vmcnt(1)
	v_pk_fma_f32 v[0:1], v[0:1], v[4:5], v[8:9]
	v_pk_fma_f32 v[2:3], v[2:3], v[6:7], v[10:11]
	v_cvt_pk_bf16_f32 v226, v0, v1
	v_cvt_pk_bf16_f32 v227, v2, v3
	global_load_dwordx4 v[0:3], v[18:19], off
	s_nop 0
	global_load_dwordx4 v[4:7], v[50:51], off
	global_load_dwordx4 v[8:11], v[72:73], off
	global_store_dwordx2 v[46:47], v[226:227], off offset:1536
	v_pk_mul_f32 v[50:51], v[48:49], v[100:101] op_sel_hi:[0,1]
	v_pk_mul_f32 v[52:53], v[48:49], v[98:99] op_sel_hi:[0,1]
	s_waitcnt vmcnt(3)
	v_pk_mul_f32 v[0:1], v[50:51], v[0:1]
	s_waitcnt vmcnt(2)
	v_pk_add_f32 v[4:5], v[4:5], 1.0 op_sel_hi:[1,0]
	v_pk_mul_f32 v[2:3], v[52:53], v[2:3]
	v_pk_add_f32 v[6:7], v[6:7], 1.0 op_sel_hi:[1,0]
	s_waitcnt vmcnt(1)
	v_pk_fma_f32 v[0:1], v[0:1], v[4:5], v[8:9]
	v_pk_fma_f32 v[2:3], v[2:3], v[6:7], v[10:11]
	v_cvt_pk_bf16_f32 v226, v0, v1
	v_cvt_pk_bf16_f32 v227, v2, v3
	global_load_dwordx4 v[0:3], v[20:21], off
	s_nop 0
	global_load_dwordx4 v[4:7], v[56:57], off
	global_load_dwordx4 v[8:11], v[78:79], off
	global_store_dwordx2 v[46:47], v[226:227], off offset:2048
	v_pk_mul_f32 v[50:51], v[48:49], v[92:93] op_sel_hi:[0,1]
	v_pk_mul_f32 v[52:53], v[48:49], v[90:91] op_sel_hi:[0,1]
	s_waitcnt vmcnt(3)
	v_pk_mul_f32 v[0:1], v[50:51], v[0:1]
	s_waitcnt vmcnt(2)
	v_pk_add_f32 v[4:5], v[4:5], 1.0 op_sel_hi:[1,0]
	v_pk_mul_f32 v[2:3], v[52:53], v[2:3]
	v_pk_add_f32 v[6:7], v[6:7], 1.0 op_sel_hi:[1,0]
	s_waitcnt vmcnt(1)
	v_pk_fma_f32 v[0:1], v[0:1], v[4:5], v[8:9]
	v_pk_fma_f32 v[2:3], v[2:3], v[6:7], v[10:11]
	v_cvt_pk_bf16_f32 v226, v0, v1
	v_cvt_pk_bf16_f32 v227, v2, v3
	global_load_dwordx4 v[0:3], v[22:23], off
	s_nop 0
	global_load_dwordx4 v[4:7], v[58:59], off
	global_load_dwordx4 v[8:11], v[74:75], off
	global_store_dwordx2 v[46:47], v[226:227], off offset:2560
	v_pk_mul_f32 v[50:51], v[48:49], v[108:109] op_sel_hi:[0,1]
	v_pk_mul_f32 v[52:53], v[48:49], v[104:105] op_sel_hi:[0,1]
	s_waitcnt vmcnt(3)
	v_pk_mul_f32 v[0:1], v[50:51], v[0:1]
	s_waitcnt vmcnt(2)
	v_pk_add_f32 v[4:5], v[4:5], 1.0 op_sel_hi:[1,0]
	v_pk_mul_f32 v[2:3], v[52:53], v[2:3]
	v_pk_add_f32 v[6:7], v[6:7], 1.0 op_sel_hi:[1,0]
	s_waitcnt vmcnt(1)
	v_pk_fma_f32 v[0:1], v[0:1], v[4:5], v[8:9]
	v_pk_fma_f32 v[2:3], v[2:3], v[6:7], v[10:11]
	v_cvt_pk_bf16_f32 v226, v0, v1
	v_cvt_pk_bf16_f32 v227, v2, v3
	global_load_dwordx4 v[0:3], v[24:25], off
	s_nop 0
	global_load_dwordx4 v[4:7], v[60:61], off
	global_load_dwordx4 v[8:11], v[76:77], off
	global_store_dwordx2 v[46:47], v[226:227], off offset:3072
	v_pk_mul_f32 v[50:51], v[48:49], v[96:97] op_sel_hi:[0,1]
	v_pk_mul_f32 v[48:49], v[48:49], v[94:95] op_sel_hi:[0,1]
	s_waitcnt vmcnt(3)
	v_pk_mul_f32 v[0:1], v[50:51], v[0:1]
	s_waitcnt vmcnt(2)
	v_pk_add_f32 v[4:5], v[4:5], 1.0 op_sel_hi:[1,0]
	v_pk_mul_f32 v[2:3], v[48:49], v[2:3]
	v_pk_add_f32 v[6:7], v[6:7], 1.0 op_sel_hi:[1,0]
	s_waitcnt vmcnt(1)
	v_pk_fma_f32 v[0:1], v[0:1], v[4:5], v[8:9]
	v_pk_fma_f32 v[2:3], v[2:3], v[6:7], v[10:11]
	v_cvt_pk_bf16_f32 v226, v0, v1
	v_cvt_pk_bf16_f32 v227, v2, v3
	global_store_dwordx2 v[46:47], v[226:227], off offset:3584
	s_andn2_b64 exec, exec, s[10:11]
	s_cbranch_execnz .LBB0_1137

.LBB0_1203:
	ds_read_b128 v[150:153], v147
	ds_read_b128 v[154:157], v147 offset:1024
	ds_read_b128 v[158:161], v147 offset:2048
	ds_read_b128 v[162:165], v147 offset:3072
	s_add_u32 s36, s34, 0xfff80080
	s_addc_u32 s37, s35, -1
	s_cmp_eq_u32 s60, 28
	s_cselect_b32 s39, s13, s37
	s_cselect_b32 s38, s58, s36
	s_cselect_b32 s37, s11, s59
	s_cselect_b32 s36, s28, s29
	v_lshl_add_u64 v[198:199], s[34:35], 0, v[136:137]
	s_add_i32 m0, s31, 0xc000
	ds_read_b128 v[166:169], v148
	ds_read_b128 v[170:173], v148 offset:1024
	ds_read_b128 v[174:177], v148 offset:2048
	ds_read_b128 v[178:181], v148 offset:3072
	ds_read_b128 v[182:185], v148 offset:4096
	ds_read_b128 v[186:189], v148 offset:5120
	ds_read_b128 v[190:193], v148 offset:6144
	ds_read_b128 v[194:197], v148 offset:7168
	global_load_lds_dwordx4 v[198:199], off
	v_lshl_add_u64 v[198:199], s[34:35], 0, v[138:139]
	s_add_i32 m0, s31, 0xe000
	s_nop 0
	global_load_lds_dwordx4 v[198:199], off
	s_waitcnt lgkmcnt(8)
	s_barrier
	s_waitcnt lgkmcnt(0)
	s_setprio 1
	s_waitcnt lgkmcnt(0)
	v_mfma_f32_16x16x32_bf16 v[124:127], v[150:153], v[166:169], v[124:127]
	v_mfma_f32_16x16x32_bf16 v[120:123], v[158:161], v[166:169], v[120:123]
	v_mfma_f32_16x16x32_bf16 v[108:111], v[150:153], v[174:177], v[108:111]
	v_mfma_f32_16x16x32_bf16 v[104:107], v[158:161], v[174:177], v[104:107]
	v_mfma_f32_16x16x32_bf16 v[92:95], v[150:153], v[182:185], v[92:95]
	v_mfma_f32_16x16x32_bf16 v[88:91], v[158:161], v[182:185], v[88:91]
	v_mfma_f32_16x16x32_bf16 v[76:79], v[150:153], v[190:193], v[76:79]
	v_mfma_f32_16x16x32_bf16 v[72:75], v[158:161], v[190:193], v[72:75]
	v_mfma_f32_16x16x32_bf16 v[124:127], v[154:157], v[170:173], v[124:127]
	v_mfma_f32_16x16x32_bf16 v[120:123], v[162:165], v[170:173], v[120:123]
	v_mfma_f32_16x16x32_bf16 v[108:111], v[154:157], v[178:181], v[108:111]
	v_mfma_f32_16x16x32_bf16 v[104:107], v[162:165], v[178:181], v[104:107]
	v_mfma_f32_16x16x32_bf16 v[92:95], v[154:157], v[186:189], v[92:95]
	v_mfma_f32_16x16x32_bf16 v[88:91], v[162:165], v[186:189], v[88:91]
	v_mfma_f32_16x16x32_bf16 v[76:79], v[154:157], v[194:197], v[76:79]
	v_mfma_f32_16x16x32_bf16 v[72:75], v[162:165], v[194:197], v[72:75]
	s_setprio 0
	s_barrier
	s_add_i32 s61, s54, s43
	v_lshl_add_u64 v[214:215], s[36:37], 0, v[132:133]
	s_mov_b32 m0, s61
	ds_read_b128 v[198:201], v149
	ds_read_b128 v[202:205], v149 offset:1024
	ds_read_b128 v[206:209], v149 offset:2048
	ds_read_b128 v[210:213], v149 offset:3072
	global_load_lds_dwordx4 v[214:215], off
	v_lshl_add_u64 v[216:217], s[36:37], 0, v[128:129]
	s_add_i32 m0, s61, 0x2000
	s_nop 0
	global_load_lds_dwordx4 v[216:217], off
	s_barrier
	s_waitcnt lgkmcnt(0)
	s_setprio 1
	s_waitcnt lgkmcnt(0)
	v_mfma_f32_16x16x32_bf16 v[116:119], v[198:201], v[166:169], v[116:119]
	v_mfma_f32_16x16x32_bf16 v[112:115], v[206:209], v[166:169], v[112:115]
	v_mfma_f32_16x16x32_bf16 v[100:103], v[198:201], v[174:177], v[100:103]
	v_mfma_f32_16x16x32_bf16 v[96:99], v[206:209], v[174:177], v[96:99]
	v_mfma_f32_16x16x32_bf16 v[84:87], v[198:201], v[182:185], v[84:87]
	v_mfma_f32_16x16x32_bf16 v[80:83], v[206:209], v[182:185], v[80:83]
	v_mfma_f32_16x16x32_bf16 v[68:71], v[198:201], v[190:193], v[68:71]
	v_mfma_f32_16x16x32_bf16 v[64:67], v[206:209], v[190:193], v[64:67]
	v_mfma_f32_16x16x32_bf16 v[116:119], v[202:205], v[170:173], v[116:119]
	v_mfma_f32_16x16x32_bf16 v[112:115], v[210:213], v[170:173], v[112:115]
	v_mfma_f32_16x16x32_bf16 v[100:103], v[202:205], v[178:181], v[100:103]
	v_mfma_f32_16x16x32_bf16 v[96:99], v[210:213], v[178:181], v[96:99]
	v_mfma_f32_16x16x32_bf16 v[84:87], v[202:205], v[186:189], v[84:87]
	v_mfma_f32_16x16x32_bf16 v[80:83], v[210:213], v[186:189], v[80:83]
	v_mfma_f32_16x16x32_bf16 v[68:71], v[202:205], v[194:197], v[68:71]
	v_mfma_f32_16x16x32_bf16 v[64:67], v[210:213], v[194:197], v[64:67]
	s_setprio 0
	s_mov_b32 m0, s31
	v_lshl_add_u64 v[218:219], s[38:39], 0, v[134:135]
	s_barrier
	ds_read_b128 v[166:169], v148 offset:16384
	ds_read_b128 v[170:173], v148 offset:17408
	ds_read_b128 v[174:177], v148 offset:18432
	ds_read_b128 v[178:181], v148 offset:19456
	ds_read_b128 v[182:185], v148 offset:20480
	ds_read_b128 v[186:189], v148 offset:21504
	ds_read_b128 v[190:193], v148 offset:22528
	ds_read_b128 v[194:197], v148 offset:23552
	global_load_lds_dwordx4 v[218:219], off
	v_lshl_add_u64 v[220:221], s[38:39], 0, v[130:131]
	s_mov_b32 m0, s46
	s_nop 0
	global_load_lds_dwordx4 v[220:221], off
	s_barrier
	s_waitcnt lgkmcnt(0)
	s_setprio 1
	s_waitcnt lgkmcnt(0)
	v_mfma_f32_16x16x32_bf16 v[60:63], v[150:153], v[166:169], v[60:63]
	v_mfma_f32_16x16x32_bf16 v[56:59], v[158:161], v[166:169], v[56:59]
	v_mfma_f32_16x16x32_bf16 v[44:47], v[150:153], v[174:177], v[44:47]
	v_mfma_f32_16x16x32_bf16 v[40:43], v[158:161], v[174:177], v[40:43]
	v_mfma_f32_16x16x32_bf16 v[28:31], v[150:153], v[182:185], v[28:31]
	v_mfma_f32_16x16x32_bf16 v[24:27], v[158:161], v[182:185], v[24:27]
	v_mfma_f32_16x16x32_bf16 v[12:15], v[150:153], v[190:193], v[12:15]
	v_mfma_f32_16x16x32_bf16 v[8:11], v[158:161], v[190:193], v[8:11]
	v_mfma_f32_16x16x32_bf16 v[60:63], v[154:157], v[170:173], v[60:63]
	v_mfma_f32_16x16x32_bf16 v[56:59], v[162:165], v[170:173], v[56:59]
	v_mfma_f32_16x16x32_bf16 v[44:47], v[154:157], v[178:181], v[44:47]
	v_mfma_f32_16x16x32_bf16 v[40:43], v[162:165], v[178:181], v[40:43]
	v_mfma_f32_16x16x32_bf16 v[28:31], v[154:157], v[186:189], v[28:31]
	v_mfma_f32_16x16x32_bf16 v[24:27], v[162:165], v[186:189], v[24:27]
	v_mfma_f32_16x16x32_bf16 v[12:15], v[154:157], v[194:197], v[12:15]
	v_mfma_f32_16x16x32_bf16 v[8:11], v[162:165], v[194:197], v[8:11]
	s_setprio 0
	s_barrier
	s_add_u32 s62, s36, 0x80000
	s_addc_u32 s63, s37, 0
	s_add_i32 s61, s55, s43
	v_lshl_add_u64 v[150:151], s[62:63], 0, v[132:133]
	s_mov_b32 m0, s61
	s_nop 0
	global_load_lds_dwordx4 v[150:151], off
	v_lshl_add_u64 v[150:151], s[62:63], 0, v[128:129]
	s_add_i32 m0, s61, 0x2000
	s_nop 0
	global_load_lds_dwordx4 v[150:151], off
	s_waitcnt vmcnt(6)
	s_barrier
	s_setprio 1
	v_mfma_f32_16x16x32_bf16 v[52:55], v[198:201], v[166:169], v[52:55]
	v_mfma_f32_16x16x32_bf16 v[48:51], v[206:209], v[166:169], v[48:51]
	v_mfma_f32_16x16x32_bf16 v[36:39], v[198:201], v[174:177], v[36:39]
	v_mfma_f32_16x16x32_bf16 v[32:35], v[206:209], v[174:177], v[32:35]
	v_mfma_f32_16x16x32_bf16 v[20:23], v[198:201], v[182:185], v[20:23]
	v_mfma_f32_16x16x32_bf16 v[16:19], v[206:209], v[182:185], v[16:19]
	v_mfma_f32_16x16x32_bf16 v[4:7], v[198:201], v[190:193], v[4:7]
	v_mfma_f32_16x16x32_bf16 v[0:3], v[206:209], v[190:193], v[0:3]
	v_mfma_f32_16x16x32_bf16 v[52:55], v[202:205], v[170:173], v[52:55]
	v_mfma_f32_16x16x32_bf16 v[48:51], v[210:213], v[170:173], v[48:51]
	v_mfma_f32_16x16x32_bf16 v[36:39], v[202:205], v[178:181], v[36:39]
	v_mfma_f32_16x16x32_bf16 v[32:35], v[210:213], v[178:181], v[32:35]
	v_mfma_f32_16x16x32_bf16 v[20:23], v[202:205], v[186:189], v[20:23]
	v_mfma_f32_16x16x32_bf16 v[16:19], v[210:213], v[186:189], v[16:19]
	v_mfma_f32_16x16x32_bf16 v[4:7], v[202:205], v[194:197], v[4:7]
	v_mfma_f32_16x16x32_bf16 v[0:3], v[210:213], v[194:197], v[0:3]
	s_setprio 0
	s_add_i32 s61, 0, 0x18000
	v_add_u32_e32 v162, s61, v143
	s_barrier
	ds_read_b128 v[150:153], v162
	ds_read_b128 v[154:157], v162 offset:1024
	ds_read_b128 v[158:161], v162 offset:2048
	ds_read_b128 v[162:165], v162 offset:3072
	s_add_u32 s38, s38, 0x80000
	s_addc_u32 s39, s39, 0
	s_mov_b32 m0, s47
	v_lshl_add_u64 v[198:199], s[38:39], 0, v[134:135]
	ds_read_b128 v[166:169], v148 offset:32768
	ds_read_b128 v[170:173], v148 offset:33792
	ds_read_b128 v[174:177], v148 offset:34816
	ds_read_b128 v[178:181], v148 offset:35840
	ds_read_b128 v[182:185], v148 offset:36864
	ds_read_b128 v[186:189], v148 offset:37888
	ds_read_b128 v[190:193], v148 offset:38912
	ds_read_b128 v[194:197], v148 offset:39936
	global_load_lds_dwordx4 v[198:199], off
	v_lshl_add_u64 v[198:199], s[38:39], 0, v[130:131]
	s_mov_b32 m0, s48
	s_nop 0
	global_load_lds_dwordx4 v[198:199], off
	s_waitcnt lgkmcnt(8)
	s_barrier
	s_waitcnt lgkmcnt(0)
	s_setprio 1
	s_waitcnt lgkmcnt(0)
	v_mfma_f32_16x16x32_bf16 v[124:127], v[150:153], v[166:169], v[124:127]
	v_mfma_f32_16x16x32_bf16 v[120:123], v[158:161], v[166:169], v[120:123]
	v_mfma_f32_16x16x32_bf16 v[108:111], v[150:153], v[174:177], v[108:111]
	v_mfma_f32_16x16x32_bf16 v[104:107], v[158:161], v[174:177], v[104:107]
	v_mfma_f32_16x16x32_bf16 v[92:95], v[150:153], v[182:185], v[92:95]
	v_mfma_f32_16x16x32_bf16 v[88:91], v[158:161], v[182:185], v[88:91]
	v_mfma_f32_16x16x32_bf16 v[76:79], v[150:153], v[190:193], v[76:79]
	v_mfma_f32_16x16x32_bf16 v[72:75], v[158:161], v[190:193], v[72:75]
	v_mfma_f32_16x16x32_bf16 v[124:127], v[154:157], v[170:173], v[124:127]
	v_mfma_f32_16x16x32_bf16 v[120:123], v[162:165], v[170:173], v[120:123]
	v_mfma_f32_16x16x32_bf16 v[108:111], v[154:157], v[178:181], v[108:111]
	v_mfma_f32_16x16x32_bf16 v[104:107], v[162:165], v[178:181], v[104:107]
	v_mfma_f32_16x16x32_bf16 v[92:95], v[154:157], v[186:189], v[92:95]
	v_mfma_f32_16x16x32_bf16 v[88:91], v[162:165], v[186:189], v[88:91]
	v_mfma_f32_16x16x32_bf16 v[76:79], v[154:157], v[194:197], v[76:79]
	v_mfma_f32_16x16x32_bf16 v[72:75], v[162:165], v[194:197], v[72:75]
	s_setprio 0
	s_barrier
	s_add_i32 s38, 0, 0x1c000
	s_add_i32 s39, s61, s43
	v_add_u32_e32 v210, s38, v143
	v_lshl_add_u64 v[214:215], v[214:215], 0, s[8:9]
	s_mov_b32 m0, s39
	ds_read_b128 v[198:201], v210
	ds_read_b128 v[202:205], v210 offset:1024
	ds_read_b128 v[206:209], v210 offset:2048
	ds_read_b128 v[210:213], v210 offset:3072
	global_load_lds_dwordx4 v[214:215], off
	v_lshl_add_u64 v[214:215], v[216:217], 0, s[8:9]
	s_add_i32 m0, s39, 0x2000
	s_nop 0
	global_load_lds_dwordx4 v[214:215], off
	s_barrier
	s_waitcnt lgkmcnt(0)
	s_setprio 1
	s_waitcnt lgkmcnt(0)
	v_mfma_f32_16x16x32_bf16 v[116:119], v[198:201], v[166:169], v[116:119]
	v_mfma_f32_16x16x32_bf16 v[112:115], v[206:209], v[166:169], v[112:115]
	v_mfma_f32_16x16x32_bf16 v[100:103], v[198:201], v[174:177], v[100:103]
	v_mfma_f32_16x16x32_bf16 v[96:99], v[206:209], v[174:177], v[96:99]
	v_mfma_f32_16x16x32_bf16 v[84:87], v[198:201], v[182:185], v[84:87]
	v_mfma_f32_16x16x32_bf16 v[80:83], v[206:209], v[182:185], v[80:83]
	v_mfma_f32_16x16x32_bf16 v[68:71], v[198:201], v[190:193], v[68:71]
	v_mfma_f32_16x16x32_bf16 v[64:67], v[206:209], v[190:193], v[64:67]
	v_mfma_f32_16x16x32_bf16 v[116:119], v[202:205], v[170:173], v[116:119]
	v_mfma_f32_16x16x32_bf16 v[112:115], v[210:213], v[170:173], v[112:115]
	v_mfma_f32_16x16x32_bf16 v[100:103], v[202:205], v[178:181], v[100:103]
	v_mfma_f32_16x16x32_bf16 v[96:99], v[210:213], v[178:181], v[96:99]
	v_mfma_f32_16x16x32_bf16 v[84:87], v[202:205], v[186:189], v[84:87]
	v_mfma_f32_16x16x32_bf16 v[80:83], v[210:213], v[186:189], v[80:83]
	v_mfma_f32_16x16x32_bf16 v[68:71], v[202:205], v[194:197], v[68:71]
	v_mfma_f32_16x16x32_bf16 v[64:67], v[210:213], v[194:197], v[64:67]
	s_setprio 0
	s_mov_b32 m0, s50
	v_lshl_add_u64 v[214:215], v[218:219], 0, s[8:9]
	s_barrier
	ds_read_b128 v[166:169], v148 offset:49152
	ds_read_b128 v[170:173], v148 offset:50176
	ds_read_b128 v[174:177], v148 offset:51200
	ds_read_b128 v[178:181], v148 offset:52224
	ds_read_b128 v[182:185], v148 offset:53248
	ds_read_b128 v[186:189], v148 offset:54272
	ds_read_b128 v[190:193], v148 offset:55296
	ds_read_b128 v[194:197], v148 offset:56320
	global_load_lds_dwordx4 v[214:215], off
	v_lshl_add_u64 v[214:215], v[220:221], 0, s[8:9]
	s_mov_b32 m0, s51
	s_nop 0
	global_load_lds_dwordx4 v[214:215], off
	s_barrier
	s_waitcnt lgkmcnt(0)
	s_setprio 1
	s_waitcnt lgkmcnt(0)
	v_mfma_f32_16x16x32_bf16 v[60:63], v[150:153], v[166:169], v[60:63]
	v_mfma_f32_16x16x32_bf16 v[56:59], v[158:161], v[166:169], v[56:59]
	v_mfma_f32_16x16x32_bf16 v[44:47], v[150:153], v[174:177], v[44:47]
	v_mfma_f32_16x16x32_bf16 v[40:43], v[158:161], v[174:177], v[40:43]
	v_mfma_f32_16x16x32_bf16 v[28:31], v[150:153], v[182:185], v[28:31]
	v_mfma_f32_16x16x32_bf16 v[24:27], v[158:161], v[182:185], v[24:27]
	v_mfma_f32_16x16x32_bf16 v[12:15], v[150:153], v[190:193], v[12:15]
	v_mfma_f32_16x16x32_bf16 v[8:11], v[158:161], v[190:193], v[8:11]
	v_mfma_f32_16x16x32_bf16 v[60:63], v[154:157], v[170:173], v[60:63]
	v_mfma_f32_16x16x32_bf16 v[56:59], v[162:165], v[170:173], v[56:59]
	v_mfma_f32_16x16x32_bf16 v[44:47], v[154:157], v[178:181], v[44:47]
	v_mfma_f32_16x16x32_bf16 v[40:43], v[162:165], v[178:181], v[40:43]
	v_mfma_f32_16x16x32_bf16 v[28:31], v[154:157], v[186:189], v[28:31]
	v_mfma_f32_16x16x32_bf16 v[24:27], v[162:165], v[186:189], v[24:27]
	v_mfma_f32_16x16x32_bf16 v[12:15], v[154:157], v[194:197], v[12:15]
	v_mfma_f32_16x16x32_bf16 v[8:11], v[162:165], v[194:197], v[8:11]
	s_setprio 0
	s_barrier
	s_add_u32 s36, s36, 0x80080
	s_addc_u32 s37, s37, 0
	s_add_i32 s38, s38, s43
	v_lshl_add_u64 v[150:151], s[36:37], 0, v[132:133]
	s_mov_b32 m0, s38
	s_nop 0
	global_load_lds_dwordx4 v[150:151], off
	v_lshl_add_u64 v[150:151], s[36:37], 0, v[128:129]
	s_add_i32 m0, s38, 0x2000
	s_nop 0
	global_load_lds_dwordx4 v[150:151], off
	s_waitcnt vmcnt(6)
	s_barrier
	s_setprio 1
	v_mfma_f32_16x16x32_bf16 v[52:55], v[198:201], v[166:169], v[52:55]
	v_mfma_f32_16x16x32_bf16 v[48:51], v[206:209], v[166:169], v[48:51]
	v_mfma_f32_16x16x32_bf16 v[36:39], v[198:201], v[174:177], v[36:39]
	v_mfma_f32_16x16x32_bf16 v[32:35], v[206:209], v[174:177], v[32:35]
	v_mfma_f32_16x16x32_bf16 v[20:23], v[198:201], v[182:185], v[20:23]
	v_mfma_f32_16x16x32_bf16 v[16:19], v[206:209], v[182:185], v[16:19]
	v_mfma_f32_16x16x32_bf16 v[4:7], v[198:201], v[190:193], v[4:7]
	v_mfma_f32_16x16x32_bf16 v[0:3], v[206:209], v[190:193], v[0:3]
	v_mfma_f32_16x16x32_bf16 v[52:55], v[202:205], v[170:173], v[52:55]
	v_mfma_f32_16x16x32_bf16 v[48:51], v[210:213], v[170:173], v[48:51]
	v_mfma_f32_16x16x32_bf16 v[36:39], v[202:205], v[178:181], v[36:39]
	v_mfma_f32_16x16x32_bf16 v[32:35], v[210:213], v[178:181], v[32:35]
	v_mfma_f32_16x16x32_bf16 v[20:23], v[202:205], v[186:189], v[20:23]
	v_mfma_f32_16x16x32_bf16 v[16:19], v[210:213], v[186:189], v[16:19]
	v_mfma_f32_16x16x32_bf16 v[4:7], v[202:205], v[194:197], v[4:7]
	v_mfma_f32_16x16x32_bf16 v[0:3], v[210:213], v[194:197], v[0:3]
	s_setprio 0
	s_add_i32 s60, s60, 2
	s_add_u32 s34, s34, 0x100
	s_addc_u32 s35, s35, 0
	s_add_u32 s29, s29, 0x100
	s_addc_u32 s59, s59, 0
	s_cmp_gt_u32 s60, 29
	s_barrier
	s_cbranch_scc0 .LBB0_1203
	v_pk_add_f32 v[124:125], v[124:125], 0 op_sel_hi:[1,0]
	v_pk_add_f32 v[126:127], v[126:127], 0 op_sel_hi:[1,0]
	v_mul_f32_e32 v151, 0xbfb8aa3b, v124
	v_exp_f32_e32 v151, v151
	v_mul_f32_e32 v154, 0xbfb8aa3b, v125
	v_exp_f32_e32 v155, v154
	v_pk_add_f32 v[116:117], v[116:117], 0 op_sel_hi:[1,0]
	v_add_f32_e32 v151, 1.0, v151
	v_rcp_f32_e32 v154, v151
	v_add_f32_e32 v151, 1.0, v155
	v_mul_f32_e32 v155, 0xbfb8aa3b, v126
	v_exp_f32_e32 v156, v155
	v_mul_f32_e32 v155, 0xbfb8aa3b, v127
	v_exp_f32_e32 v157, v155
	v_rcp_f32_e32 v155, v151
	v_add_f32_e32 v151, 1.0, v156
	v_rcp_f32_e32 v156, v151
	v_add_f32_e32 v151, 1.0, v157
	v_rcp_f32_e32 v157, v151
	v_pk_mul_f32 v[124:125], v[124:125], v[154:155]
	v_pk_add_f32 v[120:121], v[120:121], 0 op_sel_hi:[1,0]
	v_pk_mul_f32 v[116:117], v[124:125], v[116:117]
	v_pk_mul_f32 v[124:125], v[126:127], v[156:157]
	v_mul_f32_e32 v126, 0xbfb8aa3b, v120
	v_exp_f32_e32 v126, v126
	v_pk_add_f32 v[118:119], v[118:119], 0 op_sel_hi:[1,0]
	v_pk_add_f32 v[122:123], v[122:123], 0 op_sel_hi:[1,0]
	v_pk_mul_f32 v[118:119], v[124:125], v[118:119]
	v_mul_f32_e32 v124, 0xbfb8aa3b, v121
	v_exp_f32_e32 v125, v124
	v_add_f32_e32 v124, 1.0, v126
	v_mul_f32_e32 v126, 0xbfb8aa3b, v122
	v_mul_f32_e32 v127, 0xbfb8aa3b, v123
	v_exp_f32_e32 v126, v126
	v_exp_f32_e32 v127, v127
	v_add_f32_e32 v125, 1.0, v125
	v_rcp_f32_e32 v124, v124
	v_rcp_f32_e32 v125, v125
	v_add_f32_e32 v126, 1.0, v126
	v_add_f32_e32 v127, 1.0, v127
	v_rcp_f32_e32 v126, v126
	v_rcp_f32_e32 v127, v127
	v_pk_add_f32 v[112:113], v[112:113], 0 op_sel_hi:[1,0]
	v_pk_mul_f32 v[120:121], v[120:121], v[124:125]
	v_lshl_or_b32 v152, s57, 7, v146
	v_pk_mul_f32 v[112:113], v[120:121], v[112:113]
	v_pk_add_f32 v[114:115], v[114:115], 0 op_sel_hi:[1,0]
	v_pk_mul_f32 v[120:121], v[122:123], v[126:127]
	v_lshl_add_u32 v150, s30, 8, v142
	v_ashrrev_i32_e32 v153, 31, v152
	v_pk_mul_f32 v[114:115], v[120:121], v[114:115]
	v_cvt_pk_bf16_f32 v116, v116, v117
	v_cvt_pk_bf16_f32 v117, v118, v119
	v_cvt_pk_bf16_f32 v118, v112, v113
	v_mov_b64_e32 v[112:113], s[6:7]
	v_cvt_pk_bf16_f32 v119, v114, v115
	v_mad_i64_i32 v[120:121], s[28:29], v150, s56, v[112:113]
	v_lshlrev_b64 v[114:115], 1, v[152:153]
	v_lshl_add_u64 v[120:121], v[120:121], 0, v[114:115]
	v_pk_add_f32 v[108:109], v[108:109], 0 op_sel_hi:[1,0]
	global_store_dwordx4 v[120:121], v[116:119], off sc0 sc1
	v_mul_f32_e32 v122, 0xbfb8aa3b, v108
	v_pk_add_f32 v[110:111], v[110:111], 0 op_sel_hi:[1,0]
	v_mul_f32_e32 v116, 0xbfb8aa3b, v109
	v_exp_f32_e32 v122, v122
	v_exp_f32_e32 v117, v116
	v_mul_f32_e32 v118, 0xbfb8aa3b, v110
	v_mul_f32_e32 v119, 0xbfb8aa3b, v111
	v_exp_f32_e32 v118, v118
	v_exp_f32_e32 v119, v119
	v_add_f32_e32 v116, 1.0, v122
	v_add_f32_e32 v117, 1.0, v117
	v_rcp_f32_e32 v116, v116
	v_rcp_f32_e32 v117, v117
	v_add_f32_e32 v118, 1.0, v118
	v_add_f32_e32 v119, 1.0, v119
	v_rcp_f32_e32 v118, v118
	v_rcp_f32_e32 v119, v119
	v_pk_add_f32 v[100:101], v[100:101], 0 op_sel_hi:[1,0]
	v_pk_mul_f32 v[108:109], v[108:109], v[116:117]
	v_pk_add_f32 v[104:105], v[104:105], 0 op_sel_hi:[1,0]
	v_pk_mul_f32 v[100:101], v[108:109], v[100:101]
	v_pk_mul_f32 v[108:109], v[110:111], v[118:119]
	v_mul_f32_e32 v110, 0xbfb8aa3b, v104
	v_exp_f32_e32 v110, v110
	v_pk_add_f32 v[102:103], v[102:103], 0 op_sel_hi:[1,0]
	v_pk_add_f32 v[106:107], v[106:107], 0 op_sel_hi:[1,0]
	v_pk_mul_f32 v[102:103], v[108:109], v[102:103]
	v_mul_f32_e32 v108, 0xbfb8aa3b, v105
	v_exp_f32_e32 v109, v108
	v_add_f32_e32 v108, 1.0, v110
	v_mul_f32_e32 v110, 0xbfb8aa3b, v106
	v_mul_f32_e32 v111, 0xbfb8aa3b, v107
	v_exp_f32_e32 v110, v110
	v_exp_f32_e32 v111, v111
	v_add_f32_e32 v109, 1.0, v109
	v_rcp_f32_e32 v108, v108
	v_rcp_f32_e32 v109, v109
	v_add_f32_e32 v110, 1.0, v110
	v_add_f32_e32 v111, 1.0, v111
	v_rcp_f32_e32 v110, v110
	v_rcp_f32_e32 v111, v111
	v_pk_add_f32 v[96:97], v[96:97], 0 op_sel_hi:[1,0]
	v_pk_mul_f32 v[104:105], v[104:105], v[108:109]
	v_or_b32_e32 v108, 16, v150
	v_pk_mul_f32 v[104:105], v[104:105], v[96:97]
	v_pk_add_f32 v[96:97], v[98:99], 0 op_sel_hi:[1,0]
	v_pk_mul_f32 v[98:99], v[106:107], v[110:111]
	v_pk_add_f32 v[92:93], v[92:93], 0 op_sel_hi:[1,0]
	v_pk_mul_f32 v[106:107], v[98:99], v[96:97]
	v_cvt_pk_bf16_f32 v96, v100, v101
	v_mad_i64_i32 v[100:101], s[28:29], v108, s56, v[112:113]
	v_cvt_pk_bf16_f32 v97, v102, v103
	v_cvt_pk_bf16_f32 v98, v104, v105
	v_cvt_pk_bf16_f32 v99, v106, v107
	v_lshl_add_u64 v[100:101], v[100:101], 0, v[114:115]
	v_mul_f32_e32 v102, 0xbfb8aa3b, v92
	global_store_dwordx4 v[100:101], v[96:99], off sc0 sc1
	v_pk_add_f32 v[94:95], v[94:95], 0 op_sel_hi:[1,0]
	v_exp_f32_e32 v102, v102
	v_mul_f32_e32 v96, 0xbfb8aa3b, v93
	v_exp_f32_e32 v97, v96
	v_mul_f32_e32 v98, 0xbfb8aa3b, v94
	v_mul_f32_e32 v99, 0xbfb8aa3b, v95
	v_exp_f32_e32 v98, v98
	v_exp_f32_e32 v99, v99
	v_add_f32_e32 v96, 1.0, v102
	v_add_f32_e32 v97, 1.0, v97
	v_rcp_f32_e32 v96, v96
	v_rcp_f32_e32 v97, v97
	v_add_f32_e32 v98, 1.0, v98
	v_add_f32_e32 v99, 1.0, v99
	v_rcp_f32_e32 v98, v98
	v_rcp_f32_e32 v99, v99
	v_pk_add_f32 v[84:85], v[84:85], 0 op_sel_hi:[1,0]
	v_pk_mul_f32 v[92:93], v[92:93], v[96:97]
	v_pk_add_f32 v[88:89], v[88:89], 0 op_sel_hi:[1,0]
	v_pk_mul_f32 v[84:85], v[92:93], v[84:85]
	v_pk_mul_f32 v[92:93], v[94:95], v[98:99]
	v_mul_f32_e32 v94, 0xbfb8aa3b, v88
	v_exp_f32_e32 v94, v94
	v_pk_add_f32 v[86:87], v[86:87], 0 op_sel_hi:[1,0]
	v_pk_add_f32 v[90:91], v[90:91], 0 op_sel_hi:[1,0]
	v_pk_mul_f32 v[86:87], v[92:93], v[86:87]
	v_mul_f32_e32 v92, 0xbfb8aa3b, v89
	v_exp_f32_e32 v93, v92
	v_add_f32_e32 v92, 1.0, v94
	v_mul_f32_e32 v94, 0xbfb8aa3b, v90
	v_mul_f32_e32 v95, 0xbfb8aa3b, v91
	v_exp_f32_e32 v94, v94
	v_exp_f32_e32 v95, v95
	v_add_f32_e32 v93, 1.0, v93
	v_rcp_f32_e32 v92, v92
	v_rcp_f32_e32 v93, v93
	v_add_f32_e32 v94, 1.0, v94
	v_add_f32_e32 v95, 1.0, v95
	v_rcp_f32_e32 v94, v94
	v_rcp_f32_e32 v95, v95
	v_pk_add_f32 v[80:81], v[80:81], 0 op_sel_hi:[1,0]
	v_pk_mul_f32 v[88:89], v[88:89], v[92:93]
	v_or_b32_e32 v92, 32, v150
	v_pk_mul_f32 v[88:89], v[88:89], v[80:81]
	v_pk_add_f32 v[80:81], v[82:83], 0 op_sel_hi:[1,0]
	v_pk_mul_f32 v[82:83], v[90:91], v[94:95]
	v_pk_add_f32 v[76:77], v[76:77], 0 op_sel_hi:[1,0]
	v_pk_mul_f32 v[90:91], v[82:83], v[80:81]
	v_cvt_pk_bf16_f32 v80, v84, v85
	v_mad_i64_i32 v[84:85], s[28:29], v92, s56, v[112:113]
	v_cvt_pk_bf16_f32 v81, v86, v87
	v_cvt_pk_bf16_f32 v82, v88, v89
	v_cvt_pk_bf16_f32 v83, v90, v91
	v_lshl_add_u64 v[84:85], v[84:85], 0, v[114:115]
	v_mul_f32_e32 v86, 0xbfb8aa3b, v76
	global_store_dwordx4 v[84:85], v[80:83], off sc0 sc1
	v_pk_add_f32 v[78:79], v[78:79], 0 op_sel_hi:[1,0]
	v_exp_f32_e32 v86, v86
	v_mul_f32_e32 v80, 0xbfb8aa3b, v77
	v_exp_f32_e32 v81, v80
	v_mul_f32_e32 v82, 0xbfb8aa3b, v78
	v_mul_f32_e32 v83, 0xbfb8aa3b, v79
	v_exp_f32_e32 v82, v82
	v_exp_f32_e32 v83, v83
	v_add_f32_e32 v80, 1.0, v86
	v_add_f32_e32 v81, 1.0, v81
	v_rcp_f32_e32 v80, v80
	v_rcp_f32_e32 v81, v81
	v_add_f32_e32 v82, 1.0, v82
	v_add_f32_e32 v83, 1.0, v83
	v_rcp_f32_e32 v82, v82
	v_rcp_f32_e32 v83, v83
	v_pk_add_f32 v[68:69], v[68:69], 0 op_sel_hi:[1,0]
	v_pk_mul_f32 v[76:77], v[76:77], v[80:81]
	v_pk_add_f32 v[72:73], v[72:73], 0 op_sel_hi:[1,0]
	v_pk_mul_f32 v[68:69], v[76:77], v[68:69]
	v_pk_mul_f32 v[76:77], v[78:79], v[82:83]
	v_mul_f32_e32 v78, 0xbfb8aa3b, v72
	v_exp_f32_e32 v78, v78
	v_pk_add_f32 v[70:71], v[70:71], 0 op_sel_hi:[1,0]
	v_pk_add_f32 v[74:75], v[74:75], 0 op_sel_hi:[1,0]
	v_pk_mul_f32 v[70:71], v[76:77], v[70:71]
	v_mul_f32_e32 v76, 0xbfb8aa3b, v73
	v_exp_f32_e32 v77, v76
	v_add_f32_e32 v76, 1.0, v78
	v_mul_f32_e32 v78, 0xbfb8aa3b, v74
	v_mul_f32_e32 v79, 0xbfb8aa3b, v75
	v_exp_f32_e32 v78, v78
	v_exp_f32_e32 v79, v79
	v_add_f32_e32 v77, 1.0, v77
	v_rcp_f32_e32 v76, v76
	v_rcp_f32_e32 v77, v77
	v_add_f32_e32 v78, 1.0, v78
	v_add_f32_e32 v79, 1.0, v79
	v_rcp_f32_e32 v78, v78
	v_rcp_f32_e32 v79, v79
	v_pk_add_f32 v[64:65], v[64:65], 0 op_sel_hi:[1,0]
	v_pk_mul_f32 v[72:73], v[72:73], v[76:77]
	v_or_b32_e32 v76, 48, v150
	v_pk_mul_f32 v[72:73], v[72:73], v[64:65]
	v_pk_add_f32 v[64:65], v[66:67], 0 op_sel_hi:[1,0]
	v_pk_mul_f32 v[66:67], v[74:75], v[78:79]
	v_pk_add_f32 v[60:61], v[60:61], 0 op_sel_hi:[1,0]
	v_pk_mul_f32 v[74:75], v[66:67], v[64:65]
	v_cvt_pk_bf16_f32 v64, v68, v69
	v_mad_i64_i32 v[68:69], s[28:29], v76, s56, v[112:113]
	v_cvt_pk_bf16_f32 v65, v70, v71
	v_cvt_pk_bf16_f32 v66, v72, v73
	v_cvt_pk_bf16_f32 v67, v74, v75
	v_lshl_add_u64 v[68:69], v[68:69], 0, v[114:115]
	global_store_dwordx4 v[68:69], v[64:67], off sc0 sc1
	v_pk_add_f32 v[62:63], v[62:63], 0 op_sel_hi:[1,0]
	v_pk_add_f32 v[52:53], v[52:53], 0 op_sel_hi:[1,0]
	v_mul_f32_e32 v64, 0xbfb8aa3b, v60
	v_mul_f32_e32 v65, 0xbfb8aa3b, v61
	v_exp_f32_e32 v64, v64
	v_exp_f32_e32 v65, v65
	v_mul_f32_e32 v66, 0xbfb8aa3b, v62
	v_mul_f32_e32 v67, 0xbfb8aa3b, v63
	v_exp_f32_e32 v66, v66
	v_exp_f32_e32 v67, v67
	v_add_f32_e32 v64, 1.0, v64
	v_add_f32_e32 v65, 1.0, v65
	v_rcp_f32_e32 v64, v64
	v_rcp_f32_e32 v65, v65
	v_add_f32_e32 v66, 1.0, v66
	v_add_f32_e32 v67, 1.0, v67
	v_rcp_f32_e32 v66, v66
	v_rcp_f32_e32 v67, v67
	v_pk_mul_f32 v[60:61], v[60:61], v[64:65]
	v_pk_add_f32 v[56:57], v[56:57], 0 op_sel_hi:[1,0]
	v_pk_mul_f32 v[52:53], v[60:61], v[52:53]
	v_pk_mul_f32 v[60:61], v[62:63], v[66:67]
	v_mul_f32_e32 v62, 0xbfb8aa3b, v56
	v_exp_f32_e32 v62, v62
	v_pk_add_f32 v[54:55], v[54:55], 0 op_sel_hi:[1,0]
	v_pk_add_f32 v[58:59], v[58:59], 0 op_sel_hi:[1,0]
	v_pk_mul_f32 v[54:55], v[60:61], v[54:55]
	v_mul_f32_e32 v60, 0xbfb8aa3b, v57
	v_exp_f32_e32 v61, v60
	v_add_f32_e32 v60, 1.0, v62
	v_mul_f32_e32 v62, 0xbfb8aa3b, v58
	v_mul_f32_e32 v63, 0xbfb8aa3b, v59
	v_exp_f32_e32 v62, v62
	v_exp_f32_e32 v63, v63
	v_add_f32_e32 v61, 1.0, v61
	v_rcp_f32_e32 v60, v60
	v_rcp_f32_e32 v61, v61
	v_add_f32_e32 v62, 1.0, v62
	v_add_f32_e32 v63, 1.0, v63
	v_rcp_f32_e32 v62, v62
	v_rcp_f32_e32 v63, v63
	v_pk_add_f32 v[48:49], v[48:49], 0 op_sel_hi:[1,0]
	v_pk_mul_f32 v[56:57], v[56:57], v[60:61]
	v_add_u32_e32 v68, 0x80, v150
	v_pk_mul_f32 v[56:57], v[56:57], v[48:49]
	v_pk_add_f32 v[48:49], v[50:51], 0 op_sel_hi:[1,0]
	v_pk_mul_f32 v[50:51], v[58:59], v[62:63]
	v_pk_add_f32 v[44:45], v[44:45], 0 op_sel_hi:[1,0]
	v_pk_mul_f32 v[58:59], v[50:51], v[48:49]
	v_cvt_pk_bf16_f32 v48, v52, v53
	v_mad_i64_i32 v[52:53], s[28:29], v68, s56, v[112:113]
	v_cvt_pk_bf16_f32 v49, v54, v55
	v_cvt_pk_bf16_f32 v50, v56, v57
	v_cvt_pk_bf16_f32 v51, v58, v59
	v_lshl_add_u64 v[52:53], v[52:53], 0, v[114:115]
	v_mul_f32_e32 v54, 0xbfb8aa3b, v44
	global_store_dwordx4 v[52:53], v[48:51], off sc0 sc1
	v_pk_add_f32 v[46:47], v[46:47], 0 op_sel_hi:[1,0]
	v_exp_f32_e32 v54, v54
	v_mul_f32_e32 v48, 0xbfb8aa3b, v45
	v_exp_f32_e32 v49, v48
	v_mul_f32_e32 v50, 0xbfb8aa3b, v46
	v_mul_f32_e32 v51, 0xbfb8aa3b, v47
	v_exp_f32_e32 v50, v50
	v_exp_f32_e32 v51, v51
	v_add_f32_e32 v48, 1.0, v54
	v_add_f32_e32 v49, 1.0, v49
	v_rcp_f32_e32 v48, v48
	v_rcp_f32_e32 v49, v49
	v_add_f32_e32 v50, 1.0, v50
	v_add_f32_e32 v51, 1.0, v51
	v_rcp_f32_e32 v50, v50
	v_rcp_f32_e32 v51, v51
	v_pk_add_f32 v[36:37], v[36:37], 0 op_sel_hi:[1,0]
	v_pk_mul_f32 v[44:45], v[44:45], v[48:49]
	v_pk_add_f32 v[40:41], v[40:41], 0 op_sel_hi:[1,0]
	v_pk_mul_f32 v[36:37], v[44:45], v[36:37]
	v_pk_mul_f32 v[44:45], v[46:47], v[50:51]
	v_mul_f32_e32 v46, 0xbfb8aa3b, v40
	v_exp_f32_e32 v46, v46
	v_pk_add_f32 v[38:39], v[38:39], 0 op_sel_hi:[1,0]
	v_pk_add_f32 v[42:43], v[42:43], 0 op_sel_hi:[1,0]
	v_pk_mul_f32 v[38:39], v[44:45], v[38:39]
	v_mul_f32_e32 v44, 0xbfb8aa3b, v41
	v_exp_f32_e32 v45, v44
	v_add_f32_e32 v44, 1.0, v46
	v_mul_f32_e32 v46, 0xbfb8aa3b, v42
	v_mul_f32_e32 v47, 0xbfb8aa3b, v43
	v_exp_f32_e32 v46, v46
	v_exp_f32_e32 v47, v47
	v_add_f32_e32 v45, 1.0, v45
	v_rcp_f32_e32 v44, v44
	v_rcp_f32_e32 v45, v45
	v_add_f32_e32 v46, 1.0, v46
	v_add_f32_e32 v47, 1.0, v47
	v_rcp_f32_e32 v46, v46
	v_rcp_f32_e32 v47, v47
	v_pk_add_f32 v[32:33], v[32:33], 0 op_sel_hi:[1,0]
	v_pk_mul_f32 v[40:41], v[40:41], v[44:45]
	v_add_u32_e32 v44, 0x90, v150
	v_pk_mul_f32 v[40:41], v[40:41], v[32:33]
	v_pk_add_f32 v[32:33], v[34:35], 0 op_sel_hi:[1,0]
	v_pk_mul_f32 v[34:35], v[42:43], v[46:47]
	v_pk_add_f32 v[28:29], v[28:29], 0 op_sel_hi:[1,0]
	v_pk_mul_f32 v[42:43], v[34:35], v[32:33]
	v_cvt_pk_bf16_f32 v32, v36, v37
	v_mad_i64_i32 v[36:37], s[28:29], v44, s56, v[112:113]
	v_cvt_pk_bf16_f32 v33, v38, v39
	v_cvt_pk_bf16_f32 v34, v40, v41
	v_cvt_pk_bf16_f32 v35, v42, v43
	v_lshl_add_u64 v[36:37], v[36:37], 0, v[114:115]
	v_mul_f32_e32 v38, 0xbfb8aa3b, v28
	global_store_dwordx4 v[36:37], v[32:35], off sc0 sc1
	v_pk_add_f32 v[30:31], v[30:31], 0 op_sel_hi:[1,0]
	v_exp_f32_e32 v38, v38
	v_mul_f32_e32 v32, 0xbfb8aa3b, v29
	v_exp_f32_e32 v33, v32
	v_mul_f32_e32 v34, 0xbfb8aa3b, v30
	v_mul_f32_e32 v35, 0xbfb8aa3b, v31
	v_exp_f32_e32 v34, v34
	v_exp_f32_e32 v35, v35
	v_add_f32_e32 v32, 1.0, v38
	v_add_f32_e32 v33, 1.0, v33
	v_rcp_f32_e32 v32, v32
	v_rcp_f32_e32 v33, v33
	v_add_f32_e32 v34, 1.0, v34
	v_add_f32_e32 v35, 1.0, v35
	v_rcp_f32_e32 v34, v34
	v_rcp_f32_e32 v35, v35
	v_pk_add_f32 v[20:21], v[20:21], 0 op_sel_hi:[1,0]
	v_pk_mul_f32 v[28:29], v[28:29], v[32:33]
	v_pk_add_f32 v[24:25], v[24:25], 0 op_sel_hi:[1,0]
	v_pk_mul_f32 v[20:21], v[28:29], v[20:21]
	v_pk_mul_f32 v[28:29], v[30:31], v[34:35]
	v_mul_f32_e32 v30, 0xbfb8aa3b, v24
	v_exp_f32_e32 v30, v30
	v_pk_add_f32 v[22:23], v[22:23], 0 op_sel_hi:[1,0]
	v_pk_add_f32 v[26:27], v[26:27], 0 op_sel_hi:[1,0]
	v_pk_mul_f32 v[22:23], v[28:29], v[22:23]
	v_mul_f32_e32 v28, 0xbfb8aa3b, v25
	v_exp_f32_e32 v29, v28
	v_add_f32_e32 v28, 1.0, v30
	v_mul_f32_e32 v30, 0xbfb8aa3b, v26
	v_mul_f32_e32 v31, 0xbfb8aa3b, v27
	v_exp_f32_e32 v30, v30
	v_exp_f32_e32 v31, v31
	v_add_f32_e32 v29, 1.0, v29
	v_rcp_f32_e32 v28, v28
	v_rcp_f32_e32 v29, v29
	v_add_f32_e32 v30, 1.0, v30
	v_add_f32_e32 v31, 1.0, v31
	v_rcp_f32_e32 v30, v30
	v_rcp_f32_e32 v31, v31
	v_pk_add_f32 v[16:17], v[16:17], 0 op_sel_hi:[1,0]
	v_pk_mul_f32 v[24:25], v[24:25], v[28:29]
	v_add_u32_e32 v28, 0xa0, v150
	v_pk_mul_f32 v[24:25], v[24:25], v[16:17]
	v_pk_add_f32 v[16:17], v[18:19], 0 op_sel_hi:[1,0]
	v_pk_mul_f32 v[18:19], v[26:27], v[30:31]
	v_pk_add_f32 v[12:13], v[12:13], 0 op_sel_hi:[1,0]
	v_pk_mul_f32 v[26:27], v[18:19], v[16:17]
	v_cvt_pk_bf16_f32 v16, v20, v21
	v_mad_i64_i32 v[20:21], s[28:29], v28, s56, v[112:113]
	v_cvt_pk_bf16_f32 v17, v22, v23
	v_cvt_pk_bf16_f32 v18, v24, v25
	v_cvt_pk_bf16_f32 v19, v26, v27
	v_lshl_add_u64 v[20:21], v[20:21], 0, v[114:115]
	v_mul_f32_e32 v22, 0xbfb8aa3b, v12
	global_store_dwordx4 v[20:21], v[16:19], off sc0 sc1
	v_pk_add_f32 v[14:15], v[14:15], 0 op_sel_hi:[1,0]
	v_exp_f32_e32 v22, v22
	v_mul_f32_e32 v16, 0xbfb8aa3b, v13
	v_exp_f32_e32 v17, v16
	v_mul_f32_e32 v18, 0xbfb8aa3b, v14
	v_mul_f32_e32 v19, 0xbfb8aa3b, v15
	v_exp_f32_e32 v18, v18
	v_exp_f32_e32 v19, v19
	v_add_f32_e32 v16, 1.0, v22
	v_add_f32_e32 v17, 1.0, v17
	v_rcp_f32_e32 v16, v16
	v_rcp_f32_e32 v17, v17
	v_add_f32_e32 v18, 1.0, v18
	v_add_f32_e32 v19, 1.0, v19
	v_rcp_f32_e32 v18, v18
	v_rcp_f32_e32 v19, v19
	v_pk_add_f32 v[4:5], v[4:5], 0 op_sel_hi:[1,0]
	v_pk_mul_f32 v[12:13], v[12:13], v[16:17]
	v_pk_add_f32 v[8:9], v[8:9], 0 op_sel_hi:[1,0]
	v_pk_mul_f32 v[4:5], v[12:13], v[4:5]
	v_pk_mul_f32 v[12:13], v[14:15], v[18:19]
	v_mul_f32_e32 v14, 0xbfb8aa3b, v8
	v_exp_f32_e32 v14, v14
	v_pk_add_f32 v[6:7], v[6:7], 0 op_sel_hi:[1,0]
	v_pk_add_f32 v[10:11], v[10:11], 0 op_sel_hi:[1,0]
	v_pk_mul_f32 v[6:7], v[12:13], v[6:7]
	v_mul_f32_e32 v12, 0xbfb8aa3b, v9
	v_exp_f32_e32 v13, v12
	v_add_f32_e32 v12, 1.0, v14
	v_mul_f32_e32 v14, 0xbfb8aa3b, v10
	v_mul_f32_e32 v15, 0xbfb8aa3b, v11
	v_exp_f32_e32 v14, v14
	v_exp_f32_e32 v15, v15
	v_add_f32_e32 v13, 1.0, v13
	v_rcp_f32_e32 v12, v12
	v_rcp_f32_e32 v13, v13
	v_add_f32_e32 v14, 1.0, v14
	v_add_f32_e32 v15, 1.0, v15
	v_rcp_f32_e32 v14, v14
	v_rcp_f32_e32 v15, v15
	v_pk_add_f32 v[0:1], v[0:1], 0 op_sel_hi:[1,0]
	v_pk_mul_f32 v[8:9], v[8:9], v[12:13]
	v_add_u32_e32 v12, 0xb0, v150
	v_pk_mul_f32 v[8:9], v[8:9], v[0:1]
	v_pk_add_f32 v[0:1], v[2:3], 0 op_sel_hi:[1,0]
	v_pk_mul_f32 v[2:3], v[10:11], v[14:15]
	s_and_b64 vcc, exec, s[16:17]
	v_pk_mul_f32 v[10:11], v[2:3], v[0:1]
	v_cvt_pk_bf16_f32 v0, v4, v5
	v_mad_i64_i32 v[4:5], s[28:29], v12, s56, v[112:113]
	v_cvt_pk_bf16_f32 v1, v6, v7
	v_cvt_pk_bf16_f32 v2, v8, v9
	v_cvt_pk_bf16_f32 v3, v10, v11
	v_lshl_add_u64 v[4:5], v[4:5], 0, v[114:115]
	s_mov_b32 s57, s10
	s_mov_b32 s30, s12
	s_mov_b64 s[36:37], s[18:19]
	s_mov_b64 s[34:35], s[14:15]
	global_store_dwordx4 v[4:5], v[0:3], off sc0 sc1
	s_cbranch_vccz .LBB0_1198
	s_branch .LBB0_1206

.LBB0_1345:
	s_cmp_lt_i32 s24, 11
	s_cselect_b64 s[4:5], -1, 0
	s_and_b64 s[0:1], s[4:5], s[0:1]
	s_andn2_b64 vcc, exec, s[0:1]
	s_cbranch_vccnz .LBB0_1349
	s_waitcnt vmcnt(0)
	v_and_b32_e32 v0, 60, v145
	v_lshl_add_u32 v4, s3, 5, v0
	s_movk_i32 s0, 0x4000
	v_cmp_gt_i32_e32 vcc, s0, v4
	s_and_saveexec_b64 s[0:1], vcc
	s_cbranch_execz .LBB0_1349
	v_mbcnt_lo_u32_b32 v1, -1, 0
	v_mbcnt_hi_u32_b32 v1, -1, v1
	v_and_b32_e32 v2, 64, v1
	v_add_u32_e32 v2, 64, v2
	v_xor_b32_e32 v3, 32, v1
	v_cmp_lt_i32_e32 vcc, v3, v2
	v_lshlrev_b32_e32 v0, 2, v144
	v_readlane_b32 s4, v248, 0
	v_cndmask_b32_e32 v3, v1, v3, vcc
	v_lshlrev_b32_e32 v132, 2, v3
	v_xor_b32_e32 v3, 16, v1
	v_cmp_lt_i32_e32 vcc, v3, v2
	v_and_b32_e32 v0, 0xfc, v0
	v_readlane_b32 s6, v248, 2
	v_cndmask_b32_e32 v3, v1, v3, vcc
	v_lshlrev_b32_e32 v133, 2, v3
	v_xor_b32_e32 v3, 8, v1
	v_cmp_lt_i32_e32 vcc, v3, v2
	v_readlane_b32 s7, v248, 3
	v_readlane_b32 s10, v248, 6
	v_cndmask_b32_e32 v3, v1, v3, vcc
	v_lshlrev_b32_e32 v134, 2, v3
	v_xor_b32_e32 v3, 4, v1
	v_cmp_lt_i32_e32 vcc, v3, v2
	v_readlane_b32 s11, v248, 7
	v_mov_b32_e32 v7, 0
	v_cndmask_b32_e32 v3, v1, v3, vcc
	v_lshlrev_b32_e32 v135, 2, v3
	v_xor_b32_e32 v3, 2, v1
	v_cmp_lt_i32_e32 vcc, v3, v2
	v_lshlrev_b32_e32 v6, 2, v0
	s_mov_b64 s[6:7], s[10:11]
	v_cndmask_b32_e32 v3, v1, v3, vcc
	v_lshlrev_b32_e32 v136, 2, v3
	v_xor_b32_e32 v3, 1, v1
	v_cmp_lt_i32_e32 vcc, v3, v2
	v_or_b32_e32 v2, 0x400, v0
	v_or_b32_e32 v22, 0x500, v0
	v_lshl_add_u64 v[8:9], s[6:7], 0, v[6:7]
	v_lshlrev_b32_e32 v6, 2, v2
	v_or_b32_e32 v24, 0x600, v0
	v_lshl_add_u64 v[10:11], s[6:7], 0, v[6:7]
	v_lshlrev_b32_e32 v6, 2, v22
	v_or_b32_e32 v26, 0x700, v0
	v_lshl_add_u64 v[12:13], s[6:7], 0, v[6:7]
	v_lshlrev_b32_e32 v6, 2, v24
	v_lshl_add_u64 v[14:15], s[6:7], 0, v[6:7]
	v_lshlrev_b32_e32 v6, 2, v26
	v_lshl_add_u64 v[16:17], s[6:7], 0, v[6:7]
	v_lshlrev_b32_e32 v6, 1, v0
	v_cndmask_b32_e32 v1, v1, v3, vcc
	v_readlane_b32 s5, v248, 1
	v_lshl_add_u64 v[18:19], s[22:23], 0, v[6:7]
	s_mov_b64 s[0:1], 0x16a00000
	s_mov_b32 s4, 0x358637bd
	v_lshlrev_b32_e32 v137, 2, v1
	s_lshl_b32 s3, s26, 5
	v_lshl_add_u64 v[18:19], v[18:19], 0, s[0:1]
	s_mov_b64 s[0:1], 0
	v_lshlrev_b32_e32 v6, 2, v0
	v_lshlrev_b32_e32 v20, 2, v2
	v_mov_b32_e32 v21, v7
	v_lshlrev_b32_e32 v22, 2, v22
	v_mov_b32_e32 v23, v7
	v_lshlrev_b32_e32 v24, 2, v24
	v_mov_b32_e32 v25, v7
	v_lshlrev_b32_e32 v26, 2, v26
	v_mov_b32_e32 v27, v7
	s_mov_b32 s2, 0x3a000000
	v_mov_b64_e32 v[28:29], s[4:5]
	s_mov_b32 s4, 0x800000
	s_movk_i32 s5, 0x3fff
	v_readlane_b32 s8, v248, 4
	v_readlane_b32 s9, v248, 5
	global_load_dwordx4 v[180:183], v[8:9], off
	global_load_dwordx4 v[184:187], v[8:9], off offset:1024
	global_load_dwordx4 v[188:191], v[8:9], off offset:2048
	global_load_dwordx4 v[192:195], v[8:9], off offset:3072
	global_load_dwordx4 v[196:199], v[10:11], off
	global_load_dwordx4 v[200:203], v[12:13], off
	global_load_dwordx4 v[204:207], v[14:15], off
	global_load_dwordx4 v[208:211], v[16:17], off
.LBB0_1348:
	v_ashrrev_i32_e32 v5, 31, v4
	v_lshlrev_b64 v[0:1], 12, v[4:5]
	v_lshl_add_u64 v[0:1], v[18:19], 0, v[0:1]
	v_add_u32_e32 v48, 1, v4
	global_load_dwordx2 v[30:31], v[0:1], off offset:2560
	global_load_dwordx2 v[32:33], v[0:1], off offset:2048
	global_load_dwordx2 v[34:35], v[0:1], off offset:3584
	global_load_dwordx2 v[36:37], v[0:1], off offset:3072
	global_load_dwordx2 v[38:39], v[0:1], off
	global_load_dwordx2 v[40:41], v[0:1], off offset:512
	global_load_dwordx2 v[42:43], v[0:1], off offset:1024
	v_ashrrev_i32_e32 v49, 31, v48
	global_load_dwordx2 v[44:45], v[0:1], off offset:1536
	v_lshlrev_b64 v[0:1], 12, v[48:49]
	v_lshl_add_u64 v[46:47], v[18:19], 0, v[0:1]
	global_load_dwordx2 v[52:53], v[46:47], off offset:2560
	global_load_dwordx2 v[54:55], v[46:47], off offset:2048
	global_load_dwordx2 v[56:57], v[46:47], off
	global_load_dwordx2 v[58:59], v[46:47], off offset:512
	global_load_dwordx2 v[60:61], v[46:47], off offset:1024
	global_load_dwordx2 v[62:63], v[46:47], off offset:1536
	global_load_dwordx4 v[0:3], v[8:9], off
	global_load_dwordx2 v[64:65], v[46:47], off offset:3072
	global_load_dwordx2 v[72:73], v[46:47], off offset:3584
	v_lshlrev_b64 v[48:49], 13, v[48:49]
	v_lshl_add_u64 v[48:49], s[20:21], 0, v[48:49]
	s_waitcnt vmcnt(0)
	v_and_b32_e32 v123, 0xffff0000, v30
	v_and_b32_e32 v122, 0xffff0000, v32
	v_lshlrev_b32_e32 v101, 16, v34
	v_and_b32_e32 v51, 0xffff0000, v52
	v_and_b32_e32 v50, 0xffff0000, v54
	v_and_b32_e32 v95, 0xffff0000, v34
	v_lshlrev_b32_e32 v109, 16, v35
	v_and_b32_e32 v111, 0xffff0000, v35
	v_lshlrev_b32_e32 v67, 16, v52
	v_lshlrev_b32_e32 v66, 16, v54
	v_pk_mul_f32 v[34:35], v[50:51], v[50:51]
	v_lshlrev_b32_e32 v69, 16, v53
	v_lshlrev_b32_e32 v68, 16, v55
	v_pk_fma_f32 v[34:35], v[66:67], v[66:67], v[34:35]
	v_and_b32_e32 v99, 0xffff0000, v38
	v_and_b32_e32 v93, 0xffff0000, v40
	v_and_b32_e32 v71, 0xffff0000, v53
	v_and_b32_e32 v70, 0xffff0000, v55
	v_and_b32_e32 v98, 0xffff0000, v56
	v_and_b32_e32 v92, 0xffff0000, v58
	v_pk_fma_f32 v[34:35], v[68:69], v[68:69], v[34:35]
	v_lshlrev_b32_e32 v100, 16, v36
	v_and_b32_e32 v94, 0xffff0000, v36
	v_lshlrev_b32_e32 v108, 16, v37
	v_and_b32_e32 v110, 0xffff0000, v37
	v_lshlrev_b32_e32 v87, 16, v38
	v_lshlrev_b32_e32 v85, 16, v40
	v_lshlrev_b32_e32 v83, 16, v42
	v_and_b32_e32 v91, 0xffff0000, v42
	v_lshlrev_b32_e32 v97, 16, v43
	v_and_b32_e32 v107, 0xffff0000, v43
	v_lshlrev_b32_e32 v86, 16, v56
	v_lshlrev_b32_e32 v84, 16, v58
	v_pk_fma_f32 v[42:43], v[70:71], v[70:71], v[34:35]
	v_pk_mul_f32 v[34:35], v[98:99], v[98:99]
	v_pk_mul_f32 v[36:37], v[92:93], v[92:93]
	v_lshlrev_b32_e32 v105, 16, v39
	v_lshlrev_b32_e32 v103, 16, v41
	v_lshlrev_b32_e32 v104, 16, v57
	v_lshlrev_b32_e32 v102, 16, v59
	v_pk_fma_f32 v[34:35], v[86:87], v[86:87], v[34:35]
	v_pk_fma_f32 v[36:37], v[84:85], v[84:85], v[36:37]
	v_and_b32_e32 v117, 0xffff0000, v39
	v_and_b32_e32 v113, 0xffff0000, v41
	v_and_b32_e32 v116, 0xffff0000, v57
	v_and_b32_e32 v112, 0xffff0000, v59
	v_pk_fma_f32 v[34:35], v[104:105], v[104:105], v[34:35]
	v_pk_fma_f32 v[36:37], v[102:103], v[102:103], v[36:37]
	v_and_b32_e32 v90, 0xffff0000, v60
	v_pk_fma_f32 v[34:35], v[116:117], v[116:117], v[34:35]
	v_pk_fma_f32 v[36:37], v[112:113], v[112:113], v[36:37]
	v_lshlrev_b32_e32 v82, 16, v60
	v_pk_add_f32 v[34:35], v[34:35], v[36:37]
	v_pk_mul_f32 v[36:37], v[90:91], v[90:91]
	v_lshlrev_b32_e32 v96, 16, v61
	v_pk_fma_f32 v[36:37], v[82:83], v[82:83], v[36:37]
	v_and_b32_e32 v106, 0xffff0000, v61
	v_pk_fma_f32 v[36:37], v[96:97], v[96:97], v[36:37]
	v_and_b32_e32 v89, 0xffff0000, v44
	v_and_b32_e32 v88, 0xffff0000, v62
	v_pk_fma_f32 v[36:37], v[106:107], v[106:107], v[36:37]
	v_lshlrev_b32_e32 v125, 16, v30
	v_lshlrev_b32_e32 v124, 16, v32
	v_lshlrev_b32_e32 v127, 16, v31
	v_and_b32_e32 v129, 0xffff0000, v31
	v_lshlrev_b32_e32 v81, 16, v44
	v_pk_mul_f32 v[30:31], v[122:123], v[122:123]
	v_lshlrev_b32_e32 v80, 16, v62
	v_pk_add_f32 v[34:35], v[34:35], v[36:37]
	v_pk_mul_f32 v[36:37], v[88:89], v[88:89]
	v_lshlrev_b32_e32 v126, 16, v33
	v_lshlrev_b32_e32 v120, 16, v63
	v_pk_fma_f32 v[30:31], v[124:125], v[124:125], v[30:31]
	v_lshlrev_b32_e32 v121, 16, v45
	v_pk_fma_f32 v[36:37], v[80:81], v[80:81], v[36:37]
	v_and_b32_e32 v128, 0xffff0000, v33
	v_pk_fma_f32 v[30:31], v[126:127], v[126:127], v[30:31]
	v_and_b32_e32 v131, 0xffff0000, v45
	v_and_b32_e32 v130, 0xffff0000, v63
	v_pk_fma_f32 v[36:37], v[120:121], v[120:121], v[36:37]
	v_pk_fma_f32 v[30:31], v[128:129], v[128:129], v[30:31]
	v_pk_fma_f32 v[36:37], v[130:131], v[130:131], v[36:37]
	v_pk_mul_f32 v[32:33], v[94:95], v[94:95]
	v_pk_add_f32 v[34:35], v[34:35], v[36:37]
	v_mov_b32_e32 v36, v42
	v_mov_b32_e32 v37, v30
	v_pk_add_f32 v[44:45], v[34:35], v[36:37]
	v_and_b32_e32 v35, 0xffff0000, v72
	v_and_b32_e32 v34, 0xffff0000, v64
	v_lshlrev_b32_e32 v41, 16, v72
	v_lshlrev_b32_e32 v40, 16, v64
	v_pk_mul_f32 v[46:47], v[34:35], v[34:35]
	v_pk_fma_f32 v[32:33], v[100:101], v[100:101], v[32:33]
	v_lshlrev_b32_e32 v37, 16, v73
	v_lshlrev_b32_e32 v36, 16, v65
	v_pk_fma_f32 v[46:47], v[40:41], v[40:41], v[46:47]
	v_pk_fma_f32 v[32:33], v[108:109], v[108:109], v[32:33]
	v_and_b32_e32 v39, 0xffff0000, v73
	v_and_b32_e32 v38, 0xffff0000, v65
	v_pk_fma_f32 v[46:47], v[36:37], v[36:37], v[46:47]
	v_pk_fma_f32 v[32:33], v[110:111], v[110:111], v[32:33]
	v_pk_fma_f32 v[46:47], v[38:39], v[38:39], v[46:47]
	v_mov_b32_e32 v30, v43
	v_pk_add_f32 v[30:31], v[44:45], v[30:31]
	v_mov_b32_e32 v42, v46
	v_mov_b32_e32 v43, v32
	v_pk_add_f32 v[30:31], v[30:31], v[42:43]
	v_mov_b32_e32 v32, v47
	v_pk_add_f32 v[30:31], v[30:31], v[32:33]
	ds_bpermute_b32 v43, v132, v31
	ds_bpermute_b32 v42, v132, v30
	v_add_u32_e32 v32, 2, v4
	v_ashrrev_i32_e32 v33, 31, v32
	v_lshlrev_b64 v[44:45], 12, v[32:33]
	v_lshl_add_u64 v[44:45], v[18:19], 0, v[44:45]
	s_waitcnt lgkmcnt(0)
	v_pk_add_f32 v[30:31], v[30:31], v[42:43]
	ds_bpermute_b32 v43, v133, v31
	ds_bpermute_b32 v42, v133, v30
	global_load_dwordx2 v[60:61], v[44:45], off
	global_load_dwordx2 v[56:57], v[44:45], off offset:512
	global_load_dwordx2 v[52:53], v[44:45], off offset:1024
	global_load_dwordx2 v[46:47], v[44:45], off offset:1536
	global_load_dwordx2 v[114:115], v[44:45], off offset:2048
	global_load_dwordx2 v[118:119], v[44:45], off offset:2560
	global_load_dwordx2 v[74:75], v[44:45], off offset:3072
	global_load_dwordx2 v[78:79], v[44:45], off offset:3584
	v_mov_b32_e32 v146, v87
	v_mov_b32_e32 v147, v99
	s_waitcnt lgkmcnt(0)
	v_pk_add_f32 v[30:31], v[30:31], v[42:43]
	ds_bpermute_b32 v43, v134, v31
	ds_bpermute_b32 v42, v134, v30
	v_mov_b32_e32 v148, v105
	v_mov_b32_e32 v149, v117
	v_mov_b32_e32 v87, v98
	v_mov_b32_e32 v105, v116
	s_waitcnt lgkmcnt(0)
	v_pk_add_f32 v[42:43], v[30:31], v[42:43]
	ds_bpermute_b32 v45, v135, v43
	ds_bpermute_b32 v44, v135, v42
	v_add_u32_e32 v30, 3, v4
	v_ashrrev_i32_e32 v31, 31, v30
	v_lshlrev_b64 v[54:55], 12, v[30:31]
	v_lshl_add_u64 v[138:139], v[18:19], 0, v[54:55]
	s_waitcnt lgkmcnt(0)
	v_pk_add_f32 v[42:43], v[42:43], v[44:45]
	ds_bpermute_b32 v45, v136, v43
	ds_bpermute_b32 v44, v136, v42
	global_load_dwordx2 v[64:65], v[138:139], off
	global_load_dwordx2 v[62:63], v[138:139], off offset:512
	global_load_dwordx2 v[58:59], v[138:139], off offset:1024
	global_load_dwordx2 v[54:55], v[138:139], off offset:1536
	v_lshlrev_b64 v[32:33], 13, v[32:33]
	v_lshlrev_b64 v[30:31], 13, v[30:31]
	s_waitcnt lgkmcnt(0)
	v_pk_add_f32 v[140:141], v[42:43], v[44:45]
	ds_bpermute_b32 v143, v137, v141
	ds_bpermute_b32 v142, v137, v140
	global_load_dwordx2 v[72:73], v[138:139], off offset:2048
	global_load_dwordx2 v[76:77], v[138:139], off offset:2560
	global_load_dwordx2 v[42:43], v[138:139], off offset:3072
	global_load_dwordx2 v[44:45], v[138:139], off offset:3584
	s_waitcnt lgkmcnt(0)
	v_pk_add_f32 v[138:139], v[140:141], v[142:143]
	s_nop 0
	v_pk_fma_f32 v[138:139], v[138:139], s[2:3], v[28:29] op_sel_hi:[1,0,0]
	s_nop 0
	v_mul_f32_e32 v140, 0x4b800000, v139
	v_cmp_gt_f32_e32 vcc, s4, v139
	s_nop 1
	v_cndmask_b32_e32 v139, v139, v140, vcc
	v_rsq_f32_e32 v139, v139
	v_lshlrev_b64 v[140:141], 13, v[4:5]
	v_lshl_add_u64 v[140:141], s[20:21], 0, v[140:141]
	v_lshl_add_u64 v[142:143], v[140:141], 0, v[6:7]
	v_mul_f32_e32 v5, 0x45800000, v139
	v_cndmask_b32_e32 v144, v139, v5, vcc
	v_pk_mul_f32 v[146:147], v[146:147], v[144:145] op_sel_hi:[1,0]
	v_pk_mul_f32 v[148:149], v[148:149], v[144:145] op_sel_hi:[1,0]
	v_pk_mul_f32 v[0:1], v[0:1], v[146:147]
	v_pk_mul_f32 v[2:3], v[2:3], v[148:149]
	global_store_dwordx4 v[142:143], v[0:3], off nt
	v_mov_b32_e32 v146, v103
	v_mov_b32_e32 v147, v113
	v_mov_b32_e32 v148, v85
	v_mov_b32_e32 v149, v93
	v_pk_mul_f32 v[146:147], v[146:147], v[144:145] op_sel_hi:[1,0]
	v_pk_mul_f32 v[148:149], v[148:149], v[144:145] op_sel_hi:[1,0]
	v_mul_f32_e32 v5, 0x4b800000, v138
	v_cmp_gt_f32_e32 vcc, s4, v138
	v_mov_b32_e32 v85, v92
	v_mov_b32_e32 v103, v112
	v_cndmask_b32_e32 v5, v138, v5, vcc
	v_rsq_f32_e32 v5, v5
	v_add_u32_e32 v4, s3, v4
	s_waitcnt vmcnt(12)
	v_lshlrev_b32_e32 v92, 16, v115
	s_waitcnt vmcnt(11)
	v_lshlrev_b32_e32 v93, 16, v119
	s_waitcnt vmcnt(1)
	v_pk_mul_f32 v[0:1], v[184:185], v[148:149]
	v_pk_mul_f32 v[2:3], v[186:187], v[146:147]
	global_store_dwordx4 v[142:143], v[0:3], off offset:1024 nt
	v_mov_b32_e32 v146, v97
	v_mov_b32_e32 v147, v107
	v_mov_b32_e32 v148, v83
	v_mov_b32_e32 v149, v91
	v_pk_mul_f32 v[146:147], v[146:147], v[144:145] op_sel_hi:[1,0]
	v_pk_mul_f32 v[148:149], v[148:149], v[144:145] op_sel_hi:[1,0]
	v_mov_b32_e32 v83, v90
	v_mov_b32_e32 v97, v106
	v_lshlrev_b32_e32 v90, 16, v65
	v_lshlrev_b32_e32 v91, 16, v61
	s_waitcnt vmcnt(2)
	v_pk_mul_f32 v[0:1], v[188:189], v[148:149]
	v_pk_mul_f32 v[2:3], v[190:191], v[146:147]
	global_store_dwordx4 v[142:143], v[0:3], off offset:2048 nt
	v_mov_b32_e32 v146, v121
	v_mov_b32_e32 v147, v131
	v_mov_b32_e32 v148, v81
	v_mov_b32_e32 v149, v89
	v_pk_mul_f32 v[146:147], v[146:147], v[144:145] op_sel_hi:[1,0]
	v_pk_mul_f32 v[148:149], v[148:149], v[144:145] op_sel_hi:[1,0]
	v_mul_f32_e32 v81, 0x45800000, v5
	v_mov_b32_e32 v121, v130
	v_lshlrev_b32_e32 v89, 16, v57
	s_waitcnt vmcnt(3)
	v_pk_mul_f32 v[0:1], v[192:193], v[148:149]
	v_pk_mul_f32 v[2:3], v[194:195], v[146:147]
	global_store_dwordx4 v[142:143], v[0:3], off offset:3072 nt
	v_mov_b32_e32 v146, v126
	v_mov_b32_e32 v147, v128
	v_mov_b32_e32 v148, v124
	v_mov_b32_e32 v149, v122
	v_pk_mul_f32 v[146:147], v[146:147], v[144:145] op_sel_hi:[1,0]
	v_pk_mul_f32 v[148:149], v[148:149], v[144:145] op_sel_hi:[1,0]
	v_lshl_add_u64 v[142:143], v[140:141], 0, v[20:21]
	v_mov_b32_e32 v122, v125
	v_mov_b32_e32 v128, v127
	v_pk_mul_f32 v[124:125], v[128:129], v[144:145] op_sel_hi:[1,0]
	v_pk_mul_f32 v[122:123], v[122:123], v[144:145] op_sel_hi:[1,0]
	v_mov_b32_e32 v126, v100
	v_mov_b32_e32 v127, v94
	v_pk_mul_f32 v[126:127], v[126:127], v[144:145] op_sel_hi:[1,0]
	v_mov_b32_e32 v94, v101
	v_pk_mul_f32 v[94:95], v[94:95], v[144:145] op_sel_hi:[1,0]
	s_waitcnt vmcnt(4)
	v_pk_mul_f32 v[0:1], v[196:197], v[148:149]
	v_pk_mul_f32 v[2:3], v[198:199], v[146:147]
	global_store_dwordx4 v[142:143], v[0:3], off nt
	v_lshl_add_u64 v[142:143], v[140:141], 0, v[22:23]
	s_waitcnt vmcnt(5)
	v_pk_mul_f32 v[0:1], v[200:201], v[122:123]
	v_pk_mul_f32 v[2:3], v[202:203], v[124:125]
	global_store_dwordx4 v[142:143], v[0:3], off nt
	v_mov_b32_e32 v124, v108
	v_mov_b32_e32 v125, v110
	v_pk_mul_f32 v[124:125], v[124:125], v[144:145] op_sel_hi:[1,0]
	v_lshl_add_u64 v[122:123], v[140:141], 0, v[24:25]
	v_mov_b32_e32 v110, v109
	v_pk_mul_f32 v[100:101], v[110:111], v[144:145] op_sel_hi:[1,0]
	v_cndmask_b32_e32 v108, v5, v81, vcc
	v_pk_mul_f32 v[98:99], v[104:105], v[108:109] op_sel_hi:[1,0]
	v_pk_mul_f32 v[86:87], v[86:87], v[108:109] op_sel_hi:[1,0]
	v_pk_mul_f32 v[84:85], v[84:85], v[108:109] op_sel_hi:[1,0]
	v_pk_mul_f32 v[82:83], v[82:83], v[108:109] op_sel_hi:[1,0]
	v_mov_b32_e32 v81, v88
	v_pk_mul_f32 v[80:81], v[80:81], v[108:109] op_sel_hi:[1,0]
	v_lshl_add_u64 v[110:111], v[48:49], 0, v[26:27]
	v_lshlrev_b32_e32 v88, 16, v63
	s_waitcnt vmcnt(6)
	v_pk_mul_f32 v[0:1], v[126:127], v[204:205]
	v_pk_mul_f32 v[2:3], v[124:125], v[206:207]
	global_store_dwordx4 v[122:123], v[0:3], off nt
	v_lshl_add_u64 v[122:123], v[140:141], 0, v[26:27]
	s_waitcnt vmcnt(7)
	v_pk_mul_f32 v[0:1], v[94:95], v[208:209]
	v_pk_mul_f32 v[2:3], v[100:101], v[210:211]
	global_store_dwordx4 v[122:123], v[0:3], off nt
	v_lshl_add_u64 v[94:95], v[48:49], 0, v[6:7]
	v_and_b32_e32 v100, 0xffff0000, v63
	v_and_b32_e32 v63, 0xffff0000, v52
	v_and_b32_e32 v101, 0xffff0000, v57
	v_lshlrev_b32_e32 v57, 16, v46
	s_waitcnt vmcnt(8)
	v_pk_mul_f32 v[0:1], v[180:181], v[86:87]
	v_pk_mul_f32 v[2:3], v[182:183], v[98:99]
	global_store_dwordx4 v[94:95], v[0:3], off nt
	v_pk_mul_f32 v[86:87], v[102:103], v[108:109] op_sel_hi:[1,0]
	v_and_b32_e32 v98, 0xffff0000, v115
	v_and_b32_e32 v102, 0xffff0000, v65
	v_lshlrev_b32_e32 v65, 16, v56
	v_and_b32_e32 v99, 0xffff0000, v119
	v_and_b32_e32 v103, 0xffff0000, v61
	v_lshlrev_b32_e32 v61, 16, v52
	v_and_b32_e32 v52, 0xffff0000, v42
	s_waitcnt vmcnt(9)
	v_pk_mul_f32 v[0:1], v[184:185], v[84:85]
	v_pk_mul_f32 v[2:3], v[186:187], v[86:87]
	global_store_dwordx4 v[94:95], v[0:3], off offset:1024 nt
	v_pk_mul_f32 v[84:85], v[96:97], v[108:109] op_sel_hi:[1,0]
	v_and_b32_e32 v87, 0xffff0000, v60
	v_and_b32_e32 v86, 0xffff0000, v64
	v_and_b32_e32 v96, 0xffff0000, v59
	v_and_b32_e32 v97, 0xffff0000, v53
	s_waitcnt vmcnt(10)
	v_pk_mul_f32 v[0:1], v[188:189], v[82:83]
	v_pk_mul_f32 v[2:3], v[190:191], v[84:85]
	global_store_dwordx4 v[94:95], v[0:3], off offset:2048 nt
	v_pk_mul_f32 v[82:83], v[120:121], v[108:109] op_sel_hi:[1,0]
	v_mov_b32_e32 v84, v66
	v_mov_b32_e32 v85, v50
	v_pk_mul_f32 v[84:85], v[84:85], v[108:109] op_sel_hi:[1,0]
	v_mov_b32_e32 v50, v67
	v_pk_mul_f32 v[50:51], v[50:51], v[108:109] op_sel_hi:[1,0]
	s_waitcnt vmcnt(11)
	v_pk_mul_f32 v[0:1], v[192:193], v[80:81]
	v_pk_mul_f32 v[2:3], v[194:195], v[82:83]
	global_store_dwordx4 v[94:95], v[0:3], off offset:3072 nt
	v_mov_b32_e32 v82, v68
	v_mov_b32_e32 v83, v70
	v_pk_mul_f32 v[82:83], v[82:83], v[108:109] op_sel_hi:[1,0]
	v_lshl_add_u64 v[80:81], v[48:49], 0, v[20:21]
	v_mov_b32_e32 v70, v69
	v_pk_mul_f32 v[66:67], v[70:71], v[108:109] op_sel_hi:[1,0]
	v_mov_b32_e32 v68, v40
	v_mov_b32_e32 v69, v34
	v_pk_mul_f32 v[68:69], v[68:69], v[108:109] op_sel_hi:[1,0]
	v_mov_b32_e32 v34, v41
	v_pk_mul_f32 v[34:35], v[34:35], v[108:109] op_sel_hi:[1,0]
	v_lshlrev_b32_e32 v71, 16, v60
	v_lshlrev_b32_e32 v70, 16, v64
	v_lshlrev_b32_e32 v64, 16, v62
	v_lshlrev_b32_e32 v60, 16, v58
	v_and_b32_e32 v95, 0xffff0000, v47
	v_and_b32_e32 v94, 0xffff0000, v55
	s_waitcnt vmcnt(12)
	v_pk_mul_f32 v[0:1], v[196:197], v[84:85]
	v_pk_mul_f32 v[2:3], v[198:199], v[82:83]
	global_store_dwordx4 v[80:81], v[0:3], off nt
	v_lshl_add_u64 v[80:81], v[48:49], 0, v[22:23]
	v_lshlrev_b32_e32 v82, 16, v75
	v_lshlrev_b32_e32 v84, 16, v114
	v_lshlrev_b32_e32 v85, 16, v118
	v_lshlrev_b32_e32 v83, 16, v79
	v_and_b32_e32 v79, 0xffff0000, v79
	s_waitcnt vmcnt(13)
	v_pk_mul_f32 v[0:1], v[200:201], v[50:51]
	v_pk_mul_f32 v[2:3], v[202:203], v[66:67]
	global_store_dwordx4 v[80:81], v[0:3], off nt
	v_lshl_add_u64 v[50:51], v[48:49], 0, v[24:25]
	v_mov_b32_e32 v48, v36
	v_mov_b32_e32 v49, v38
	v_pk_mul_f32 v[48:49], v[48:49], v[108:109] op_sel_hi:[1,0]
	v_mov_b32_e32 v38, v37
	v_pk_mul_f32 v[36:37], v[38:39], v[108:109] op_sel_hi:[1,0]
	v_lshlrev_b32_e32 v67, 16, v78
	v_lshlrev_b32_e32 v66, 16, v74
	v_and_b32_e32 v80, 0xffff0000, v114
	v_pk_mul_f32 v[114:115], v[86:87], v[86:87]
	v_and_b32_e32 v81, 0xffff0000, v118
	v_pk_fma_f32 v[114:115], v[70:71], v[70:71], v[114:115]
	v_pk_mul_f32 v[40:41], v[80:81], v[80:81]
	v_pk_fma_f32 v[114:115], v[90:91], v[90:91], v[114:115]
	v_pk_fma_f32 v[40:41], v[84:85], v[84:85], v[40:41]
	s_waitcnt vmcnt(14)
	v_pk_mul_f32 v[0:1], v[68:69], v[204:205]
	v_pk_mul_f32 v[2:3], v[48:49], v[206:207]
	global_store_dwordx4 v[50:51], v[0:3], off nt
	v_and_b32_e32 v69, 0xffff0000, v78
	v_and_b32_e32 v68, 0xffff0000, v74
	v_and_b32_e32 v78, 0xffff0000, v75
	v_and_b32_e32 v3, 0xffff0000, v76
	v_and_b32_e32 v2, 0xffff0000, v72
	v_and_b32_e32 v75, 0xffff0000, v56
	v_and_b32_e32 v74, 0xffff0000, v62
	v_lshlrev_b32_e32 v1, 16, v76
	v_lshlrev_b32_e32 v0, 16, v72
	v_and_b32_e32 v62, 0xffff0000, v58
	v_pk_mul_f32 v[112:113], v[2:3], v[2:3]
	v_pk_mul_f32 v[116:117], v[74:75], v[74:75]
	v_lshlrev_b32_e32 v49, 16, v77
	v_lshlrev_b32_e32 v48, 16, v73
	v_lshlrev_b32_e32 v76, 16, v59
	v_and_b32_e32 v59, 0xffff0000, v46
	v_and_b32_e32 v58, 0xffff0000, v54
	v_pk_mul_f32 v[118:119], v[62:63], v[62:63]
	v_pk_fma_f32 v[112:113], v[0:1], v[0:1], v[112:113]
	v_pk_fma_f32 v[116:117], v[64:65], v[64:65], v[116:117]
	v_and_b32_e32 v51, 0xffff0000, v77
	v_and_b32_e32 v50, 0xffff0000, v73
	v_lshlrev_b32_e32 v77, 16, v53
	v_lshlrev_b32_e32 v56, 16, v54
	v_pk_mul_f32 v[120:121], v[58:59], v[58:59]
	v_pk_fma_f32 v[118:119], v[60:61], v[60:61], v[118:119]
	v_pk_fma_f32 v[112:113], v[48:49], v[48:49], v[112:113]
	v_pk_fma_f32 v[38:39], v[88:89], v[88:89], v[116:117]
	v_lshlrev_b32_e32 v73, 16, v47
	v_lshlrev_b32_e32 v72, 16, v55
	v_and_b32_e32 v53, 0xffff0000, v44
	v_pk_fma_f32 v[120:121], v[56:57], v[56:57], v[120:121]
	v_pk_fma_f32 v[38:39], v[100:101], v[100:101], v[38:39]
	v_lshlrev_b32_e32 v47, 16, v44
	v_lshlrev_b32_e32 v46, 16, v42
	v_lshlrev_b32_e32 v54, 16, v43
	v_and_b32_e32 v44, 0xffff0000, v43
	v_pk_mul_f32 v[42:43], v[68:69], v[68:69]
	v_pk_mul_f32 v[122:123], v[52:53], v[52:53]
	v_pk_fma_f32 v[40:41], v[92:93], v[92:93], v[40:41]
	v_lshlrev_b32_e32 v55, 16, v45
	v_pk_fma_f32 v[42:43], v[66:67], v[66:67], v[42:43]
	v_pk_fma_f32 v[122:123], v[46:47], v[46:47], v[122:123]
	v_pk_fma_f32 v[40:41], v[98:99], v[98:99], v[40:41]
	v_and_b32_e32 v45, 0xffff0000, v45
	v_pk_fma_f32 v[42:43], v[82:83], v[82:83], v[42:43]
	v_pk_fma_f32 v[108:109], v[54:55], v[54:55], v[122:123]
	v_pk_fma_f32 v[42:43], v[78:79], v[78:79], v[42:43]
	v_pk_fma_f32 v[108:109], v[44:45], v[44:45], v[108:109]
	s_waitcnt vmcnt(15)
	v_pk_mul_f32 v[34:35], v[34:35], v[208:209]
	v_pk_mul_f32 v[36:37], v[36:37], v[210:211]
	global_store_dwordx4 v[110:111], v[34:37], off nt
	v_pk_fma_f32 v[104:105], v[76:77], v[76:77], v[118:119]
	v_pk_fma_f32 v[110:111], v[50:51], v[50:51], v[112:113]
	v_pk_fma_f32 v[112:113], v[102:103], v[102:103], v[114:115]
	v_pk_fma_f32 v[106:107], v[72:73], v[72:73], v[120:121]
	v_pk_fma_f32 v[104:105], v[96:97], v[96:97], v[104:105]
	v_pk_add_f32 v[38:39], v[112:113], v[38:39]
	v_pk_fma_f32 v[106:107], v[94:95], v[94:95], v[106:107]
	v_pk_add_f32 v[38:39], v[38:39], v[104:105]
	v_mov_b32_e32 v112, v110
	v_mov_b32_e32 v113, v40
	v_pk_add_f32 v[38:39], v[38:39], v[106:107]
	v_mov_b32_e32 v40, v111
	v_pk_add_f32 v[38:39], v[38:39], v[112:113]
	v_mov_b32_e32 v110, v108
	v_mov_b32_e32 v111, v42
	v_pk_add_f32 v[38:39], v[38:39], v[40:41]
	v_mov_b32_e32 v42, v109
	v_pk_add_f32 v[38:39], v[38:39], v[110:111]
	s_nop 0
	v_pk_add_f32 v[38:39], v[38:39], v[42:43]
	ds_bpermute_b32 v41, v132, v39
	ds_bpermute_b32 v40, v132, v38
	v_lshl_add_u64 v[42:43], s[20:21], 0, v[32:33]
	v_mov_b32_e32 v32, v91
	v_mov_b32_e32 v33, v103
	v_lshl_add_u64 v[104:105], v[42:43], 0, v[6:7]
	s_waitcnt lgkmcnt(0)
	v_pk_add_f32 v[38:39], v[38:39], v[40:41]
	ds_bpermute_b32 v41, v133, v39
	ds_bpermute_b32 v40, v133, v38
	v_mov_b32_e32 v91, v102
	s_waitcnt lgkmcnt(0)
	v_pk_add_f32 v[38:39], v[38:39], v[40:41]
	ds_bpermute_b32 v41, v134, v39
	ds_bpermute_b32 v40, v134, v38
	s_waitcnt lgkmcnt(0)
	v_pk_add_f32 v[38:39], v[38:39], v[40:41]
	ds_bpermute_b32 v41, v135, v39
	ds_bpermute_b32 v40, v135, v38
	s_waitcnt lgkmcnt(0)
	v_pk_add_f32 v[38:39], v[38:39], v[40:41]
	ds_bpermute_b32 v41, v136, v39
	ds_bpermute_b32 v40, v136, v38
	s_waitcnt lgkmcnt(0)
	v_pk_add_f32 v[38:39], v[38:39], v[40:41]
	ds_bpermute_b32 v41, v137, v39
	ds_bpermute_b32 v40, v137, v38
	s_waitcnt lgkmcnt(0)
	v_pk_add_f32 v[38:39], v[38:39], v[40:41]
	s_nop 0
	v_pk_fma_f32 v[38:39], v[38:39], s[2:3], v[28:29] op_sel_hi:[1,0,0]
	v_mov_b32_e32 v40, v71
	v_mul_f32_e32 v5, 0x4b800000, v39
	v_cmp_gt_f32_e32 vcc, s4, v39
	v_mov_b32_e32 v41, v87
	v_mov_b32_e32 v71, v86
	v_cndmask_b32_e32 v5, v39, v5, vcc
	v_rsq_f32_e32 v5, v5
	s_nop 0
	v_mul_f32_e32 v39, 0x45800000, v5
	v_cndmask_b32_e32 v106, v5, v39, vcc
	v_pk_mul_f32 v[108:109], v[32:33], v[106:107] op_sel_hi:[1,0]
	v_pk_mul_f32 v[32:33], v[40:41], v[106:107] op_sel_hi:[1,0]
	v_mov_b32_e32 v40, v65
	v_mov_b32_e32 v41, v75
	s_waitcnt vmcnt(16)
	v_pk_mul_f32 v[32:33], v[180:181], v[32:33]
	v_pk_mul_f32 v[34:35], v[182:183], v[108:109]
	global_store_dwordx4 v[104:105], v[32:35], off nt
	v_mov_b32_e32 v36, v89
	v_mov_b32_e32 v37, v101
	v_pk_mul_f32 v[36:37], v[36:37], v[106:107] op_sel_hi:[1,0]
	v_pk_mul_f32 v[40:41], v[40:41], v[106:107] op_sel_hi:[1,0]
	v_mul_f32_e32 v5, 0x4b800000, v38
	v_cmp_gt_f32_e32 vcc, s4, v38
	v_mov_b32_e32 v65, v74
	v_mov_b32_e32 v89, v100
	v_cndmask_b32_e32 v5, v38, v5, vcc
	v_rsq_f32_e32 v5, v5
	s_waitcnt vmcnt(17)
	v_pk_mul_f32 v[32:33], v[184:185], v[40:41]
	v_pk_mul_f32 v[34:35], v[186:187], v[36:37]
	global_store_dwordx4 v[104:105], v[32:35], off offset:1024 nt
	v_mov_b32_e32 v36, v77
	v_mov_b32_e32 v37, v97
	v_mov_b32_e32 v40, v61
	v_mov_b32_e32 v41, v63
	v_pk_mul_f32 v[36:37], v[36:37], v[106:107] op_sel_hi:[1,0]
	v_pk_mul_f32 v[40:41], v[40:41], v[106:107] op_sel_hi:[1,0]
	v_mov_b32_e32 v61, v62
	v_mov_b32_e32 v77, v96
	s_waitcnt vmcnt(18)
	v_pk_mul_f32 v[32:33], v[188:189], v[40:41]
	v_pk_mul_f32 v[34:35], v[190:191], v[36:37]
	global_store_dwordx4 v[104:105], v[32:35], off offset:2048 nt
	v_mov_b32_e32 v36, v73
	v_mov_b32_e32 v37, v95
	v_mov_b32_e32 v40, v57
	v_mov_b32_e32 v41, v59
	v_pk_mul_f32 v[36:37], v[36:37], v[106:107] op_sel_hi:[1,0]
	v_pk_mul_f32 v[40:41], v[40:41], v[106:107] op_sel_hi:[1,0]
	v_mov_b32_e32 v57, v58
	v_mov_b32_e32 v73, v94
	s_waitcnt vmcnt(19)
	v_pk_mul_f32 v[32:33], v[192:193], v[40:41]
	v_pk_mul_f32 v[34:35], v[194:195], v[36:37]
	global_store_dwordx4 v[104:105], v[32:35], off offset:3072 nt
	v_mov_b32_e32 v40, v92
	v_mov_b32_e32 v41, v98
	v_mov_b32_e32 v104, v84
	v_mov_b32_e32 v105, v80
	v_pk_mul_f32 v[40:41], v[40:41], v[106:107] op_sel_hi:[1,0]
	v_pk_mul_f32 v[104:105], v[104:105], v[106:107] op_sel_hi:[1,0]
	v_lshl_add_u64 v[36:37], v[42:43], 0, v[20:21]
	v_mov_b32_e32 v80, v85
	v_mov_b32_e32 v98, v93
	v_pk_mul_f32 v[80:81], v[80:81], v[106:107] op_sel_hi:[1,0]
	s_waitcnt vmcnt(20)
	v_pk_mul_f32 v[32:33], v[196:197], v[104:105]
	v_pk_mul_f32 v[34:35], v[198:199], v[40:41]
	global_store_dwordx4 v[36:37], v[32:35], off nt
	v_pk_mul_f32 v[40:41], v[98:99], v[106:107] op_sel_hi:[1,0]
	v_lshl_add_u64 v[36:37], v[42:43], 0, v[22:23]
	s_waitcnt vmcnt(21)
	v_pk_mul_f32 v[32:33], v[200:201], v[80:81]
	v_pk_mul_f32 v[34:35], v[202:203], v[40:41]
	global_store_dwordx4 v[36:37], v[32:35], off nt
	v_mov_b32_e32 v40, v82
	v_mov_b32_e32 v41, v78
	v_mov_b32_e32 v80, v66
	v_mov_b32_e32 v81, v68
	v_pk_mul_f32 v[40:41], v[40:41], v[106:107] op_sel_hi:[1,0]
	v_pk_mul_f32 v[80:81], v[80:81], v[106:107] op_sel_hi:[1,0]
	v_lshl_add_u64 v[36:37], v[42:43], 0, v[24:25]
	v_mov_b32_e32 v68, v67
	v_mov_b32_e32 v78, v83
	s_waitcnt vmcnt(22)
	v_pk_mul_f32 v[32:33], v[80:81], v[204:205]
	v_pk_mul_f32 v[34:35], v[40:41], v[206:207]
	global_store_dwordx4 v[36:37], v[32:35], off nt
	v_lshl_add_u64 v[36:37], v[42:43], 0, v[26:27]
	v_pk_mul_f32 v[40:41], v[78:79], v[106:107] op_sel_hi:[1,0]
	v_pk_mul_f32 v[42:43], v[68:69], v[106:107] op_sel_hi:[1,0]
	s_waitcnt vmcnt(23)
	v_pk_mul_f32 v[34:35], v[40:41], v[210:211]
	v_pk_mul_f32 v[32:33], v[42:43], v[208:209]
	global_store_dwordx4 v[36:37], v[32:35], off nt
	v_lshl_add_u64 v[36:37], s[20:21], 0, v[30:31]
	v_mul_f32_e32 v30, 0x45800000, v5
	v_cndmask_b32_e32 v40, v5, v30, vcc
	v_pk_mul_f32 v[42:43], v[90:91], v[40:41] op_sel_hi:[1,0]
	v_pk_mul_f32 v[30:31], v[70:71], v[40:41] op_sel_hi:[1,0]
	v_lshl_add_u64 v[38:39], v[36:37], 0, v[6:7]
	v_cmp_lt_i32_e32 vcc, s5, v4
	s_or_b64 s[0:1], vcc, s[0:1]
	s_waitcnt vmcnt(24)
	v_pk_mul_f32 v[30:31], v[180:181], v[30:31]
	v_pk_mul_f32 v[32:33], v[182:183], v[42:43]
	global_store_dwordx4 v[38:39], v[30:33], off nt
	v_pk_mul_f32 v[34:35], v[88:89], v[40:41] op_sel_hi:[1,0]
	v_pk_mul_f32 v[42:43], v[64:65], v[40:41] op_sel_hi:[1,0]
	s_waitcnt vmcnt(25)
	v_pk_mul_f32 v[32:33], v[186:187], v[34:35]
	v_pk_mul_f32 v[30:31], v[184:185], v[42:43]
	global_store_dwordx4 v[38:39], v[30:33], off offset:1024 nt
	v_pk_mul_f32 v[34:35], v[76:77], v[40:41] op_sel_hi:[1,0]
	v_pk_mul_f32 v[42:43], v[60:61], v[40:41] op_sel_hi:[1,0]
	s_waitcnt vmcnt(26)
	v_pk_mul_f32 v[32:33], v[190:191], v[34:35]
	v_pk_mul_f32 v[30:31], v[188:189], v[42:43]
	global_store_dwordx4 v[38:39], v[30:33], off offset:2048 nt
	v_pk_mul_f32 v[34:35], v[72:73], v[40:41] op_sel_hi:[1,0]
	v_pk_mul_f32 v[42:43], v[56:57], v[40:41] op_sel_hi:[1,0]
	s_waitcnt vmcnt(27)
	v_pk_mul_f32 v[32:33], v[194:195], v[34:35]
	v_pk_mul_f32 v[30:31], v[192:193], v[42:43]
	global_store_dwordx4 v[38:39], v[30:33], off offset:3072 nt
	v_mov_b32_e32 v38, v48
	v_mov_b32_e32 v39, v50
	v_mov_b32_e32 v42, v0
	v_mov_b32_e32 v43, v2
	v_pk_mul_f32 v[38:39], v[38:39], v[40:41] op_sel_hi:[1,0]
	v_pk_mul_f32 v[42:43], v[42:43], v[40:41] op_sel_hi:[1,0]
	v_lshl_add_u64 v[34:35], v[36:37], 0, v[20:21]
	v_mov_b32_e32 v2, v1
	v_mov_b32_e32 v50, v49
	v_pk_mul_f32 v[0:1], v[2:3], v[40:41] op_sel_hi:[1,0]
	s_waitcnt vmcnt(28)
	v_pk_mul_f32 v[30:31], v[196:197], v[42:43]
	v_pk_mul_f32 v[32:33], v[198:199], v[38:39]
	global_store_dwordx4 v[34:35], v[30:33], off nt
	v_pk_mul_f32 v[38:39], v[50:51], v[40:41] op_sel_hi:[1,0]
	v_lshl_add_u64 v[34:35], v[36:37], 0, v[22:23]
	s_waitcnt vmcnt(29)
	v_pk_mul_f32 v[0:1], v[200:201], v[0:1]
	v_pk_mul_f32 v[2:3], v[202:203], v[38:39]
	global_store_dwordx4 v[34:35], v[0:3], off nt
	v_mov_b32_e32 v32, v54
	v_mov_b32_e32 v33, v44
	v_mov_b32_e32 v34, v46
	v_mov_b32_e32 v35, v52
	v_pk_mul_f32 v[32:33], v[32:33], v[40:41] op_sel_hi:[1,0]
	v_pk_mul_f32 v[34:35], v[34:35], v[40:41] op_sel_hi:[1,0]
	v_lshl_add_u64 v[30:31], v[36:37], 0, v[24:25]
	v_mov_b32_e32 v52, v47
	v_mov_b32_e32 v44, v55
	s_waitcnt vmcnt(30)
	v_pk_mul_f32 v[0:1], v[34:35], v[204:205]
	v_pk_mul_f32 v[2:3], v[32:33], v[206:207]
	global_store_dwordx4 v[30:31], v[0:3], off nt
	v_pk_mul_f32 v[32:33], v[44:45], v[40:41] op_sel_hi:[1,0]
	v_pk_mul_f32 v[34:35], v[52:53], v[40:41] op_sel_hi:[1,0]
	v_lshl_add_u64 v[30:31], v[36:37], 0, v[26:27]
	s_waitcnt vmcnt(31)
	v_pk_mul_f32 v[0:1], v[34:35], v[208:209]
	v_pk_mul_f32 v[2:3], v[32:33], v[210:211]
	global_store_dwordx4 v[30:31], v[0:3], off nt
	s_andn2_b64 exec, exec, s[0:1]
	s_cbranch_execnz .LBB0_1348
